# K-loops: ds_reads first in load segments, B-base offset folded, loop bookkeeping in MFMA shadow, LDS-DMA issue balanced 4/4 (vmcnt 8/6), pre-MFMA barrier passed 2 MFMAs into the block
# speedup vs baseline: 1.0092x; 1.0092x over previous
.LBB0_121:
	s_lshl_b32 s5, s2, 13
	s_lshl_b32 s2, s3, 12
	s_add_i32 m0, s38, 0x18000
	v_lshl_add_u64 v[10:11], v[10:11], 0, s[94:95]
	s_and_b32 s16, s2, 0x3000
	s_waitcnt vmcnt(2)
	s_barrier
	global_load_lds_dwordx4 v[10:11], off
	v_lshl_add_u64 v[8:9], v[8:9], 0, s[94:95]
	s_add_i32 m0, s38, 0x1a000
	s_add_i32 s52, s38, 0x8000
	s_add_i32 s53, s38, 0xa000
	global_load_lds_dwordx4 v[8:9], off
	v_lshl_add_u64 v[4:5], v[4:5], 0, s[94:95]
	s_mov_b32 m0, s52
	s_add_u32 s2, s30, 0x80080
	global_load_lds_dwordx4 v[4:5], off
	v_lshl_add_u64 v[4:5], v[6:7], 0, s[94:95]
	s_mov_b32 m0, s53
	s_addc_u32 s3, s31, 0
	global_load_lds_dwordx4 v[4:5], off
	s_add_i32 m0, s38, 0x1c000
	v_lshl_add_u64 v[4:5], s[2:3], 0, v[152:153]
	global_load_lds_dwordx4 v[4:5], off
	v_lshl_add_u64 v[4:5], s[2:3], 0, v[156:157]
	s_add_i32 m0, s38, 0x1e000
	v_and_b32_e32 v6, 15, v12
	global_load_lds_dwordx4 v[4:5], off
	v_lshlrev_b32_e32 v9, 2, v12
	v_and_b32_e32 v7, 48, v12
	v_lshlrev_b32_e32 v6, 6, v6
	v_and_b32_e32 v9, 32, v9
	v_or_b32_e32 v8, v6, v7
	v_bitop3_b32 v6, v6, v9, v7 bitop3:0x36
	s_cmpk_lt_u32 s4, 0x100
	v_or_b32_e32 v224, s16, v6
	v_add_u32_e32 v224, 0x10000, v224
	s_cselect_b64 s[16:17], -1, 0
	s_ashr_i32 s54, s42, 31
	s_add_u32 s18, s6, 0x6000
	v_and_b32_e32 v6, 1, v13
	v_bitop3_b32 v7, v8, s5, v9 bitop3:0xde
	s_addc_u32 s19, s7, 0
	v_lshlrev_b32_e32 v6, 6, v6
	v_lshlrev_b32_e32 v8, 1, v14
	s_add_u32 s20, s6, 0xc000
	v_add3_u32 v194, v15, v6, v8
	v_and_b32_e32 v6, 1, v16
	s_waitcnt vmcnt(6)
	s_addc_u32 s21, s7, 0
	s_mov_b64 s[2:3], 0x4080
	v_lshlrev_b32_e32 v6, 6, v6
	v_lshlrev_b32_e32 v8, 1, v17
	s_add_u32 s22, s6, 0x12000
	v_lshl_add_u64 v[158:159], v[194:195], 0, s[2:3]
	v_add3_u32 v194, v18, v6, v8
	v_mov_b32_e32 v3, v2
	v_mov_b32_e32 v4, v2
	v_mov_b32_e32 v5, v2
	s_addc_u32 s23, s7, 0
	v_lshl_add_u64 v[160:161], v[194:195], 0, s[2:3]
	s_mov_b32 s33, 0
	v_add_u32_e32 v225, 0, v7
	s_barrier
	s_branch .LBB0_124

.LBB0_133:
	s_add_u32 vcc_lo, s0, 0xffffc000
	s_addc_u32 vcc_hi, s1, -1
	v_lshl_add_u64 v[198:199], vcc, 0, v[158:159]
	s_mov_b32 m0, s52
	s_nop 0
	global_load_lds_dwordx4 v[198:199], off
	v_lshl_add_u64 v[198:199], vcc, 0, v[160:161]
	s_mov_b32 m0, s53
	s_nop 0
	global_load_lds_dwordx4 v[198:199], off
	ds_read_b128 v[130:133], v224
	ds_read_b128 v[134:137], v224 offset:1024
	ds_read_b128 v[138:141], v224 offset:2048
	ds_read_b128 v[142:145], v224 offset:3072
	ds_read_b128 v[146:149], v224 offset:16384
	ds_read_b128 v[162:165], v224 offset:17408
	ds_read_b128 v[166:169], v224 offset:18432
	ds_read_b128 v[170:173], v224 offset:19456
	ds_read_b128 v[174:177], v225
	ds_read_b128 v[178:181], v225 offset:1024
	ds_read_b128 v[182:185], v225 offset:2048
	ds_read_b128 v[186:189], v225 offset:3072
	ds_read_b128 v[190:193], v225 offset:4096
	ds_read_b128 v[204:207], v225 offset:5120
	ds_read_b128 v[208:211], v225 offset:6144
	ds_read_b128 v[212:215], v225 offset:7168
	s_add_u32 s4, s0, 0x100
	s_addc_u32 s5, s1, 0
	s_add_i32 s58, 0, 0x10000
	s_cmp_eq_u32 s57, 28
	s_cselect_b32 s35, s27, s5
	s_cselect_b32 s34, s26, s4
	s_cselect_b32 s31, s25, s51
	s_cselect_b32 s30, s37, s50
	s_add_i32 s59, 0, 0x14000
	v_lshl_add_u64 v[198:199], s[0:1], 0, v[158:159]
	s_add_i32 m0, s38, 0xc000
	s_nop 0
	global_load_lds_dwordx4 v[198:199], off
	v_lshl_add_u64 v[198:199], s[0:1], 0, v[160:161]
	s_add_i32 m0, s38, 0xe000
	s_nop 0
	global_load_lds_dwordx4 v[198:199], off
	s_waitcnt vmcnt(8)
	s_waitcnt lgkmcnt(0)
	v_mfma_f32_16x16x32_bf16 v[126:129], v[130:133], v[174:177], v[126:129]
	v_mfma_f32_16x16x32_bf16 v[122:125], v[138:141], v[174:177], v[122:125]
	s_barrier
	s_setprio 1
	v_mfma_f32_16x16x32_bf16 v[110:113], v[130:133], v[182:185], v[110:113]
	v_mfma_f32_16x16x32_bf16 v[106:109], v[138:141], v[182:185], v[106:109]
	v_mfma_f32_16x16x32_bf16 v[94:97], v[130:133], v[190:193], v[94:97]
	v_mfma_f32_16x16x32_bf16 v[90:93], v[138:141], v[190:193], v[90:93]
	v_mfma_f32_16x16x32_bf16 v[78:81], v[130:133], v[208:211], v[78:81]
	v_mfma_f32_16x16x32_bf16 v[74:77], v[138:141], v[208:211], v[74:77]
	v_mfma_f32_16x16x32_bf16 v[126:129], v[134:137], v[178:181], v[126:129]
	v_mfma_f32_16x16x32_bf16 v[122:125], v[142:145], v[178:181], v[122:125]
	v_mfma_f32_16x16x32_bf16 v[110:113], v[134:137], v[186:189], v[110:113]
	v_mfma_f32_16x16x32_bf16 v[106:109], v[142:145], v[186:189], v[106:109]
	v_mfma_f32_16x16x32_bf16 v[94:97], v[134:137], v[204:207], v[94:97]
	v_mfma_f32_16x16x32_bf16 v[90:93], v[142:145], v[204:207], v[90:93]
	v_mfma_f32_16x16x32_bf16 v[78:81], v[134:137], v[212:215], v[78:81]
	v_mfma_f32_16x16x32_bf16 v[74:77], v[142:145], v[212:215], v[74:77]
	v_mfma_f32_16x16x32_bf16 v[118:121], v[146:149], v[174:177], v[118:121]
	v_mfma_f32_16x16x32_bf16 v[114:117], v[166:169], v[174:177], v[114:117]
	v_mfma_f32_16x16x32_bf16 v[102:105], v[146:149], v[182:185], v[102:105]
	v_mfma_f32_16x16x32_bf16 v[98:101], v[166:169], v[182:185], v[98:101]
	v_mfma_f32_16x16x32_bf16 v[86:89], v[146:149], v[190:193], v[86:89]
	v_mfma_f32_16x16x32_bf16 v[82:85], v[166:169], v[190:193], v[82:85]
	v_mfma_f32_16x16x32_bf16 v[70:73], v[146:149], v[208:211], v[70:73]
	v_mfma_f32_16x16x32_bf16 v[66:69], v[166:169], v[208:211], v[66:69]
	v_mfma_f32_16x16x32_bf16 v[118:121], v[162:165], v[178:181], v[118:121]
	v_mfma_f32_16x16x32_bf16 v[114:117], v[170:173], v[178:181], v[114:117]
	v_mfma_f32_16x16x32_bf16 v[102:105], v[162:165], v[186:189], v[102:105]
	v_mfma_f32_16x16x32_bf16 v[98:101], v[170:173], v[186:189], v[98:101]
	v_mfma_f32_16x16x32_bf16 v[86:89], v[162:165], v[204:207], v[86:89]
	v_mfma_f32_16x16x32_bf16 v[82:85], v[170:173], v[204:207], v[82:85]
	v_mfma_f32_16x16x32_bf16 v[70:73], v[162:165], v[212:215], v[70:73]
	v_mfma_f32_16x16x32_bf16 v[66:69], v[170:173], v[212:215], v[66:69]
	s_setprio 0
	s_barrier
	ds_read_b128 v[174:177], v225 offset:16384
	ds_read_b128 v[178:181], v225 offset:17408
	ds_read_b128 v[182:185], v225 offset:18432
	ds_read_b128 v[186:189], v225 offset:19456
	ds_read_b128 v[190:193], v225 offset:20480
	ds_read_b128 v[204:207], v225 offset:21504
	ds_read_b128 v[208:211], v225 offset:22528
	ds_read_b128 v[212:215], v225 offset:23552
	s_add_i32 s0, s58, s15
	v_lshl_add_u64 v[198:199], s[30:31], 0, v[152:153]
	s_mov_b32 m0, s0
	s_nop 0
	global_load_lds_dwordx4 v[198:199], off
	s_add_i32 m0, s0, 0x2000
	s_add_u32 s0, s30, 0x80000
	v_lshl_add_u64 v[216:217], s[30:31], 0, v[156:157]
	s_addc_u32 s1, s31, 0
	s_add_i32 s58, s59, s15
	global_load_lds_dwordx4 v[216:217], off
	v_lshl_add_u64 v[218:219], s[0:1], 0, v[152:153]
	s_mov_b32 m0, s58
	v_lshl_add_u64 v[220:221], s[34:35], 0, v[154:155]
	global_load_lds_dwordx4 v[218:219], off
	v_lshl_add_u64 v[218:219], s[0:1], 0, v[156:157]
	s_add_i32 m0, s58, 0x2000
	s_nop 0
	global_load_lds_dwordx4 v[218:219], off
	v_lshl_add_u64 v[218:219], s[34:35], 0, v[150:151]
	s_waitcnt vmcnt(6)
	s_waitcnt lgkmcnt(0)
	v_mfma_f32_16x16x32_bf16 v[62:65], v[130:133], v[174:177], v[62:65]
	v_mfma_f32_16x16x32_bf16 v[58:61], v[138:141], v[174:177], v[58:61]
	s_barrier
	s_setprio 1
	v_mfma_f32_16x16x32_bf16 v[46:49], v[130:133], v[182:185], v[46:49]
	v_mfma_f32_16x16x32_bf16 v[42:45], v[138:141], v[182:185], v[42:45]
	v_mfma_f32_16x16x32_bf16 v[30:33], v[130:133], v[190:193], v[30:33]
	v_mfma_f32_16x16x32_bf16 v[26:29], v[138:141], v[190:193], v[26:29]
	v_mfma_f32_16x16x32_bf16 v[14:17], v[130:133], v[208:211], v[14:17]
	v_mfma_f32_16x16x32_bf16 v[10:13], v[138:141], v[208:211], v[10:13]
	v_mfma_f32_16x16x32_bf16 v[62:65], v[134:137], v[178:181], v[62:65]
	v_mfma_f32_16x16x32_bf16 v[58:61], v[142:145], v[178:181], v[58:61]
	v_mfma_f32_16x16x32_bf16 v[46:49], v[134:137], v[186:189], v[46:49]
	v_mfma_f32_16x16x32_bf16 v[42:45], v[142:145], v[186:189], v[42:45]
	v_mfma_f32_16x16x32_bf16 v[30:33], v[134:137], v[204:207], v[30:33]
	v_mfma_f32_16x16x32_bf16 v[26:29], v[142:145], v[204:207], v[26:29]
	v_mfma_f32_16x16x32_bf16 v[14:17], v[134:137], v[212:215], v[14:17]
	v_mfma_f32_16x16x32_bf16 v[10:13], v[142:145], v[212:215], v[10:13]
	v_mfma_f32_16x16x32_bf16 v[54:57], v[146:149], v[174:177], v[54:57]
	v_mfma_f32_16x16x32_bf16 v[50:53], v[166:169], v[174:177], v[50:53]
	v_mfma_f32_16x16x32_bf16 v[38:41], v[146:149], v[182:185], v[38:41]
	v_mfma_f32_16x16x32_bf16 v[34:37], v[166:169], v[182:185], v[34:37]
	v_mfma_f32_16x16x32_bf16 v[22:25], v[146:149], v[190:193], v[22:25]
	v_mfma_f32_16x16x32_bf16 v[18:21], v[166:169], v[190:193], v[18:21]
	v_mfma_f32_16x16x32_bf16 v[6:9], v[146:149], v[208:211], v[6:9]
	v_mfma_f32_16x16x32_bf16 v[2:5], v[166:169], v[208:211], v[2:5]
	v_mfma_f32_16x16x32_bf16 v[54:57], v[162:165], v[178:181], v[54:57]
	v_mfma_f32_16x16x32_bf16 v[50:53], v[170:173], v[178:181], v[50:53]
	v_mfma_f32_16x16x32_bf16 v[38:41], v[162:165], v[186:189], v[38:41]
	v_mfma_f32_16x16x32_bf16 v[34:37], v[170:173], v[186:189], v[34:37]
	v_mfma_f32_16x16x32_bf16 v[22:25], v[162:165], v[204:207], v[22:25]
	v_mfma_f32_16x16x32_bf16 v[18:21], v[170:173], v[204:207], v[18:21]
	v_mfma_f32_16x16x32_bf16 v[6:9], v[162:165], v[212:215], v[6:9]
	v_mfma_f32_16x16x32_bf16 v[2:5], v[170:173], v[212:215], v[2:5]
	s_setprio 0
	s_barrier
	s_mov_b32 m0, s38
	s_nop 0
	global_load_lds_dwordx4 v[218:219], off
	s_mov_b32 m0, s39
	s_nop 0
	global_load_lds_dwordx4 v[220:221], off
	ds_read_b128 v[130:133], v224 offset:32768
	ds_read_b128 v[134:137], v224 offset:33792
	ds_read_b128 v[138:141], v224 offset:34816
	ds_read_b128 v[142:145], v224 offset:35840
	ds_read_b128 v[146:149], v224 offset:49152
	ds_read_b128 v[162:165], v224 offset:50176
	ds_read_b128 v[166:169], v224 offset:51200
	ds_read_b128 v[170:173], v224 offset:52224
	ds_read_b128 v[174:177], v225 offset:32768
	ds_read_b128 v[178:181], v225 offset:33792
	ds_read_b128 v[182:185], v225 offset:34816
	ds_read_b128 v[186:189], v225 offset:35840
	ds_read_b128 v[190:193], v225 offset:36864
	ds_read_b128 v[204:207], v225 offset:37888
	ds_read_b128 v[208:211], v225 offset:38912
	ds_read_b128 v[212:215], v225 offset:39936
	s_add_i32 s58, 0, 0x18000
	s_add_i32 s59, 0, 0x1c000
	s_add_u32 s0, s34, 0x4000
	s_addc_u32 s1, s35, 0
	s_mov_b32 m0, s40
	v_lshl_add_u64 v[222:223], s[0:1], 0, v[150:151]
	global_load_lds_dwordx4 v[222:223], off
	v_lshl_add_u64 v[222:223], s[0:1], 0, v[154:155]
	s_mov_b32 m0, s41
	s_nop 0
	global_load_lds_dwordx4 v[222:223], off
	s_waitcnt vmcnt(8)
	s_waitcnt lgkmcnt(0)
	v_mfma_f32_16x16x32_bf16 v[126:129], v[130:133], v[174:177], v[126:129]
	v_mfma_f32_16x16x32_bf16 v[122:125], v[138:141], v[174:177], v[122:125]
	s_barrier
	s_setprio 1
	v_mfma_f32_16x16x32_bf16 v[110:113], v[130:133], v[182:185], v[110:113]
	v_mfma_f32_16x16x32_bf16 v[106:109], v[138:141], v[182:185], v[106:109]
	v_mfma_f32_16x16x32_bf16 v[94:97], v[130:133], v[190:193], v[94:97]
	v_mfma_f32_16x16x32_bf16 v[90:93], v[138:141], v[190:193], v[90:93]
	v_mfma_f32_16x16x32_bf16 v[78:81], v[130:133], v[208:211], v[78:81]
	v_mfma_f32_16x16x32_bf16 v[74:77], v[138:141], v[208:211], v[74:77]
	v_mfma_f32_16x16x32_bf16 v[126:129], v[134:137], v[178:181], v[126:129]
	v_mfma_f32_16x16x32_bf16 v[122:125], v[142:145], v[178:181], v[122:125]
	v_mfma_f32_16x16x32_bf16 v[110:113], v[134:137], v[186:189], v[110:113]
	v_mfma_f32_16x16x32_bf16 v[106:109], v[142:145], v[186:189], v[106:109]
	v_mfma_f32_16x16x32_bf16 v[94:97], v[134:137], v[204:207], v[94:97]
	v_mfma_f32_16x16x32_bf16 v[90:93], v[142:145], v[204:207], v[90:93]
	v_mfma_f32_16x16x32_bf16 v[78:81], v[134:137], v[212:215], v[78:81]
	v_mfma_f32_16x16x32_bf16 v[74:77], v[142:145], v[212:215], v[74:77]
	v_mfma_f32_16x16x32_bf16 v[118:121], v[146:149], v[174:177], v[118:121]
	v_mfma_f32_16x16x32_bf16 v[114:117], v[166:169], v[174:177], v[114:117]
	v_mfma_f32_16x16x32_bf16 v[102:105], v[146:149], v[182:185], v[102:105]
	v_mfma_f32_16x16x32_bf16 v[98:101], v[166:169], v[182:185], v[98:101]
	v_mfma_f32_16x16x32_bf16 v[86:89], v[146:149], v[190:193], v[86:89]
	v_mfma_f32_16x16x32_bf16 v[82:85], v[166:169], v[190:193], v[82:85]
	v_mfma_f32_16x16x32_bf16 v[70:73], v[146:149], v[208:211], v[70:73]
	v_mfma_f32_16x16x32_bf16 v[66:69], v[166:169], v[208:211], v[66:69]
	v_mfma_f32_16x16x32_bf16 v[118:121], v[162:165], v[178:181], v[118:121]
	v_mfma_f32_16x16x32_bf16 v[114:117], v[170:173], v[178:181], v[114:117]
	v_mfma_f32_16x16x32_bf16 v[102:105], v[162:165], v[186:189], v[102:105]
	v_mfma_f32_16x16x32_bf16 v[98:101], v[170:173], v[186:189], v[98:101]
	v_mfma_f32_16x16x32_bf16 v[86:89], v[162:165], v[204:207], v[86:89]
	v_mfma_f32_16x16x32_bf16 v[82:85], v[170:173], v[204:207], v[82:85]
	v_mfma_f32_16x16x32_bf16 v[70:73], v[162:165], v[212:215], v[70:73]
	v_mfma_f32_16x16x32_bf16 v[66:69], v[170:173], v[212:215], v[66:69]
	s_setprio 0
	s_barrier
	ds_read_b128 v[174:177], v225 offset:49152
	ds_read_b128 v[178:181], v225 offset:50176
	ds_read_b128 v[182:185], v225 offset:51200
	ds_read_b128 v[186:189], v225 offset:52224
	ds_read_b128 v[190:193], v225 offset:53248
	ds_read_b128 v[204:207], v225 offset:54272
	ds_read_b128 v[208:211], v225 offset:55296
	ds_read_b128 v[212:215], v225 offset:56320
	s_add_i32 s0, s58, s15
	v_lshl_add_u64 v[198:199], v[198:199], 0, s[94:95]
	s_mov_b32 m0, s0
	s_nop 0
	global_load_lds_dwordx4 v[198:199], off
	s_add_i32 m0, s0, 0x2000
	s_add_u32 s0, s30, 0x80080
	v_lshl_add_u64 v[198:199], v[216:217], 0, s[94:95]
	s_addc_u32 s1, s31, 0
	s_add_i32 s30, s59, s15
	global_load_lds_dwordx4 v[198:199], off
	v_lshl_add_u64 v[198:199], s[0:1], 0, v[152:153]
	s_mov_b32 m0, s30
	s_nop 0
	global_load_lds_dwordx4 v[198:199], off
	v_lshl_add_u64 v[198:199], s[0:1], 0, v[156:157]
	s_add_i32 m0, s30, 0x2000
	s_nop 0
	global_load_lds_dwordx4 v[198:199], off
	s_waitcnt vmcnt(6)
	s_waitcnt lgkmcnt(0)
	v_mfma_f32_16x16x32_bf16 v[62:65], v[130:133], v[174:177], v[62:65]
	v_mfma_f32_16x16x32_bf16 v[58:61], v[138:141], v[174:177], v[58:61]
	s_barrier
	s_setprio 1
	v_mfma_f32_16x16x32_bf16 v[46:49], v[130:133], v[182:185], v[46:49]
	v_mfma_f32_16x16x32_bf16 v[42:45], v[138:141], v[182:185], v[42:45]
	v_mfma_f32_16x16x32_bf16 v[30:33], v[130:133], v[190:193], v[30:33]
	v_mfma_f32_16x16x32_bf16 v[26:29], v[138:141], v[190:193], v[26:29]
	v_mfma_f32_16x16x32_bf16 v[14:17], v[130:133], v[208:211], v[14:17]
	v_mfma_f32_16x16x32_bf16 v[10:13], v[138:141], v[208:211], v[10:13]
	v_mfma_f32_16x16x32_bf16 v[62:65], v[134:137], v[178:181], v[62:65]
	v_mfma_f32_16x16x32_bf16 v[58:61], v[142:145], v[178:181], v[58:61]
	v_mfma_f32_16x16x32_bf16 v[46:49], v[134:137], v[186:189], v[46:49]
	v_mfma_f32_16x16x32_bf16 v[42:45], v[142:145], v[186:189], v[42:45]
	v_mfma_f32_16x16x32_bf16 v[30:33], v[134:137], v[204:207], v[30:33]
	v_mfma_f32_16x16x32_bf16 v[26:29], v[142:145], v[204:207], v[26:29]
	s_add_i32 s57, s57, 2
	v_mfma_f32_16x16x32_bf16 v[14:17], v[134:137], v[212:215], v[14:17]
	v_mfma_f32_16x16x32_bf16 v[10:13], v[142:145], v[212:215], v[10:13]
	s_add_u32 s50, s50, 0x100
	v_mfma_f32_16x16x32_bf16 v[54:57], v[146:149], v[174:177], v[54:57]
	v_mfma_f32_16x16x32_bf16 v[50:53], v[166:169], v[174:177], v[50:53]
	s_addc_u32 s51, s51, 0
	v_mfma_f32_16x16x32_bf16 v[38:41], v[146:149], v[182:185], v[38:41]
	v_mfma_f32_16x16x32_bf16 v[34:37], v[166:169], v[182:185], v[34:37]
	s_cmp_gt_u32 s57, 29
	v_mfma_f32_16x16x32_bf16 v[22:25], v[146:149], v[190:193], v[22:25]
	v_mfma_f32_16x16x32_bf16 v[18:21], v[166:169], v[190:193], v[18:21]
	s_mov_b64 s[0:1], s[4:5]
	v_mfma_f32_16x16x32_bf16 v[6:9], v[146:149], v[208:211], v[6:9]
	v_mfma_f32_16x16x32_bf16 v[2:5], v[166:169], v[208:211], v[2:5]
	v_mfma_f32_16x16x32_bf16 v[54:57], v[162:165], v[178:181], v[54:57]
	v_mfma_f32_16x16x32_bf16 v[50:53], v[170:173], v[178:181], v[50:53]
	v_mfma_f32_16x16x32_bf16 v[38:41], v[162:165], v[186:189], v[38:41]
	v_mfma_f32_16x16x32_bf16 v[34:37], v[170:173], v[186:189], v[34:37]
	v_mfma_f32_16x16x32_bf16 v[22:25], v[162:165], v[204:207], v[22:25]
	v_mfma_f32_16x16x32_bf16 v[18:21], v[170:173], v[204:207], v[18:21]
	v_mfma_f32_16x16x32_bf16 v[6:9], v[162:165], v[212:215], v[6:9]
	v_mfma_f32_16x16x32_bf16 v[2:5], v[170:173], v[212:215], v[2:5]
	s_setprio 0
	s_barrier
	s_cbranch_scc0 .LBB0_133
	s_and_b64 vcc, exec, s[16:17]
	s_cbranch_vccz .LBB0_136
	s_barrier

.LBB0_292:
	s_lshl_b32 s4, s2, 13
	s_lshl_b32 s2, s3, 12
	s_and_b32 s5, s2, 0x3000
	v_readlane_b32 s2, v255, 6
	v_readlane_b32 s3, v255, 7
	s_lshl_b32 s2, s2, 13
	s_mov_b32 s3, s85
	s_lshl_b64 s[2:3], s[2:3], 2
	v_readlane_b32 s18, v253, 0
	v_readlane_b32 s19, v253, 1
	s_add_u32 s2, s18, s2
	s_addc_u32 s3, s19, s3
	s_add_u32 s60, s2, 0x30000
	s_addc_u32 s61, s3, 0
	s_add_i32 m0, s56, 0x18000
	v_lshl_add_u64 v[10:11], v[10:11], 0, s[94:95]
	s_waitcnt vmcnt(2)
	s_barrier
	global_load_lds_dwordx4 v[10:11], off
	v_lshl_add_u64 v[8:9], v[8:9], 0, s[94:95]
	s_add_i32 m0, s56, 0x1a000
	s_add_i32 s62, s56, 0x8000
	s_add_i32 s63, s56, 0xa000
	global_load_lds_dwordx4 v[8:9], off
	v_lshl_add_u64 v[4:5], v[4:5], 0, s[94:95]
	s_mov_b32 m0, s62
	s_add_u32 s2, s38, 0x80080
	global_load_lds_dwordx4 v[4:5], off
	v_lshl_add_u64 v[4:5], v[6:7], 0, s[94:95]
	s_mov_b32 m0, s63
	s_addc_u32 s3, s39, 0
	global_load_lds_dwordx4 v[4:5], off
	s_add_i32 m0, s56, 0x1c000
	v_lshl_add_u64 v[4:5], s[2:3], 0, v[172:173]
	global_load_lds_dwordx4 v[4:5], off
	v_lshl_add_u64 v[4:5], s[2:3], 0, v[176:177]
	s_add_i32 m0, s56, 0x1e000
	v_and_b32_e32 v6, 15, v12
	global_load_lds_dwordx4 v[4:5], off
	v_lshlrev_b32_e32 v9, 2, v12
	v_and_b32_e32 v7, 48, v12
	v_lshlrev_b32_e32 v6, 6, v6
	v_and_b32_e32 v9, 32, v9
	v_or_b32_e32 v8, v6, v7
	v_bitop3_b32 v6, v6, v9, v7 bitop3:0x36
	s_cmpk_lt_u32 s16, 0x100
	v_or_b32_e32 v226, s5, v6
	v_add_u32_e32 v226, 0x10000, v226
	s_cselect_b64 s[16:17], -1, 0
	s_add_u32 s18, s6, 0x6000
	v_and_b32_e32 v6, 1, v13
	v_bitop3_b32 v7, v8, s4, v9 bitop3:0xde
	s_addc_u32 s19, s7, 0
	v_lshlrev_b32_e32 v6, 6, v6
	v_lshlrev_b32_e32 v8, 1, v14
	s_add_u32 s20, s6, 0xc000
	v_add3_u32 v194, v15, v6, v8
	v_and_b32_e32 v6, 1, v16
	s_waitcnt vmcnt(6)
	s_addc_u32 s21, s7, 0
	s_mov_b64 s[2:3], 0x4080
	v_lshlrev_b32_e32 v6, 6, v6
	v_lshlrev_b32_e32 v8, 1, v17
	s_add_u32 s22, s6, 0x12000
	v_lshl_add_u64 v[178:179], v[194:195], 0, s[2:3]
	v_add3_u32 v194, v18, v6, v8
	v_mov_b32_e32 v3, v2
	v_mov_b32_e32 v4, v2
	v_mov_b32_e32 v5, v2
	s_addc_u32 s23, s7, 0
	v_lshl_add_u64 v[180:181], v[194:195], 0, s[2:3]
	s_mov_b32 s33, 0
	v_add_u32_e32 v227, 0, v7
	s_mov_b32 s74, s35
	s_barrier
	s_branch .LBB0_295

.LBB0_305:
	s_add_u32 vcc_lo, s0, 0xffffc000
	s_addc_u32 vcc_hi, s1, -1
	v_lshl_add_u64 v[198:199], vcc, 0, v[178:179]
	s_mov_b32 m0, s62
	s_nop 0
	global_load_lds_dwordx4 v[198:199], off
	v_lshl_add_u64 v[198:199], vcc, 0, v[180:181]
	s_mov_b32 m0, s63
	s_nop 0
	global_load_lds_dwordx4 v[198:199], off
	ds_read_b128 v[130:133], v226
	ds_read_b128 v[134:137], v226 offset:1024
	ds_read_b128 v[138:141], v226 offset:2048
	ds_read_b128 v[142:145], v226 offset:3072
	ds_read_b128 v[146:149], v226 offset:16384
	ds_read_b128 v[150:153], v226 offset:17408
	ds_read_b128 v[154:157], v226 offset:18432
	ds_read_b128 v[158:161], v226 offset:19456
	ds_read_b128 v[162:165], v227
	ds_read_b128 v[166:169], v227 offset:1024
	ds_read_b128 v[182:185], v227 offset:2048
	ds_read_b128 v[186:189], v227 offset:3072
	ds_read_b128 v[190:193], v227 offset:4096
	ds_read_b128 v[204:207], v227 offset:5120
	ds_read_b128 v[208:211], v227 offset:6144
	ds_read_b128 v[212:215], v227 offset:7168
	s_add_i32 s71, s38, 2
	s_add_u32 s4, s0, 0x100
	s_addc_u32 s5, s1, 0
	s_add_i32 s73, 0, 0x10000
	s_cmp_eq_u32 s37, s38
	s_cselect_b32 s41, s31, s5
	s_cselect_b32 s40, s30, s4
	s_cselect_b32 s39, s25, s70
	s_cselect_b32 s38, s27, s51
	s_add_i32 s75, 0, 0x14000
	v_lshl_add_u64 v[198:199], s[0:1], 0, v[178:179]
	s_add_i32 m0, s56, 0xc000
	s_nop 0
	global_load_lds_dwordx4 v[198:199], off
	v_lshl_add_u64 v[198:199], s[0:1], 0, v[180:181]
	s_add_i32 m0, s56, 0xe000
	s_nop 0
	global_load_lds_dwordx4 v[198:199], off
	s_waitcnt vmcnt(8)
	s_waitcnt lgkmcnt(0)
	v_mfma_f32_16x16x32_bf16 v[126:129], v[130:133], v[162:165], v[126:129]
	v_mfma_f32_16x16x32_bf16 v[122:125], v[138:141], v[162:165], v[122:125]
	s_barrier
	s_setprio 1
	v_mfma_f32_16x16x32_bf16 v[110:113], v[130:133], v[182:185], v[110:113]
	v_mfma_f32_16x16x32_bf16 v[106:109], v[138:141], v[182:185], v[106:109]
	v_mfma_f32_16x16x32_bf16 v[94:97], v[130:133], v[190:193], v[94:97]
	v_mfma_f32_16x16x32_bf16 v[90:93], v[138:141], v[190:193], v[90:93]
	v_mfma_f32_16x16x32_bf16 v[78:81], v[130:133], v[208:211], v[78:81]
	v_mfma_f32_16x16x32_bf16 v[74:77], v[138:141], v[208:211], v[74:77]
	v_mfma_f32_16x16x32_bf16 v[126:129], v[134:137], v[166:169], v[126:129]
	v_mfma_f32_16x16x32_bf16 v[122:125], v[142:145], v[166:169], v[122:125]
	v_mfma_f32_16x16x32_bf16 v[110:113], v[134:137], v[186:189], v[110:113]
	v_mfma_f32_16x16x32_bf16 v[106:109], v[142:145], v[186:189], v[106:109]
	v_mfma_f32_16x16x32_bf16 v[94:97], v[134:137], v[204:207], v[94:97]
	v_mfma_f32_16x16x32_bf16 v[90:93], v[142:145], v[204:207], v[90:93]
	v_mfma_f32_16x16x32_bf16 v[78:81], v[134:137], v[212:215], v[78:81]
	v_mfma_f32_16x16x32_bf16 v[74:77], v[142:145], v[212:215], v[74:77]
	v_mfma_f32_16x16x32_bf16 v[118:121], v[146:149], v[162:165], v[118:121]
	v_mfma_f32_16x16x32_bf16 v[114:117], v[154:157], v[162:165], v[114:117]
	v_mfma_f32_16x16x32_bf16 v[102:105], v[146:149], v[182:185], v[102:105]
	v_mfma_f32_16x16x32_bf16 v[98:101], v[154:157], v[182:185], v[98:101]
	v_mfma_f32_16x16x32_bf16 v[86:89], v[146:149], v[190:193], v[86:89]
	v_mfma_f32_16x16x32_bf16 v[82:85], v[154:157], v[190:193], v[82:85]
	v_mfma_f32_16x16x32_bf16 v[70:73], v[146:149], v[208:211], v[70:73]
	v_mfma_f32_16x16x32_bf16 v[66:69], v[154:157], v[208:211], v[66:69]
	v_mfma_f32_16x16x32_bf16 v[118:121], v[150:153], v[166:169], v[118:121]
	v_mfma_f32_16x16x32_bf16 v[114:117], v[158:161], v[166:169], v[114:117]
	v_mfma_f32_16x16x32_bf16 v[102:105], v[150:153], v[186:189], v[102:105]
	v_mfma_f32_16x16x32_bf16 v[98:101], v[158:161], v[186:189], v[98:101]
	v_mfma_f32_16x16x32_bf16 v[86:89], v[150:153], v[204:207], v[86:89]
	v_mfma_f32_16x16x32_bf16 v[82:85], v[158:161], v[204:207], v[82:85]
	v_mfma_f32_16x16x32_bf16 v[70:73], v[150:153], v[212:215], v[70:73]
	v_mfma_f32_16x16x32_bf16 v[66:69], v[158:161], v[212:215], v[66:69]
	s_setprio 0
	s_barrier
	ds_read_b128 v[162:165], v227 offset:16384
	ds_read_b128 v[166:169], v227 offset:17408
	ds_read_b128 v[182:185], v227 offset:18432
	ds_read_b128 v[186:189], v227 offset:19456
	ds_read_b128 v[190:193], v227 offset:20480
	ds_read_b128 v[204:207], v227 offset:21504
	ds_read_b128 v[208:211], v227 offset:22528
	ds_read_b128 v[212:215], v227 offset:23552
	s_add_i32 s0, s73, s15
	v_lshl_add_u64 v[198:199], s[38:39], 0, v[172:173]
	s_mov_b32 m0, s0
	s_nop 0
	global_load_lds_dwordx4 v[198:199], off
	s_add_i32 m0, s0, 0x2000
	s_add_u32 s0, s38, 0x80000
	v_lshl_add_u64 v[216:217], s[38:39], 0, v[176:177]
	s_addc_u32 s1, s39, 0
	s_add_i32 s73, s75, s15
	global_load_lds_dwordx4 v[216:217], off
	v_lshl_add_u64 v[218:219], s[0:1], 0, v[172:173]
	s_mov_b32 m0, s73
	v_lshl_add_u64 v[220:221], s[40:41], 0, v[174:175]
	global_load_lds_dwordx4 v[218:219], off
	v_lshl_add_u64 v[218:219], s[0:1], 0, v[176:177]
	s_add_i32 m0, s73, 0x2000
	s_nop 0
	global_load_lds_dwordx4 v[218:219], off
	v_lshl_add_u64 v[218:219], s[40:41], 0, v[170:171]
	s_waitcnt vmcnt(6)
	s_waitcnt lgkmcnt(0)
	v_mfma_f32_16x16x32_bf16 v[62:65], v[130:133], v[162:165], v[62:65]
	v_mfma_f32_16x16x32_bf16 v[58:61], v[138:141], v[162:165], v[58:61]
	s_barrier
	s_setprio 1
	v_mfma_f32_16x16x32_bf16 v[46:49], v[130:133], v[182:185], v[46:49]
	v_mfma_f32_16x16x32_bf16 v[42:45], v[138:141], v[182:185], v[42:45]
	v_mfma_f32_16x16x32_bf16 v[30:33], v[130:133], v[190:193], v[30:33]
	v_mfma_f32_16x16x32_bf16 v[26:29], v[138:141], v[190:193], v[26:29]
	v_mfma_f32_16x16x32_bf16 v[14:17], v[130:133], v[208:211], v[14:17]
	v_mfma_f32_16x16x32_bf16 v[10:13], v[138:141], v[208:211], v[10:13]
	v_mfma_f32_16x16x32_bf16 v[62:65], v[134:137], v[166:169], v[62:65]
	v_mfma_f32_16x16x32_bf16 v[58:61], v[142:145], v[166:169], v[58:61]
	v_mfma_f32_16x16x32_bf16 v[46:49], v[134:137], v[186:189], v[46:49]
	v_mfma_f32_16x16x32_bf16 v[42:45], v[142:145], v[186:189], v[42:45]
	v_mfma_f32_16x16x32_bf16 v[30:33], v[134:137], v[204:207], v[30:33]
	v_mfma_f32_16x16x32_bf16 v[26:29], v[142:145], v[204:207], v[26:29]
	v_mfma_f32_16x16x32_bf16 v[14:17], v[134:137], v[212:215], v[14:17]
	v_mfma_f32_16x16x32_bf16 v[10:13], v[142:145], v[212:215], v[10:13]
	v_mfma_f32_16x16x32_bf16 v[54:57], v[146:149], v[162:165], v[54:57]
	v_mfma_f32_16x16x32_bf16 v[50:53], v[154:157], v[162:165], v[50:53]
	v_mfma_f32_16x16x32_bf16 v[38:41], v[146:149], v[182:185], v[38:41]
	v_mfma_f32_16x16x32_bf16 v[34:37], v[154:157], v[182:185], v[34:37]
	v_mfma_f32_16x16x32_bf16 v[22:25], v[146:149], v[190:193], v[22:25]
	v_mfma_f32_16x16x32_bf16 v[18:21], v[154:157], v[190:193], v[18:21]
	v_mfma_f32_16x16x32_bf16 v[6:9], v[146:149], v[208:211], v[6:9]
	v_mfma_f32_16x16x32_bf16 v[2:5], v[154:157], v[208:211], v[2:5]
	v_mfma_f32_16x16x32_bf16 v[54:57], v[150:153], v[166:169], v[54:57]
	v_mfma_f32_16x16x32_bf16 v[50:53], v[158:161], v[166:169], v[50:53]
	v_mfma_f32_16x16x32_bf16 v[38:41], v[150:153], v[186:189], v[38:41]
	v_mfma_f32_16x16x32_bf16 v[34:37], v[158:161], v[186:189], v[34:37]
	v_mfma_f32_16x16x32_bf16 v[22:25], v[150:153], v[204:207], v[22:25]
	v_mfma_f32_16x16x32_bf16 v[18:21], v[158:161], v[204:207], v[18:21]
	v_mfma_f32_16x16x32_bf16 v[6:9], v[150:153], v[212:215], v[6:9]
	v_mfma_f32_16x16x32_bf16 v[2:5], v[158:161], v[212:215], v[2:5]
	s_setprio 0
	s_barrier
	s_mov_b32 m0, s56
	s_nop 0
	global_load_lds_dwordx4 v[218:219], off
	s_mov_b32 m0, s57
	s_nop 0
	global_load_lds_dwordx4 v[220:221], off
	ds_read_b128 v[130:133], v226 offset:32768
	ds_read_b128 v[134:137], v226 offset:33792
	ds_read_b128 v[138:141], v226 offset:34816
	ds_read_b128 v[142:145], v226 offset:35840
	ds_read_b128 v[146:149], v226 offset:49152
	ds_read_b128 v[150:153], v226 offset:50176
	ds_read_b128 v[154:157], v226 offset:51200
	ds_read_b128 v[158:161], v226 offset:52224
	ds_read_b128 v[162:165], v227 offset:32768
	ds_read_b128 v[166:169], v227 offset:33792
	ds_read_b128 v[182:185], v227 offset:34816
	ds_read_b128 v[186:189], v227 offset:35840
	ds_read_b128 v[190:193], v227 offset:36864
	ds_read_b128 v[204:207], v227 offset:37888
	ds_read_b128 v[208:211], v227 offset:38912
	ds_read_b128 v[212:215], v227 offset:39936
	s_add_i32 s73, 0, 0x18000
	s_add_i32 s75, 0, 0x1c000
	s_add_u32 s0, s40, 0x4000
	s_addc_u32 s1, s41, 0
	s_mov_b32 m0, s58
	v_lshl_add_u64 v[222:223], s[0:1], 0, v[170:171]
	global_load_lds_dwordx4 v[222:223], off
	v_lshl_add_u64 v[222:223], s[0:1], 0, v[174:175]
	s_mov_b32 m0, s59
	s_nop 0
	global_load_lds_dwordx4 v[222:223], off
	s_waitcnt vmcnt(8)
	s_waitcnt lgkmcnt(0)
	v_mfma_f32_16x16x32_bf16 v[126:129], v[130:133], v[162:165], v[126:129]
	v_mfma_f32_16x16x32_bf16 v[122:125], v[138:141], v[162:165], v[122:125]
	s_barrier
	s_setprio 1
	v_mfma_f32_16x16x32_bf16 v[110:113], v[130:133], v[182:185], v[110:113]
	v_mfma_f32_16x16x32_bf16 v[106:109], v[138:141], v[182:185], v[106:109]
	v_mfma_f32_16x16x32_bf16 v[94:97], v[130:133], v[190:193], v[94:97]
	v_mfma_f32_16x16x32_bf16 v[90:93], v[138:141], v[190:193], v[90:93]
	v_mfma_f32_16x16x32_bf16 v[78:81], v[130:133], v[208:211], v[78:81]
	v_mfma_f32_16x16x32_bf16 v[74:77], v[138:141], v[208:211], v[74:77]
	v_mfma_f32_16x16x32_bf16 v[126:129], v[134:137], v[166:169], v[126:129]
	v_mfma_f32_16x16x32_bf16 v[122:125], v[142:145], v[166:169], v[122:125]
	v_mfma_f32_16x16x32_bf16 v[110:113], v[134:137], v[186:189], v[110:113]
	v_mfma_f32_16x16x32_bf16 v[106:109], v[142:145], v[186:189], v[106:109]
	v_mfma_f32_16x16x32_bf16 v[94:97], v[134:137], v[204:207], v[94:97]
	v_mfma_f32_16x16x32_bf16 v[90:93], v[142:145], v[204:207], v[90:93]
	v_mfma_f32_16x16x32_bf16 v[78:81], v[134:137], v[212:215], v[78:81]
	v_mfma_f32_16x16x32_bf16 v[74:77], v[142:145], v[212:215], v[74:77]
	v_mfma_f32_16x16x32_bf16 v[118:121], v[146:149], v[162:165], v[118:121]
	v_mfma_f32_16x16x32_bf16 v[114:117], v[154:157], v[162:165], v[114:117]
	v_mfma_f32_16x16x32_bf16 v[102:105], v[146:149], v[182:185], v[102:105]
	v_mfma_f32_16x16x32_bf16 v[98:101], v[154:157], v[182:185], v[98:101]
	v_mfma_f32_16x16x32_bf16 v[86:89], v[146:149], v[190:193], v[86:89]
	v_mfma_f32_16x16x32_bf16 v[82:85], v[154:157], v[190:193], v[82:85]
	v_mfma_f32_16x16x32_bf16 v[70:73], v[146:149], v[208:211], v[70:73]
	v_mfma_f32_16x16x32_bf16 v[66:69], v[154:157], v[208:211], v[66:69]
	v_mfma_f32_16x16x32_bf16 v[118:121], v[150:153], v[166:169], v[118:121]
	v_mfma_f32_16x16x32_bf16 v[114:117], v[158:161], v[166:169], v[114:117]
	v_mfma_f32_16x16x32_bf16 v[102:105], v[150:153], v[186:189], v[102:105]
	v_mfma_f32_16x16x32_bf16 v[98:101], v[158:161], v[186:189], v[98:101]
	v_mfma_f32_16x16x32_bf16 v[86:89], v[150:153], v[204:207], v[86:89]
	v_mfma_f32_16x16x32_bf16 v[82:85], v[158:161], v[204:207], v[82:85]
	v_mfma_f32_16x16x32_bf16 v[70:73], v[150:153], v[212:215], v[70:73]
	v_mfma_f32_16x16x32_bf16 v[66:69], v[158:161], v[212:215], v[66:69]
	s_setprio 0
	s_barrier
	ds_read_b128 v[162:165], v227 offset:49152
	ds_read_b128 v[166:169], v227 offset:50176
	ds_read_b128 v[182:185], v227 offset:51200
	ds_read_b128 v[186:189], v227 offset:52224
	ds_read_b128 v[190:193], v227 offset:53248
	ds_read_b128 v[204:207], v227 offset:54272
	ds_read_b128 v[208:211], v227 offset:55296
	ds_read_b128 v[212:215], v227 offset:56320
	s_add_i32 s0, s73, s15
	v_lshl_add_u64 v[198:199], v[198:199], 0, s[94:95]
	s_mov_b32 m0, s0
	s_nop 0
	global_load_lds_dwordx4 v[198:199], off
	s_add_i32 m0, s0, 0x2000
	s_add_u32 s0, s38, 0x80080
	v_lshl_add_u64 v[198:199], v[216:217], 0, s[94:95]
	s_addc_u32 s1, s39, 0
	s_add_i32 s38, s75, s15
	global_load_lds_dwordx4 v[198:199], off
	v_lshl_add_u64 v[198:199], s[0:1], 0, v[172:173]
	s_mov_b32 m0, s38
	s_nop 0
	global_load_lds_dwordx4 v[198:199], off
	v_lshl_add_u64 v[198:199], s[0:1], 0, v[176:177]
	s_add_i32 m0, s38, 0x2000
	s_nop 0
	global_load_lds_dwordx4 v[198:199], off
	s_waitcnt vmcnt(6)
	s_waitcnt lgkmcnt(0)
	v_mfma_f32_16x16x32_bf16 v[62:65], v[130:133], v[162:165], v[62:65]
	v_mfma_f32_16x16x32_bf16 v[58:61], v[138:141], v[162:165], v[58:61]
	s_barrier
	s_setprio 1
	v_mfma_f32_16x16x32_bf16 v[46:49], v[130:133], v[182:185], v[46:49]
	v_mfma_f32_16x16x32_bf16 v[42:45], v[138:141], v[182:185], v[42:45]
	v_mfma_f32_16x16x32_bf16 v[30:33], v[130:133], v[190:193], v[30:33]
	v_mfma_f32_16x16x32_bf16 v[26:29], v[138:141], v[190:193], v[26:29]
	v_mfma_f32_16x16x32_bf16 v[14:17], v[130:133], v[208:211], v[14:17]
	v_mfma_f32_16x16x32_bf16 v[10:13], v[138:141], v[208:211], v[10:13]
	v_mfma_f32_16x16x32_bf16 v[62:65], v[134:137], v[166:169], v[62:65]
	v_mfma_f32_16x16x32_bf16 v[58:61], v[142:145], v[166:169], v[58:61]
	v_mfma_f32_16x16x32_bf16 v[46:49], v[134:137], v[186:189], v[46:49]
	v_mfma_f32_16x16x32_bf16 v[42:45], v[142:145], v[186:189], v[42:45]
	v_mfma_f32_16x16x32_bf16 v[30:33], v[134:137], v[204:207], v[30:33]
	v_mfma_f32_16x16x32_bf16 v[26:29], v[142:145], v[204:207], v[26:29]
	s_add_u32 s51, s51, 0x100
	v_mfma_f32_16x16x32_bf16 v[14:17], v[134:137], v[212:215], v[14:17]
	v_mfma_f32_16x16x32_bf16 v[10:13], v[142:145], v[212:215], v[10:13]
	s_addc_u32 s70, s70, 0
	v_mfma_f32_16x16x32_bf16 v[54:57], v[146:149], v[162:165], v[54:57]
	v_mfma_f32_16x16x32_bf16 v[50:53], v[154:157], v[162:165], v[50:53]
	s_cmp_ge_i32 s71, s35
	v_mfma_f32_16x16x32_bf16 v[38:41], v[146:149], v[182:185], v[38:41]
	v_mfma_f32_16x16x32_bf16 v[34:37], v[154:157], v[182:185], v[34:37]
	s_mov_b64 s[0:1], s[4:5]
	v_mfma_f32_16x16x32_bf16 v[22:25], v[146:149], v[190:193], v[22:25]
	v_mfma_f32_16x16x32_bf16 v[18:21], v[154:157], v[190:193], v[18:21]
	s_mov_b32 s38, s71
	v_mfma_f32_16x16x32_bf16 v[6:9], v[146:149], v[208:211], v[6:9]
	v_mfma_f32_16x16x32_bf16 v[2:5], v[154:157], v[208:211], v[2:5]
	v_mfma_f32_16x16x32_bf16 v[54:57], v[150:153], v[166:169], v[54:57]
	v_mfma_f32_16x16x32_bf16 v[50:53], v[158:161], v[166:169], v[50:53]
	v_mfma_f32_16x16x32_bf16 v[38:41], v[150:153], v[186:189], v[38:41]
	v_mfma_f32_16x16x32_bf16 v[34:37], v[158:161], v[186:189], v[34:37]
	v_mfma_f32_16x16x32_bf16 v[22:25], v[150:153], v[204:207], v[22:25]
	v_mfma_f32_16x16x32_bf16 v[18:21], v[158:161], v[204:207], v[18:21]
	v_mfma_f32_16x16x32_bf16 v[6:9], v[150:153], v[212:215], v[6:9]
	v_mfma_f32_16x16x32_bf16 v[2:5], v[158:161], v[212:215], v[2:5]
	s_setprio 0
	s_barrier
	s_cbranch_scc0 .LBB0_305
	s_movk_i32 s51, 0x2000
	s_mov_b32 s73, 0x10000
	s_mov_b32 s75, 0x12000
	s_and_b64 vcc, exec, s[16:17]
	s_cbranch_vccz .LBB0_308

.LBB0_524:
	v_readlane_b32 s4, v255, 4
	v_readlane_b32 s5, v255, 5
	s_mov_b32 s8, s4
	s_mov_b32 s5, s85
	v_writelane_b32 v255, s8, 4
	s_lshl_b64 s[4:5], s[4:5], 3
	v_lshl_add_u64 v[10:11], v[10:11], 0, s[94:95]
	v_writelane_b32 v255, s9, 5
	v_readlane_b32 s8, v253, 63
	s_add_u32 s4, s8, s4
	v_readlane_b32 s8, v254, 0
	s_addc_u32 s5, s8, s5
	s_lshl_b32 s7, s7, 5
	s_and_b32 s11, s7, 0x60
	s_add_i32 m0, s23, 0x18000
	s_lshl_b32 s10, s6, 13
	s_lshl_b32 s7, s11, 7
	s_waitcnt vmcnt(2)
	s_barrier
	global_load_lds_dwordx4 v[10:11], off
	v_lshl_add_u64 v[8:9], v[8:9], 0, s[94:95]
	s_add_i32 m0, s23, 0x1a000
	s_add_i32 s27, s23, 0x8000
	s_add_i32 s28, s23, 0xa000
	global_load_lds_dwordx4 v[8:9], off
	v_lshl_add_u64 v[4:5], v[4:5], 0, s[94:95]
	s_mov_b32 m0, s27
	s_add_u32 s8, s16, 0x80080
	global_load_lds_dwordx4 v[4:5], off
	v_lshl_add_u64 v[4:5], v[6:7], 0, s[94:95]
	s_mov_b32 m0, s28
	s_addc_u32 s9, s17, 0
	global_load_lds_dwordx4 v[4:5], off
	s_add_i32 m0, s23, 0x1c000
	v_lshl_add_u64 v[4:5], s[8:9], 0, v[134:135]
	global_load_lds_dwordx4 v[4:5], off
	v_lshl_add_u64 v[4:5], s[8:9], 0, v[130:131]
	s_add_i32 m0, s23, 0x1e000
	v_lshrrev_b32_e32 v7, 1, v13
	global_load_lds_dwordx4 v[4:5], off
	v_and_b32_e32 v7, 24, v7
	v_and_b32_e32 v6, 15, v13
	v_lshlrev_b32_e32 v8, 1, v7
	v_lshl_or_b32 v143, s6, 6, v6
	v_lshl_or_b32 v6, v6, 6, v8
	v_lshlrev_b32_e32 v8, 2, v13
	v_and_b32_e32 v8, 32, v8
	v_bitop3_b32 v9, v6, s10, v8 bitop3:0xde
	v_bitop3_b32 v145, v6, s7, v8 bitop3:0xde
	v_add_u32_e32 v145, 0x10000, v145
	v_lshlrev_b32_e32 v6, 15, v17
	v_and_b32_e32 v6, 0xffff0000, v6
	v_or_b32_e32 v147, s11, v7
	v_lshl_add_u32 v6, v16, 12, v6
	v_and_b32_e32 v7, 1, v17
	v_lshl_or_b32 v6, v7, 6, v6
	v_lshl_add_u32 v138, v18, 1, v6
	v_lshlrev_b32_e32 v6, 15, v12
	v_and_b32_e32 v6, 0xffff0000, v6
	s_waitcnt vmcnt(6)
	v_lshl_add_u32 v6, v14, 12, v6
	v_and_b32_e32 v7, 1, v12
	s_cmpk_lt_u32 s3, 0x100
	v_lshl_or_b32 v6, v7, 6, v6
	s_sext_i32_i16 s31, s2
	v_mov_b32_e32 v3, v2
	v_mov_b32_e32 v4, v2
	v_mov_b32_e32 v5, v2
	s_cselect_b64 s[6:7], -1, 0
	v_or_b32_e32 v149, 0xfffffc00, v147
	v_mov_b32_e32 v139, v195
	v_lshl_add_u32 v140, v15, 1, v6
	v_mov_b32_e32 v141, v195
	s_mov_b32 s29, 0
	v_add_u32_e32 v151, 0, v9
	s_barrier
	s_branch .LBB0_527

.LBB0_530:
	s_add_u32 vcc_lo, s14, 0xfff80000
	s_addc_u32 vcc_hi, s15, -1
	v_lshl_add_u64 v[192:193], vcc, 0, v[138:139]
	s_mov_b32 m0, s27
	s_nop 0
	global_load_lds_dwordx4 v[192:193], off
	v_lshl_add_u64 v[192:193], vcc, 0, v[140:141]
	s_mov_b32 m0, s28
	s_nop 0
	global_load_lds_dwordx4 v[192:193], off
	ds_read_b128 v[152:155], v145
	ds_read_b128 v[156:159], v145 offset:1024
	ds_read_b128 v[160:163], v145 offset:2048
	ds_read_b128 v[164:167], v145 offset:3072
	ds_read_b128 v[168:171], v145 offset:16384
	ds_read_b128 v[172:175], v145 offset:17408
	ds_read_b128 v[176:179], v145 offset:18432
	ds_read_b128 v[180:183], v145 offset:19456
	ds_read_b128 v[184:187], v151
	ds_read_b128 v[188:191], v151 offset:1024
	ds_read_b128 v[204:207], v151 offset:2048
	ds_read_b128 v[208:211], v151 offset:3072
	ds_read_b128 v[212:215], v151 offset:4096
	ds_read_b128 v[216:219], v151 offset:5120
	ds_read_b128 v[220:223], v151 offset:6144
	ds_read_b128 v[224:227], v151 offset:7168
	s_add_u32 s16, s14, 0xfff80080
	s_addc_u32 s17, s15, -1
	s_add_i32 s40, 0, 0x10000
	s_cmp_eq_u32 s39, 28
	s_cselect_b32 s19, s34, s17
	s_cselect_b32 s18, s35, s16
	s_cselect_b32 s17, s9, s38
	s_cselect_b32 s16, s36, s37
	s_add_i32 s42, 0, 0x14000
	v_lshl_add_u64 v[192:193], s[14:15], 0, v[138:139]
	s_add_i32 m0, s23, 0xc000
	s_nop 0
	global_load_lds_dwordx4 v[192:193], off
	v_lshl_add_u64 v[192:193], s[14:15], 0, v[140:141]
	s_add_i32 m0, s23, 0xe000
	s_nop 0
	global_load_lds_dwordx4 v[192:193], off
	s_waitcnt vmcnt(8)
	s_waitcnt lgkmcnt(0)
	v_mfma_f32_16x16x32_bf16 v[126:129], v[152:155], v[184:187], v[126:129]
	v_mfma_f32_16x16x32_bf16 v[122:125], v[160:163], v[184:187], v[122:125]
	s_barrier
	s_setprio 1
	v_mfma_f32_16x16x32_bf16 v[110:113], v[152:155], v[204:207], v[110:113]
	v_mfma_f32_16x16x32_bf16 v[106:109], v[160:163], v[204:207], v[106:109]
	v_mfma_f32_16x16x32_bf16 v[94:97], v[152:155], v[212:215], v[94:97]
	v_mfma_f32_16x16x32_bf16 v[90:93], v[160:163], v[212:215], v[90:93]
	v_mfma_f32_16x16x32_bf16 v[78:81], v[152:155], v[220:223], v[78:81]
	v_mfma_f32_16x16x32_bf16 v[74:77], v[160:163], v[220:223], v[74:77]
	v_mfma_f32_16x16x32_bf16 v[126:129], v[156:159], v[188:191], v[126:129]
	v_mfma_f32_16x16x32_bf16 v[122:125], v[164:167], v[188:191], v[122:125]
	v_mfma_f32_16x16x32_bf16 v[110:113], v[156:159], v[208:211], v[110:113]
	v_mfma_f32_16x16x32_bf16 v[106:109], v[164:167], v[208:211], v[106:109]
	v_mfma_f32_16x16x32_bf16 v[94:97], v[156:159], v[216:219], v[94:97]
	v_mfma_f32_16x16x32_bf16 v[90:93], v[164:167], v[216:219], v[90:93]
	v_mfma_f32_16x16x32_bf16 v[78:81], v[156:159], v[224:227], v[78:81]
	v_mfma_f32_16x16x32_bf16 v[74:77], v[164:167], v[224:227], v[74:77]
	v_mfma_f32_16x16x32_bf16 v[118:121], v[168:171], v[184:187], v[118:121]
	v_mfma_f32_16x16x32_bf16 v[114:117], v[176:179], v[184:187], v[114:117]
	v_mfma_f32_16x16x32_bf16 v[102:105], v[168:171], v[204:207], v[102:105]
	v_mfma_f32_16x16x32_bf16 v[98:101], v[176:179], v[204:207], v[98:101]
	v_mfma_f32_16x16x32_bf16 v[86:89], v[168:171], v[212:215], v[86:89]
	v_mfma_f32_16x16x32_bf16 v[82:85], v[176:179], v[212:215], v[82:85]
	v_mfma_f32_16x16x32_bf16 v[70:73], v[168:171], v[220:223], v[70:73]
	v_mfma_f32_16x16x32_bf16 v[66:69], v[176:179], v[220:223], v[66:69]
	v_mfma_f32_16x16x32_bf16 v[118:121], v[172:175], v[188:191], v[118:121]
	v_mfma_f32_16x16x32_bf16 v[114:117], v[180:183], v[188:191], v[114:117]
	v_mfma_f32_16x16x32_bf16 v[102:105], v[172:175], v[208:211], v[102:105]
	v_mfma_f32_16x16x32_bf16 v[98:101], v[180:183], v[208:211], v[98:101]
	v_mfma_f32_16x16x32_bf16 v[86:89], v[172:175], v[216:219], v[86:89]
	v_mfma_f32_16x16x32_bf16 v[82:85], v[180:183], v[216:219], v[82:85]
	v_mfma_f32_16x16x32_bf16 v[70:73], v[172:175], v[224:227], v[70:73]
	v_mfma_f32_16x16x32_bf16 v[66:69], v[180:183], v[224:227], v[66:69]
	s_setprio 0
	s_barrier
	ds_read_b128 v[184:187], v151 offset:16384
	ds_read_b128 v[188:191], v151 offset:17408
	ds_read_b128 v[204:207], v151 offset:18432
	ds_read_b128 v[208:211], v151 offset:19456
	ds_read_b128 v[212:215], v151 offset:20480
	ds_read_b128 v[216:219], v151 offset:21504
	ds_read_b128 v[220:223], v151 offset:22528
	ds_read_b128 v[224:227], v151 offset:23552
	s_add_i32 s40, s40, s22
	v_lshl_add_u64 v[192:193], s[16:17], 0, v[134:135]
	s_mov_b32 m0, s40
	s_nop 0
	global_load_lds_dwordx4 v[192:193], off
	s_add_i32 m0, s40, 0x2000
	s_add_u32 s40, s16, 0x80000
	v_lshl_add_u64 v[198:199], s[16:17], 0, v[130:131]
	s_addc_u32 s41, s17, 0
	s_add_i32 s42, s42, s22
	global_load_lds_dwordx4 v[198:199], off
	v_lshl_add_u64 v[228:229], s[40:41], 0, v[134:135]
	s_mov_b32 m0, s42
	v_lshl_add_u64 v[230:231], s[18:19], 0, v[132:133]
	global_load_lds_dwordx4 v[228:229], off
	v_lshl_add_u64 v[228:229], s[40:41], 0, v[130:131]
	s_add_i32 m0, s42, 0x2000
	s_nop 0
	global_load_lds_dwordx4 v[228:229], off
	v_lshl_add_u64 v[228:229], s[18:19], 0, v[136:137]
	s_waitcnt vmcnt(6)
	s_waitcnt lgkmcnt(0)
	v_mfma_f32_16x16x32_bf16 v[62:65], v[152:155], v[184:187], v[62:65]
	v_mfma_f32_16x16x32_bf16 v[58:61], v[160:163], v[184:187], v[58:61]
	s_barrier
	s_setprio 1
	v_mfma_f32_16x16x32_bf16 v[46:49], v[152:155], v[204:207], v[46:49]
	v_mfma_f32_16x16x32_bf16 v[42:45], v[160:163], v[204:207], v[42:45]
	v_mfma_f32_16x16x32_bf16 v[30:33], v[152:155], v[212:215], v[30:33]
	v_mfma_f32_16x16x32_bf16 v[26:29], v[160:163], v[212:215], v[26:29]
	v_mfma_f32_16x16x32_bf16 v[14:17], v[152:155], v[220:223], v[14:17]
	v_mfma_f32_16x16x32_bf16 v[10:13], v[160:163], v[220:223], v[10:13]
	v_mfma_f32_16x16x32_bf16 v[62:65], v[156:159], v[188:191], v[62:65]
	v_mfma_f32_16x16x32_bf16 v[58:61], v[164:167], v[188:191], v[58:61]
	v_mfma_f32_16x16x32_bf16 v[46:49], v[156:159], v[208:211], v[46:49]
	v_mfma_f32_16x16x32_bf16 v[42:45], v[164:167], v[208:211], v[42:45]
	v_mfma_f32_16x16x32_bf16 v[30:33], v[156:159], v[216:219], v[30:33]
	v_mfma_f32_16x16x32_bf16 v[26:29], v[164:167], v[216:219], v[26:29]
	v_mfma_f32_16x16x32_bf16 v[14:17], v[156:159], v[224:227], v[14:17]
	v_mfma_f32_16x16x32_bf16 v[10:13], v[164:167], v[224:227], v[10:13]
	v_mfma_f32_16x16x32_bf16 v[54:57], v[168:171], v[184:187], v[54:57]
	v_mfma_f32_16x16x32_bf16 v[50:53], v[176:179], v[184:187], v[50:53]
	v_mfma_f32_16x16x32_bf16 v[38:41], v[168:171], v[204:207], v[38:41]
	v_mfma_f32_16x16x32_bf16 v[34:37], v[176:179], v[204:207], v[34:37]
	v_mfma_f32_16x16x32_bf16 v[22:25], v[168:171], v[212:215], v[22:25]
	v_mfma_f32_16x16x32_bf16 v[18:21], v[176:179], v[212:215], v[18:21]
	v_mfma_f32_16x16x32_bf16 v[6:9], v[168:171], v[220:223], v[6:9]
	v_mfma_f32_16x16x32_bf16 v[2:5], v[176:179], v[220:223], v[2:5]
	v_mfma_f32_16x16x32_bf16 v[54:57], v[172:175], v[188:191], v[54:57]
	v_mfma_f32_16x16x32_bf16 v[50:53], v[180:183], v[188:191], v[50:53]
	v_mfma_f32_16x16x32_bf16 v[38:41], v[172:175], v[208:211], v[38:41]
	v_mfma_f32_16x16x32_bf16 v[34:37], v[180:183], v[208:211], v[34:37]
	v_mfma_f32_16x16x32_bf16 v[22:25], v[172:175], v[216:219], v[22:25]
	v_mfma_f32_16x16x32_bf16 v[18:21], v[180:183], v[216:219], v[18:21]
	v_mfma_f32_16x16x32_bf16 v[6:9], v[172:175], v[224:227], v[6:9]
	v_mfma_f32_16x16x32_bf16 v[2:5], v[180:183], v[224:227], v[2:5]
	s_setprio 0
	s_barrier
	s_mov_b32 m0, s23
	s_nop 0
	global_load_lds_dwordx4 v[228:229], off
	s_mov_b32 m0, s24
	s_nop 0
	global_load_lds_dwordx4 v[230:231], off
	ds_read_b128 v[152:155], v145 offset:32768
	ds_read_b128 v[156:159], v145 offset:33792
	ds_read_b128 v[160:163], v145 offset:34816
	ds_read_b128 v[164:167], v145 offset:35840
	ds_read_b128 v[168:171], v145 offset:49152
	ds_read_b128 v[172:175], v145 offset:50176
	ds_read_b128 v[176:179], v145 offset:51200
	ds_read_b128 v[180:183], v145 offset:52224
	ds_read_b128 v[184:187], v151 offset:32768
	ds_read_b128 v[188:191], v151 offset:33792
	ds_read_b128 v[204:207], v151 offset:34816
	ds_read_b128 v[208:211], v151 offset:35840
	ds_read_b128 v[212:215], v151 offset:36864
	ds_read_b128 v[216:219], v151 offset:37888
	ds_read_b128 v[220:223], v151 offset:38912
	ds_read_b128 v[224:227], v151 offset:39936
	s_add_i32 s40, 0, 0x18000
	s_add_i32 s41, 0, 0x1c000
	s_add_u32 s18, s18, 0x80000
	s_addc_u32 s19, s19, 0
	s_mov_b32 m0, s25
	v_lshl_add_u64 v[232:233], s[18:19], 0, v[136:137]
	global_load_lds_dwordx4 v[232:233], off
	v_lshl_add_u64 v[232:233], s[18:19], 0, v[132:133]
	s_mov_b32 m0, s26
	s_nop 0
	global_load_lds_dwordx4 v[232:233], off
	s_waitcnt vmcnt(8)
	s_waitcnt lgkmcnt(0)
	v_mfma_f32_16x16x32_bf16 v[126:129], v[152:155], v[184:187], v[126:129]
	v_mfma_f32_16x16x32_bf16 v[122:125], v[160:163], v[184:187], v[122:125]
	s_barrier
	s_setprio 1
	v_mfma_f32_16x16x32_bf16 v[110:113], v[152:155], v[204:207], v[110:113]
	v_mfma_f32_16x16x32_bf16 v[106:109], v[160:163], v[204:207], v[106:109]
	v_mfma_f32_16x16x32_bf16 v[94:97], v[152:155], v[212:215], v[94:97]
	v_mfma_f32_16x16x32_bf16 v[90:93], v[160:163], v[212:215], v[90:93]
	v_mfma_f32_16x16x32_bf16 v[78:81], v[152:155], v[220:223], v[78:81]
	v_mfma_f32_16x16x32_bf16 v[74:77], v[160:163], v[220:223], v[74:77]
	v_mfma_f32_16x16x32_bf16 v[126:129], v[156:159], v[188:191], v[126:129]
	v_mfma_f32_16x16x32_bf16 v[122:125], v[164:167], v[188:191], v[122:125]
	v_mfma_f32_16x16x32_bf16 v[110:113], v[156:159], v[208:211], v[110:113]
	v_mfma_f32_16x16x32_bf16 v[106:109], v[164:167], v[208:211], v[106:109]
	v_mfma_f32_16x16x32_bf16 v[94:97], v[156:159], v[216:219], v[94:97]
	v_mfma_f32_16x16x32_bf16 v[90:93], v[164:167], v[216:219], v[90:93]
	v_mfma_f32_16x16x32_bf16 v[78:81], v[156:159], v[224:227], v[78:81]
	v_mfma_f32_16x16x32_bf16 v[74:77], v[164:167], v[224:227], v[74:77]
	v_mfma_f32_16x16x32_bf16 v[118:121], v[168:171], v[184:187], v[118:121]
	v_mfma_f32_16x16x32_bf16 v[114:117], v[176:179], v[184:187], v[114:117]
	v_mfma_f32_16x16x32_bf16 v[102:105], v[168:171], v[204:207], v[102:105]
	v_mfma_f32_16x16x32_bf16 v[98:101], v[176:179], v[204:207], v[98:101]
	v_mfma_f32_16x16x32_bf16 v[86:89], v[168:171], v[212:215], v[86:89]
	v_mfma_f32_16x16x32_bf16 v[82:85], v[176:179], v[212:215], v[82:85]
	v_mfma_f32_16x16x32_bf16 v[70:73], v[168:171], v[220:223], v[70:73]
	v_mfma_f32_16x16x32_bf16 v[66:69], v[176:179], v[220:223], v[66:69]
	v_mfma_f32_16x16x32_bf16 v[118:121], v[172:175], v[188:191], v[118:121]
	v_mfma_f32_16x16x32_bf16 v[114:117], v[180:183], v[188:191], v[114:117]
	v_mfma_f32_16x16x32_bf16 v[102:105], v[172:175], v[208:211], v[102:105]
	v_mfma_f32_16x16x32_bf16 v[98:101], v[180:183], v[208:211], v[98:101]
	v_mfma_f32_16x16x32_bf16 v[86:89], v[172:175], v[216:219], v[86:89]
	v_mfma_f32_16x16x32_bf16 v[82:85], v[180:183], v[216:219], v[82:85]
	v_mfma_f32_16x16x32_bf16 v[70:73], v[172:175], v[224:227], v[70:73]
	v_mfma_f32_16x16x32_bf16 v[66:69], v[180:183], v[224:227], v[66:69]
	s_setprio 0
	s_barrier
	ds_read_b128 v[184:187], v151 offset:49152
	ds_read_b128 v[188:191], v151 offset:50176
	ds_read_b128 v[204:207], v151 offset:51200
	ds_read_b128 v[208:211], v151 offset:52224
	ds_read_b128 v[212:215], v151 offset:53248
	ds_read_b128 v[216:219], v151 offset:54272
	ds_read_b128 v[220:223], v151 offset:55296
	ds_read_b128 v[224:227], v151 offset:56320
	s_add_i32 s18, s40, s22
	v_lshl_add_u64 v[192:193], v[192:193], 0, s[94:95]
	s_mov_b32 m0, s18
	s_nop 0
	global_load_lds_dwordx4 v[192:193], off
	s_add_i32 m0, s18, 0x2000
	s_add_u32 s16, s16, 0x80080
	v_lshl_add_u64 v[192:193], v[198:199], 0, s[94:95]
	s_addc_u32 s17, s17, 0
	s_add_i32 s18, s41, s22
	global_load_lds_dwordx4 v[192:193], off
	v_lshl_add_u64 v[192:193], s[16:17], 0, v[134:135]
	s_mov_b32 m0, s18
	s_nop 0
	global_load_lds_dwordx4 v[192:193], off
	v_lshl_add_u64 v[192:193], s[16:17], 0, v[130:131]
	s_add_i32 m0, s18, 0x2000
	s_nop 0
	global_load_lds_dwordx4 v[192:193], off
	s_waitcnt vmcnt(6)
	s_waitcnt lgkmcnt(0)
	v_mfma_f32_16x16x32_bf16 v[62:65], v[152:155], v[184:187], v[62:65]
	v_mfma_f32_16x16x32_bf16 v[58:61], v[160:163], v[184:187], v[58:61]
	s_barrier
	s_setprio 1
	v_mfma_f32_16x16x32_bf16 v[46:49], v[152:155], v[204:207], v[46:49]
	v_mfma_f32_16x16x32_bf16 v[42:45], v[160:163], v[204:207], v[42:45]
	v_mfma_f32_16x16x32_bf16 v[30:33], v[152:155], v[212:215], v[30:33]
	v_mfma_f32_16x16x32_bf16 v[26:29], v[160:163], v[212:215], v[26:29]
	v_mfma_f32_16x16x32_bf16 v[14:17], v[152:155], v[220:223], v[14:17]
	v_mfma_f32_16x16x32_bf16 v[10:13], v[160:163], v[220:223], v[10:13]
	v_mfma_f32_16x16x32_bf16 v[62:65], v[156:159], v[188:191], v[62:65]
	v_mfma_f32_16x16x32_bf16 v[58:61], v[164:167], v[188:191], v[58:61]
	v_mfma_f32_16x16x32_bf16 v[46:49], v[156:159], v[208:211], v[46:49]
	v_mfma_f32_16x16x32_bf16 v[42:45], v[164:167], v[208:211], v[42:45]
	v_mfma_f32_16x16x32_bf16 v[30:33], v[156:159], v[216:219], v[30:33]
	v_mfma_f32_16x16x32_bf16 v[26:29], v[164:167], v[216:219], v[26:29]
	s_add_i32 s39, s39, 2
	v_mfma_f32_16x16x32_bf16 v[14:17], v[156:159], v[224:227], v[14:17]
	v_mfma_f32_16x16x32_bf16 v[10:13], v[164:167], v[224:227], v[10:13]
	s_add_u32 s14, s14, 0x100
	v_mfma_f32_16x16x32_bf16 v[54:57], v[168:171], v[184:187], v[54:57]
	v_mfma_f32_16x16x32_bf16 v[50:53], v[176:179], v[184:187], v[50:53]
	s_addc_u32 s15, s15, 0
	v_mfma_f32_16x16x32_bf16 v[38:41], v[168:171], v[204:207], v[38:41]
	v_mfma_f32_16x16x32_bf16 v[34:37], v[176:179], v[204:207], v[34:37]
	s_add_u32 s37, s37, 0x100
	v_mfma_f32_16x16x32_bf16 v[22:25], v[168:171], v[212:215], v[22:25]
	v_mfma_f32_16x16x32_bf16 v[18:21], v[176:179], v[212:215], v[18:21]
	s_addc_u32 s38, s38, 0
	v_mfma_f32_16x16x32_bf16 v[6:9], v[168:171], v[220:223], v[6:9]
	v_mfma_f32_16x16x32_bf16 v[2:5], v[176:179], v[220:223], v[2:5]
	s_cmp_gt_u32 s39, 29
	v_mfma_f32_16x16x32_bf16 v[54:57], v[172:175], v[188:191], v[54:57]
	v_mfma_f32_16x16x32_bf16 v[50:53], v[180:183], v[188:191], v[50:53]
	v_mfma_f32_16x16x32_bf16 v[38:41], v[172:175], v[208:211], v[38:41]
	v_mfma_f32_16x16x32_bf16 v[34:37], v[180:183], v[208:211], v[34:37]
	v_mfma_f32_16x16x32_bf16 v[22:25], v[172:175], v[216:219], v[22:25]
	v_mfma_f32_16x16x32_bf16 v[18:21], v[180:183], v[216:219], v[18:21]
	v_mfma_f32_16x16x32_bf16 v[6:9], v[172:175], v[224:227], v[6:9]
	v_mfma_f32_16x16x32_bf16 v[2:5], v[180:183], v[224:227], v[2:5]
	s_setprio 0
	s_barrier
	s_cbranch_scc0 .LBB0_530
	s_and_b64 vcc, exec, s[6:7]
	s_cbranch_vccz .LBB0_533
	s_barrier

.LBB0_840:
	v_lshl_add_u64 v[4:5], s[20:21], 0, v[194:195]
	v_mov_b32_e32 v205, v195
	v_lshl_add_u64 v[14:15], s[20:21], 0, v[204:205]
	v_mov_b32_e32 v209, v195
	s_add_i32 m0, s26, 0x18000
	v_lshl_add_u64 v[4:5], v[4:5], 0, s[94:95]
	v_lshl_add_u64 v[20:21], s[18:19], 0, v[208:209]
	v_mov_b32_e32 v207, v195
	s_waitcnt vmcnt(2)
	s_barrier
	global_load_lds_dwordx4 v[4:5], off
	v_lshl_add_u64 v[4:5], v[14:15], 0, s[94:95]
	s_add_i32 m0, s26, 0x1a000
	s_add_i32 s33, s26, 0x8000
	v_lshl_add_u64 v[22:23], s[18:19], 0, v[206:207]
	global_load_lds_dwordx4 v[4:5], off
	v_lshl_add_u64 v[4:5], v[20:21], 0, s[94:95]
	s_mov_b32 m0, s33
	s_add_i32 s34, s26, 0xa000
	v_lshl_add_u64 v[16:17], s[0:1], 0, v[194:195]
	global_load_lds_dwordx4 v[4:5], off
	v_lshl_add_u64 v[4:5], v[22:23], 0, s[94:95]
	s_mov_b32 m0, s34
	v_lshl_add_u64 v[18:19], s[0:1], 0, v[204:205]
	global_load_lds_dwordx4 v[4:5], off
	s_add_i32 m0, s26, 0x1c000
	v_lshl_add_u64 v[4:5], v[16:17], 0, s[94:95]
	global_load_lds_dwordx4 v[4:5], off
	v_lshl_add_u64 v[4:5], v[18:19], 0, s[94:95]
	s_add_i32 m0, s26, 0x1e000
	v_bfe_u32 v13, v6, 4, 2
	global_load_lds_dwordx4 v[4:5], off
	v_and_b32_e32 v14, 15, v6
	v_lshlrev_b32_e32 v15, 4, v13
	v_lshlrev_b32_e32 v6, 2, v6
	v_lshl_or_b32 v197, s4, 6, v14
	v_lshl_or_b32 v14, v14, 6, v15
	s_lshl_b32 s0, s4, 13
	v_and_b32_e32 v6, 32, v6
	v_bitop3_b32 v15, v14, s0, v6 bitop3:0xde
	s_lshl_b32 s0, s3, 5
	s_and_b32 s0, s0, 0x60
	s_lshl_b32 s1, s0, 7
	v_bitop3_b32 v198, v14, s1, v6 bitop3:0xde
	v_add_u32_e32 v198, 0x10000, v198
	v_add_u32_e32 v6, v12, v10
	s_waitcnt vmcnt(6)
	s_add_i32 s35, s53, -2
	v_add_lshl_u32 v10, v6, v11, 1
	v_add_u32_e32 v6, v9, v7
	s_cmpk_lt_u32 s2, 0x100
	v_mov_b32_e32 v11, v195
	v_add_lshl_u32 v6, v6, v8, 1
	v_mov_b32_e32 v7, v195
	v_mov_b32_e32 v3, v2
	v_mov_b32_e32 v4, v2
	v_mov_b32_e32 v5, v2
	s_cselect_b64 s[14:15], -1, 0
	s_mov_b32 s36, 0
	v_cmp_eq_u32_e64 s[2:3], 0, v13
	s_mov_b32 s11, s85
	v_lshl_or_b32 v199, v13, 3, s0
	v_lshl_add_u64 v[210:211], s[12:13], 0, v[10:11]
	v_lshl_add_u64 v[212:213], s[12:13], 0, v[6:7]
	v_add_u32_e32 v234, 0, v15
	s_barrier
	s_branch .LBB0_843

.LBB0_850:
	s_sub_u32 vcc_lo, s18, s12
	s_subb_u32 vcc_hi, s19, 0
	v_lshl_add_u64 v[214:215], vcc, 0, v[210:211]
	s_mov_b32 m0, s33
	s_nop 0
	global_load_lds_dwordx4 v[214:215], off
	v_lshl_add_u64 v[214:215], vcc, 0, v[212:213]
	s_mov_b32 m0, s34
	s_nop 0
	global_load_lds_dwordx4 v[214:215], off
	ds_read_b128 v[66:69], v198
	ds_read_b128 v[78:81], v198 offset:1024
	ds_read_b128 v[82:85], v198 offset:2048
	ds_read_b128 v[98:101], v198 offset:3072
	ds_read_b128 v[106:109], v198 offset:16384
	ds_read_b128 v[118:121], v198 offset:17408
	ds_read_b128 v[130:133], v198 offset:18432
	ds_read_b128 v[142:145], v198 offset:19456
	ds_read_b128 v[150:153], v234
	ds_read_b128 v[154:157], v234 offset:1024
	ds_read_b128 v[158:161], v234 offset:2048
	ds_read_b128 v[162:165], v234 offset:3072
	ds_read_b128 v[170:173], v234 offset:4096
	ds_read_b128 v[174:177], v234 offset:5120
	ds_read_b128 v[178:181], v234 offset:6144
	ds_read_b128 v[190:193], v234 offset:7168
	s_add_i32 s55, s20, 2
	s_add_u32 s56, s18, 0x80
	s_addc_u32 s21, s19, 0
	s_add_i32 s58, 0, 0x10000
	s_cmp_eq_u32 s35, s20
	s_cselect_b32 s21, s1, s21
	s_cselect_b32 s20, s0, s56
	s_cselect_b32 s57, s17, s54
	s_cselect_b32 s56, s16, s51
	s_add_i32 s59, 0, 0x14000
	v_lshl_add_u64 v[214:215], s[18:19], 0, v[210:211]
	s_add_i32 m0, s26, 0xc000
	s_nop 0
	global_load_lds_dwordx4 v[214:215], off
	v_lshl_add_u64 v[214:215], s[18:19], 0, v[212:213]
	s_add_i32 m0, s26, 0xe000
	s_nop 0
	global_load_lds_dwordx4 v[214:215], off
	s_waitcnt vmcnt(8)
	s_waitcnt lgkmcnt(0)
	v_mfma_f32_16x16x32_bf16 v[186:189], v[66:69], v[150:153], v[186:189]
	v_mfma_f32_16x16x32_bf16 v[182:185], v[82:85], v[150:153], v[182:185]
	s_barrier
	s_setprio 1
	v_mfma_f32_16x16x32_bf16 v[138:141], v[66:69], v[158:161], v[138:141]
	v_mfma_f32_16x16x32_bf16 v[134:137], v[82:85], v[158:161], v[134:137]
	v_mfma_f32_16x16x32_bf16 v[114:117], v[66:69], v[170:173], v[114:117]
	v_mfma_f32_16x16x32_bf16 v[110:113], v[82:85], v[170:173], v[110:113]
	v_mfma_f32_16x16x32_bf16 v[90:93], v[66:69], v[178:181], v[90:93]
	v_mfma_f32_16x16x32_bf16 v[86:89], v[82:85], v[178:181], v[86:89]
	v_mfma_f32_16x16x32_bf16 v[186:189], v[78:81], v[154:157], v[186:189]
	v_mfma_f32_16x16x32_bf16 v[182:185], v[98:101], v[154:157], v[182:185]
	v_mfma_f32_16x16x32_bf16 v[138:141], v[78:81], v[162:165], v[138:141]
	v_mfma_f32_16x16x32_bf16 v[134:137], v[98:101], v[162:165], v[134:137]
	v_mfma_f32_16x16x32_bf16 v[114:117], v[78:81], v[174:177], v[114:117]
	v_mfma_f32_16x16x32_bf16 v[110:113], v[98:101], v[174:177], v[110:113]
	v_mfma_f32_16x16x32_bf16 v[90:93], v[78:81], v[190:193], v[90:93]
	v_mfma_f32_16x16x32_bf16 v[86:89], v[98:101], v[190:193], v[86:89]
	v_mfma_f32_16x16x32_bf16 v[166:169], v[106:109], v[150:153], v[166:169]
	v_mfma_f32_16x16x32_bf16 v[146:149], v[130:133], v[150:153], v[146:149]
	v_mfma_f32_16x16x32_bf16 v[126:129], v[106:109], v[158:161], v[126:129]
	v_mfma_f32_16x16x32_bf16 v[122:125], v[130:133], v[158:161], v[122:125]
	v_mfma_f32_16x16x32_bf16 v[102:105], v[106:109], v[170:173], v[102:105]
	v_mfma_f32_16x16x32_bf16 v[94:97], v[130:133], v[170:173], v[94:97]
	v_mfma_f32_16x16x32_bf16 v[74:77], v[106:109], v[178:181], v[74:77]
	v_mfma_f32_16x16x32_bf16 v[70:73], v[130:133], v[178:181], v[70:73]
	v_mfma_f32_16x16x32_bf16 v[166:169], v[118:121], v[154:157], v[166:169]
	v_mfma_f32_16x16x32_bf16 v[146:149], v[142:145], v[154:157], v[146:149]
	v_mfma_f32_16x16x32_bf16 v[126:129], v[118:121], v[162:165], v[126:129]
	v_mfma_f32_16x16x32_bf16 v[122:125], v[142:145], v[162:165], v[122:125]
	v_mfma_f32_16x16x32_bf16 v[102:105], v[118:121], v[174:177], v[102:105]
	v_mfma_f32_16x16x32_bf16 v[94:97], v[142:145], v[174:177], v[94:97]
	v_mfma_f32_16x16x32_bf16 v[74:77], v[118:121], v[190:193], v[74:77]
	v_mfma_f32_16x16x32_bf16 v[70:73], v[142:145], v[190:193], v[70:73]
	s_setprio 0
	s_barrier
	ds_read_b128 v[150:153], v234 offset:16384
	ds_read_b128 v[154:157], v234 offset:17408
	ds_read_b128 v[158:161], v234 offset:18432
	ds_read_b128 v[162:165], v234 offset:19456
	ds_read_b128 v[170:173], v234 offset:20480
	ds_read_b128 v[174:177], v234 offset:21504
	ds_read_b128 v[178:181], v234 offset:22528
	ds_read_b128 v[190:193], v234 offset:23552
	s_add_i32 s58, s58, s24
	v_lshl_add_u64 v[214:215], s[56:57], 0, v[194:195]
	s_mov_b32 m0, s58
	s_nop 0
	global_load_lds_dwordx4 v[214:215], off
	s_add_i32 m0, s58, 0x2000
	v_lshl_add_u64 v[216:217], s[56:57], 0, v[204:205]
	s_add_u32 s56, s56, s12
	s_addc_u32 s57, s57, 0
	s_add_i32 s58, s59, s24
	global_load_lds_dwordx4 v[216:217], off
	v_lshl_add_u64 v[218:219], s[56:57], 0, v[194:195]
	s_mov_b32 m0, s58
	v_lshl_add_u64 v[220:221], s[56:57], 0, v[204:205]
	global_load_lds_dwordx4 v[218:219], off
	s_add_i32 m0, s58, 0x2000
	v_lshl_add_u64 v[222:223], s[20:21], 0, v[208:209]
	global_load_lds_dwordx4 v[220:221], off
	v_lshl_add_u64 v[224:225], s[20:21], 0, v[206:207]
	s_waitcnt vmcnt(6)
	s_waitcnt lgkmcnt(0)
	v_mfma_f32_16x16x32_bf16 v[62:65], v[66:69], v[150:153], v[62:65]
	v_mfma_f32_16x16x32_bf16 v[58:61], v[82:85], v[150:153], v[58:61]
	s_barrier
	s_setprio 1
	v_mfma_f32_16x16x32_bf16 v[46:49], v[66:69], v[158:161], v[46:49]
	v_mfma_f32_16x16x32_bf16 v[42:45], v[82:85], v[158:161], v[42:45]
	v_mfma_f32_16x16x32_bf16 v[30:33], v[66:69], v[170:173], v[30:33]
	v_mfma_f32_16x16x32_bf16 v[26:29], v[82:85], v[170:173], v[26:29]
	v_mfma_f32_16x16x32_bf16 v[14:17], v[66:69], v[178:181], v[14:17]
	v_mfma_f32_16x16x32_bf16 v[10:13], v[82:85], v[178:181], v[10:13]
	v_mfma_f32_16x16x32_bf16 v[62:65], v[78:81], v[154:157], v[62:65]
	v_mfma_f32_16x16x32_bf16 v[58:61], v[98:101], v[154:157], v[58:61]
	v_mfma_f32_16x16x32_bf16 v[46:49], v[78:81], v[162:165], v[46:49]
	v_mfma_f32_16x16x32_bf16 v[42:45], v[98:101], v[162:165], v[42:45]
	v_mfma_f32_16x16x32_bf16 v[30:33], v[78:81], v[174:177], v[30:33]
	v_mfma_f32_16x16x32_bf16 v[26:29], v[98:101], v[174:177], v[26:29]
	v_mfma_f32_16x16x32_bf16 v[14:17], v[78:81], v[190:193], v[14:17]
	v_mfma_f32_16x16x32_bf16 v[10:13], v[98:101], v[190:193], v[10:13]
	v_mfma_f32_16x16x32_bf16 v[54:57], v[106:109], v[150:153], v[54:57]
	v_mfma_f32_16x16x32_bf16 v[50:53], v[130:133], v[150:153], v[50:53]
	v_mfma_f32_16x16x32_bf16 v[38:41], v[106:109], v[158:161], v[38:41]
	v_mfma_f32_16x16x32_bf16 v[34:37], v[130:133], v[158:161], v[34:37]
	v_mfma_f32_16x16x32_bf16 v[22:25], v[106:109], v[170:173], v[22:25]
	v_mfma_f32_16x16x32_bf16 v[18:21], v[130:133], v[170:173], v[18:21]
	v_mfma_f32_16x16x32_bf16 v[6:9], v[106:109], v[178:181], v[6:9]
	v_mfma_f32_16x16x32_bf16 v[2:5], v[130:133], v[178:181], v[2:5]
	v_mfma_f32_16x16x32_bf16 v[54:57], v[118:121], v[154:157], v[54:57]
	v_mfma_f32_16x16x32_bf16 v[50:53], v[142:145], v[154:157], v[50:53]
	v_mfma_f32_16x16x32_bf16 v[38:41], v[118:121], v[162:165], v[38:41]
	v_mfma_f32_16x16x32_bf16 v[34:37], v[142:145], v[162:165], v[34:37]
	v_mfma_f32_16x16x32_bf16 v[22:25], v[118:121], v[174:177], v[22:25]
	v_mfma_f32_16x16x32_bf16 v[18:21], v[142:145], v[174:177], v[18:21]
	v_mfma_f32_16x16x32_bf16 v[6:9], v[118:121], v[190:193], v[6:9]
	v_mfma_f32_16x16x32_bf16 v[2:5], v[142:145], v[190:193], v[2:5]
	s_setprio 0
	s_barrier
	s_mov_b32 m0, s26
	s_nop 0
	global_load_lds_dwordx4 v[222:223], off
	s_mov_b32 m0, s27
	s_nop 0
	global_load_lds_dwordx4 v[224:225], off
	ds_read_b128 v[66:69], v198 offset:32768
	ds_read_b128 v[78:81], v198 offset:33792
	ds_read_b128 v[82:85], v198 offset:34816
	ds_read_b128 v[98:101], v198 offset:35840
	ds_read_b128 v[106:109], v198 offset:49152
	ds_read_b128 v[118:121], v198 offset:50176
	ds_read_b128 v[130:133], v198 offset:51200
	ds_read_b128 v[142:145], v198 offset:52224
	ds_read_b128 v[150:153], v234 offset:32768
	ds_read_b128 v[154:157], v234 offset:33792
	ds_read_b128 v[158:161], v234 offset:34816
	ds_read_b128 v[162:165], v234 offset:35840
	ds_read_b128 v[170:173], v234 offset:36864
	ds_read_b128 v[174:177], v234 offset:37888
	ds_read_b128 v[178:181], v234 offset:38912
	ds_read_b128 v[190:193], v234 offset:39936
	s_add_i32 s56, 0, 0x18000
	s_add_i32 s57, 0, 0x1c000
	s_add_u32 s20, s20, s12
	s_addc_u32 s21, s21, 0
	s_mov_b32 m0, s28
	v_lshl_add_u64 v[226:227], s[20:21], 0, v[208:209]
	global_load_lds_dwordx4 v[226:227], off
	v_lshl_add_u64 v[226:227], s[20:21], 0, v[206:207]
	s_mov_b32 m0, s29
	s_nop 0
	global_load_lds_dwordx4 v[226:227], off
	s_waitcnt vmcnt(8)
	s_waitcnt lgkmcnt(0)
	v_mfma_f32_16x16x32_bf16 v[186:189], v[66:69], v[150:153], v[186:189]
	v_mfma_f32_16x16x32_bf16 v[182:185], v[82:85], v[150:153], v[182:185]
	s_barrier
	s_setprio 1
	v_mfma_f32_16x16x32_bf16 v[138:141], v[66:69], v[158:161], v[138:141]
	v_mfma_f32_16x16x32_bf16 v[134:137], v[82:85], v[158:161], v[134:137]
	v_mfma_f32_16x16x32_bf16 v[114:117], v[66:69], v[170:173], v[114:117]
	v_mfma_f32_16x16x32_bf16 v[110:113], v[82:85], v[170:173], v[110:113]
	v_mfma_f32_16x16x32_bf16 v[90:93], v[66:69], v[178:181], v[90:93]
	v_mfma_f32_16x16x32_bf16 v[86:89], v[82:85], v[178:181], v[86:89]
	v_mfma_f32_16x16x32_bf16 v[186:189], v[78:81], v[154:157], v[186:189]
	v_mfma_f32_16x16x32_bf16 v[182:185], v[98:101], v[154:157], v[182:185]
	v_mfma_f32_16x16x32_bf16 v[138:141], v[78:81], v[162:165], v[138:141]
	v_mfma_f32_16x16x32_bf16 v[134:137], v[98:101], v[162:165], v[134:137]
	v_mfma_f32_16x16x32_bf16 v[114:117], v[78:81], v[174:177], v[114:117]
	v_mfma_f32_16x16x32_bf16 v[110:113], v[98:101], v[174:177], v[110:113]
	v_mfma_f32_16x16x32_bf16 v[90:93], v[78:81], v[190:193], v[90:93]
	v_mfma_f32_16x16x32_bf16 v[86:89], v[98:101], v[190:193], v[86:89]
	v_mfma_f32_16x16x32_bf16 v[166:169], v[106:109], v[150:153], v[166:169]
	v_mfma_f32_16x16x32_bf16 v[146:149], v[130:133], v[150:153], v[146:149]
	v_mfma_f32_16x16x32_bf16 v[126:129], v[106:109], v[158:161], v[126:129]
	v_mfma_f32_16x16x32_bf16 v[122:125], v[130:133], v[158:161], v[122:125]
	v_mfma_f32_16x16x32_bf16 v[102:105], v[106:109], v[170:173], v[102:105]
	v_mfma_f32_16x16x32_bf16 v[94:97], v[130:133], v[170:173], v[94:97]
	v_mfma_f32_16x16x32_bf16 v[74:77], v[106:109], v[178:181], v[74:77]
	v_mfma_f32_16x16x32_bf16 v[70:73], v[130:133], v[178:181], v[70:73]
	v_mfma_f32_16x16x32_bf16 v[166:169], v[118:121], v[154:157], v[166:169]
	v_mfma_f32_16x16x32_bf16 v[146:149], v[142:145], v[154:157], v[146:149]
	v_mfma_f32_16x16x32_bf16 v[126:129], v[118:121], v[162:165], v[126:129]
	v_mfma_f32_16x16x32_bf16 v[122:125], v[142:145], v[162:165], v[122:125]
	v_mfma_f32_16x16x32_bf16 v[102:105], v[118:121], v[174:177], v[102:105]
	v_mfma_f32_16x16x32_bf16 v[94:97], v[142:145], v[174:177], v[94:97]
	v_mfma_f32_16x16x32_bf16 v[74:77], v[118:121], v[190:193], v[74:77]
	v_mfma_f32_16x16x32_bf16 v[70:73], v[142:145], v[190:193], v[70:73]
	s_setprio 0
	s_barrier
	ds_read_b128 v[150:153], v234 offset:49152
	ds_read_b128 v[154:157], v234 offset:50176
	ds_read_b128 v[158:161], v234 offset:51200
	ds_read_b128 v[162:165], v234 offset:52224
	ds_read_b128 v[170:173], v234 offset:53248
	ds_read_b128 v[174:177], v234 offset:54272
	ds_read_b128 v[178:181], v234 offset:55296
	ds_read_b128 v[190:193], v234 offset:56320
	s_add_i32 s20, s56, s24
	v_lshl_add_u64 v[214:215], v[214:215], 0, s[94:95]
	s_mov_b32 m0, s20
	s_nop 0
	global_load_lds_dwordx4 v[214:215], off
	v_lshl_add_u64 v[214:215], v[216:217], 0, s[94:95]
	s_add_i32 m0, s20, 0x2000
	s_add_i32 s20, s57, s24
	global_load_lds_dwordx4 v[214:215], off
	v_lshl_add_u64 v[214:215], v[218:219], 0, s[94:95]
	s_mov_b32 m0, s20
	s_nop 0
	global_load_lds_dwordx4 v[214:215], off
	v_lshl_add_u64 v[214:215], v[220:221], 0, s[94:95]
	s_add_i32 m0, s20, 0x2000
	s_nop 0
	global_load_lds_dwordx4 v[214:215], off
	s_waitcnt vmcnt(6)
	s_waitcnt lgkmcnt(0)
	v_mfma_f32_16x16x32_bf16 v[62:65], v[66:69], v[150:153], v[62:65]
	v_mfma_f32_16x16x32_bf16 v[58:61], v[82:85], v[150:153], v[58:61]
	s_barrier
	s_setprio 1
	v_mfma_f32_16x16x32_bf16 v[46:49], v[66:69], v[158:161], v[46:49]
	v_mfma_f32_16x16x32_bf16 v[42:45], v[82:85], v[158:161], v[42:45]
	v_mfma_f32_16x16x32_bf16 v[30:33], v[66:69], v[170:173], v[30:33]
	v_mfma_f32_16x16x32_bf16 v[26:29], v[82:85], v[170:173], v[26:29]
	v_mfma_f32_16x16x32_bf16 v[14:17], v[66:69], v[178:181], v[14:17]
	v_mfma_f32_16x16x32_bf16 v[10:13], v[82:85], v[178:181], v[10:13]
	v_mfma_f32_16x16x32_bf16 v[62:65], v[78:81], v[154:157], v[62:65]
	v_mfma_f32_16x16x32_bf16 v[58:61], v[98:101], v[154:157], v[58:61]
	v_mfma_f32_16x16x32_bf16 v[46:49], v[78:81], v[162:165], v[46:49]
	v_mfma_f32_16x16x32_bf16 v[42:45], v[98:101], v[162:165], v[42:45]
	v_mfma_f32_16x16x32_bf16 v[30:33], v[78:81], v[174:177], v[30:33]
	v_mfma_f32_16x16x32_bf16 v[26:29], v[98:101], v[174:177], v[26:29]
	s_add_u32 s18, s18, 0x100
	v_mfma_f32_16x16x32_bf16 v[14:17], v[78:81], v[190:193], v[14:17]
	v_mfma_f32_16x16x32_bf16 v[10:13], v[98:101], v[190:193], v[10:13]
	s_addc_u32 s19, s19, 0
	v_mfma_f32_16x16x32_bf16 v[54:57], v[106:109], v[150:153], v[54:57]
	v_mfma_f32_16x16x32_bf16 v[50:53], v[130:133], v[150:153], v[50:53]
	s_add_u32 s51, s51, 0x100
	v_mfma_f32_16x16x32_bf16 v[38:41], v[106:109], v[158:161], v[38:41]
	v_mfma_f32_16x16x32_bf16 v[34:37], v[130:133], v[158:161], v[34:37]
	s_addc_u32 s54, s54, 0
	v_mfma_f32_16x16x32_bf16 v[22:25], v[106:109], v[170:173], v[22:25]
	v_mfma_f32_16x16x32_bf16 v[18:21], v[130:133], v[170:173], v[18:21]
	s_cmp_ge_u32 s55, s53
	v_mfma_f32_16x16x32_bf16 v[6:9], v[106:109], v[178:181], v[6:9]
	v_mfma_f32_16x16x32_bf16 v[2:5], v[130:133], v[178:181], v[2:5]
	s_mov_b32 s20, s55
	v_mfma_f32_16x16x32_bf16 v[54:57], v[118:121], v[154:157], v[54:57]
	v_mfma_f32_16x16x32_bf16 v[50:53], v[142:145], v[154:157], v[50:53]
	v_mfma_f32_16x16x32_bf16 v[38:41], v[118:121], v[162:165], v[38:41]
	v_mfma_f32_16x16x32_bf16 v[34:37], v[142:145], v[162:165], v[34:37]
	v_mfma_f32_16x16x32_bf16 v[22:25], v[118:121], v[174:177], v[22:25]
	v_mfma_f32_16x16x32_bf16 v[18:21], v[142:145], v[174:177], v[18:21]
	v_mfma_f32_16x16x32_bf16 v[6:9], v[118:121], v[190:193], v[6:9]
	v_mfma_f32_16x16x32_bf16 v[2:5], v[142:145], v[190:193], v[2:5]
	s_setprio 0
	s_barrier
	s_cbranch_scc0 .LBB0_850
	s_and_b64 vcc, exec, s[14:15]
	s_cbranch_vccz .LBB0_853
	s_barrier

.LBB0_864:
	v_lshl_add_u64 v[4:5], s[26:27], 0, v[194:195]
	v_mov_b32_e32 v209, v195
	v_lshl_add_u64 v[14:15], s[26:27], 0, v[208:209]
	v_mov_b32_e32 v205, v195
	s_add_i32 m0, s37, 0x18000
	v_lshl_add_u64 v[4:5], v[4:5], 0, s[94:95]
	v_lshl_add_u64 v[20:21], s[20:21], 0, v[204:205]
	v_mov_b32_e32 v207, v195
	s_waitcnt vmcnt(2)
	s_barrier
	global_load_lds_dwordx4 v[4:5], off
	v_lshl_add_u64 v[4:5], v[14:15], 0, s[94:95]
	s_add_i32 m0, s37, 0x1a000
	s_add_i32 s51, s37, 0x8000
	v_lshl_add_u64 v[22:23], s[20:21], 0, v[206:207]
	global_load_lds_dwordx4 v[4:5], off
	v_lshl_add_u64 v[4:5], v[20:21], 0, s[94:95]
	s_mov_b32 m0, s51
	s_add_i32 s53, s37, 0xa000
	v_lshl_add_u64 v[16:17], s[2:3], 0, v[194:195]
	global_load_lds_dwordx4 v[4:5], off
	v_lshl_add_u64 v[4:5], v[22:23], 0, s[94:95]
	s_mov_b32 m0, s53
	v_lshl_add_u64 v[18:19], s[2:3], 0, v[208:209]
	global_load_lds_dwordx4 v[4:5], off
	s_add_i32 m0, s37, 0x1c000
	v_lshl_add_u64 v[4:5], v[16:17], 0, s[94:95]
	global_load_lds_dwordx4 v[4:5], off
	v_lshl_add_u64 v[4:5], v[18:19], 0, s[94:95]
	s_add_i32 m0, s37, 0x1e000
	v_bfe_u32 v14, v6, 4, 2
	global_load_lds_dwordx4 v[4:5], off
	v_and_b32_e32 v13, 15, v6
	v_lshlrev_b32_e32 v15, 4, v14
	v_lshlrev_b32_e32 v6, 2, v6
	v_lshl_or_b32 v234, s4, 6, v13
	v_lshl_or_b32 v13, v13, 6, v15
	s_lshl_b32 s2, s4, 13
	v_and_b32_e32 v6, 32, v6
	v_bitop3_b32 v15, v13, s2, v6 bitop3:0xde
	s_lshl_b32 s2, s5, 5
	s_and_b32 s4, s2, 0x60
	s_lshl_b32 s2, s4, 7
	v_bitop3_b32 v235, v13, s2, v6 bitop3:0xde
	v_add_u32_e32 v235, 0x10000, v235
	v_add_u32_e32 v6, v9, v7
	v_add_lshl_u32 v6, v6, v8, 1
	v_mov_b32_e32 v7, v195
	s_waitcnt vmcnt(6)
	v_lshl_add_u64 v[210:211], s[12:13], 0, v[6:7]
	v_add_u32_e32 v6, v12, v10
	s_cmpk_lt_u32 s14, 0x100
	v_add_lshl_u32 v6, v6, v11, 1
	v_mov_b32_e32 v3, v2
	v_mov_b32_e32 v4, v2
	v_mov_b32_e32 v5, v2
	s_cselect_b64 s[14:15], -1, 0
	s_mov_b32 s54, 0
	v_cmp_eq_u32_e64 s[2:3], 0, v14
	s_ashr_i32 s55, s40, 31
	s_lshr_b32 s52, s52, 7
	v_lshl_or_b32 v236, v14, 3, s4
	v_lshl_add_u64 v[212:213], s[12:13], 0, v[6:7]
	v_add_u32_e32 v237, 0, v15
	s_mov_b32 s59, s25
	s_barrier
	s_branch .LBB0_867

.LBB0_875:
	s_sub_u32 vcc_lo, s20, s12
	s_subb_u32 vcc_hi, s21, 0
	v_lshl_add_u64 v[198:199], vcc, 0, v[210:211]
	s_mov_b32 m0, s51
	s_nop 0
	global_load_lds_dwordx4 v[198:199], off
	v_lshl_add_u64 v[198:199], vcc, 0, v[212:213]
	s_mov_b32 m0, s53
	s_nop 0
	global_load_lds_dwordx4 v[198:199], off
	ds_read_b128 v[130:133], v235
	ds_read_b128 v[134:137], v235 offset:1024
	ds_read_b128 v[138:141], v235 offset:2048
	ds_read_b128 v[142:145], v235 offset:3072
	ds_read_b128 v[146:149], v235 offset:16384
	ds_read_b128 v[150:153], v235 offset:17408
	ds_read_b128 v[154:157], v235 offset:18432
	ds_read_b128 v[158:161], v235 offset:19456
	ds_read_b128 v[162:165], v237
	ds_read_b128 v[166:169], v237 offset:1024
	ds_read_b128 v[170:173], v237 offset:2048
	ds_read_b128 v[174:177], v237 offset:3072
	ds_read_b128 v[178:181], v237 offset:4096
	ds_read_b128 v[182:185], v237 offset:5120
	ds_read_b128 v[186:189], v237 offset:6144
	ds_read_b128 v[190:193], v237 offset:7168
	s_add_i32 s29, s26, 2
	s_add_u32 s62, s20, 0x80
	s_addc_u32 s27, s21, 0
	s_add_i32 s64, 0, 0x10000
	s_cmp_eq_u32 s17, s26
	s_cselect_b32 s27, s7, s27
	s_cselect_b32 s26, s6, s62
	s_cselect_b32 s63, s19, s28
	s_cselect_b32 s62, s18, s23
	s_add_i32 s65, 0, 0x14000
	v_lshl_add_u64 v[198:199], s[20:21], 0, v[210:211]
	s_add_i32 m0, s37, 0xc000
	s_nop 0
	global_load_lds_dwordx4 v[198:199], off
	v_lshl_add_u64 v[198:199], s[20:21], 0, v[212:213]
	s_add_i32 m0, s37, 0xe000
	s_nop 0
	global_load_lds_dwordx4 v[198:199], off
	s_waitcnt vmcnt(8)
	s_waitcnt lgkmcnt(0)
	v_mfma_f32_16x16x32_bf16 v[126:129], v[130:133], v[162:165], v[126:129]
	v_mfma_f32_16x16x32_bf16 v[122:125], v[138:141], v[162:165], v[122:125]
	s_barrier
	s_setprio 1
	v_mfma_f32_16x16x32_bf16 v[110:113], v[130:133], v[170:173], v[110:113]
	v_mfma_f32_16x16x32_bf16 v[106:109], v[138:141], v[170:173], v[106:109]
	v_mfma_f32_16x16x32_bf16 v[94:97], v[130:133], v[178:181], v[94:97]
	v_mfma_f32_16x16x32_bf16 v[90:93], v[138:141], v[178:181], v[90:93]
	v_mfma_f32_16x16x32_bf16 v[78:81], v[130:133], v[186:189], v[78:81]
	v_mfma_f32_16x16x32_bf16 v[74:77], v[138:141], v[186:189], v[74:77]
	v_mfma_f32_16x16x32_bf16 v[126:129], v[134:137], v[166:169], v[126:129]
	v_mfma_f32_16x16x32_bf16 v[122:125], v[142:145], v[166:169], v[122:125]
	v_mfma_f32_16x16x32_bf16 v[110:113], v[134:137], v[174:177], v[110:113]
	v_mfma_f32_16x16x32_bf16 v[106:109], v[142:145], v[174:177], v[106:109]
	v_mfma_f32_16x16x32_bf16 v[94:97], v[134:137], v[182:185], v[94:97]
	v_mfma_f32_16x16x32_bf16 v[90:93], v[142:145], v[182:185], v[90:93]
	v_mfma_f32_16x16x32_bf16 v[78:81], v[134:137], v[190:193], v[78:81]
	v_mfma_f32_16x16x32_bf16 v[74:77], v[142:145], v[190:193], v[74:77]
	v_mfma_f32_16x16x32_bf16 v[118:121], v[146:149], v[162:165], v[118:121]
	v_mfma_f32_16x16x32_bf16 v[114:117], v[154:157], v[162:165], v[114:117]
	v_mfma_f32_16x16x32_bf16 v[102:105], v[146:149], v[170:173], v[102:105]
	v_mfma_f32_16x16x32_bf16 v[98:101], v[154:157], v[170:173], v[98:101]
	v_mfma_f32_16x16x32_bf16 v[86:89], v[146:149], v[178:181], v[86:89]
	v_mfma_f32_16x16x32_bf16 v[82:85], v[154:157], v[178:181], v[82:85]
	v_mfma_f32_16x16x32_bf16 v[70:73], v[146:149], v[186:189], v[70:73]
	v_mfma_f32_16x16x32_bf16 v[66:69], v[154:157], v[186:189], v[66:69]
	v_mfma_f32_16x16x32_bf16 v[118:121], v[150:153], v[166:169], v[118:121]
	v_mfma_f32_16x16x32_bf16 v[114:117], v[158:161], v[166:169], v[114:117]
	v_mfma_f32_16x16x32_bf16 v[102:105], v[150:153], v[174:177], v[102:105]
	v_mfma_f32_16x16x32_bf16 v[98:101], v[158:161], v[174:177], v[98:101]
	v_mfma_f32_16x16x32_bf16 v[86:89], v[150:153], v[182:185], v[86:89]
	v_mfma_f32_16x16x32_bf16 v[82:85], v[158:161], v[182:185], v[82:85]
	v_mfma_f32_16x16x32_bf16 v[70:73], v[150:153], v[190:193], v[70:73]
	v_mfma_f32_16x16x32_bf16 v[66:69], v[158:161], v[190:193], v[66:69]
	s_setprio 0
	s_barrier
	ds_read_b128 v[162:165], v237 offset:16384
	ds_read_b128 v[166:169], v237 offset:17408
	ds_read_b128 v[170:173], v237 offset:18432
	ds_read_b128 v[174:177], v237 offset:19456
	ds_read_b128 v[178:181], v237 offset:20480
	ds_read_b128 v[182:185], v237 offset:21504
	ds_read_b128 v[186:189], v237 offset:22528
	ds_read_b128 v[190:193], v237 offset:23552
	s_add_i32 s64, s64, s36
	v_lshl_add_u64 v[198:199], s[62:63], 0, v[194:195]
	s_mov_b32 m0, s64
	s_nop 0
	global_load_lds_dwordx4 v[198:199], off
	s_add_i32 m0, s64, 0x2000
	v_lshl_add_u64 v[214:215], s[62:63], 0, v[208:209]
	s_add_u32 s62, s62, s12
	s_addc_u32 s63, s63, 0
	s_add_i32 s64, s65, s36
	global_load_lds_dwordx4 v[214:215], off
	v_lshl_add_u64 v[216:217], s[62:63], 0, v[194:195]
	s_mov_b32 m0, s64
	v_lshl_add_u64 v[218:219], s[62:63], 0, v[208:209]
	global_load_lds_dwordx4 v[216:217], off
	s_add_i32 m0, s64, 0x2000
	v_lshl_add_u64 v[220:221], s[26:27], 0, v[204:205]
	global_load_lds_dwordx4 v[218:219], off
	v_lshl_add_u64 v[222:223], s[26:27], 0, v[206:207]
	s_waitcnt vmcnt(6)
	s_waitcnt lgkmcnt(0)
	v_mfma_f32_16x16x32_bf16 v[62:65], v[130:133], v[162:165], v[62:65]
	v_mfma_f32_16x16x32_bf16 v[58:61], v[138:141], v[162:165], v[58:61]
	s_barrier
	s_setprio 1
	v_mfma_f32_16x16x32_bf16 v[46:49], v[130:133], v[170:173], v[46:49]
	v_mfma_f32_16x16x32_bf16 v[42:45], v[138:141], v[170:173], v[42:45]
	v_mfma_f32_16x16x32_bf16 v[30:33], v[130:133], v[178:181], v[30:33]
	v_mfma_f32_16x16x32_bf16 v[26:29], v[138:141], v[178:181], v[26:29]
	v_mfma_f32_16x16x32_bf16 v[14:17], v[130:133], v[186:189], v[14:17]
	v_mfma_f32_16x16x32_bf16 v[10:13], v[138:141], v[186:189], v[10:13]
	v_mfma_f32_16x16x32_bf16 v[62:65], v[134:137], v[166:169], v[62:65]
	v_mfma_f32_16x16x32_bf16 v[58:61], v[142:145], v[166:169], v[58:61]
	v_mfma_f32_16x16x32_bf16 v[46:49], v[134:137], v[174:177], v[46:49]
	v_mfma_f32_16x16x32_bf16 v[42:45], v[142:145], v[174:177], v[42:45]
	v_mfma_f32_16x16x32_bf16 v[30:33], v[134:137], v[182:185], v[30:33]
	v_mfma_f32_16x16x32_bf16 v[26:29], v[142:145], v[182:185], v[26:29]
	v_mfma_f32_16x16x32_bf16 v[14:17], v[134:137], v[190:193], v[14:17]
	v_mfma_f32_16x16x32_bf16 v[10:13], v[142:145], v[190:193], v[10:13]
	v_mfma_f32_16x16x32_bf16 v[54:57], v[146:149], v[162:165], v[54:57]
	v_mfma_f32_16x16x32_bf16 v[50:53], v[154:157], v[162:165], v[50:53]
	v_mfma_f32_16x16x32_bf16 v[38:41], v[146:149], v[170:173], v[38:41]
	v_mfma_f32_16x16x32_bf16 v[34:37], v[154:157], v[170:173], v[34:37]
	v_mfma_f32_16x16x32_bf16 v[22:25], v[146:149], v[178:181], v[22:25]
	v_mfma_f32_16x16x32_bf16 v[18:21], v[154:157], v[178:181], v[18:21]
	v_mfma_f32_16x16x32_bf16 v[6:9], v[146:149], v[186:189], v[6:9]
	v_mfma_f32_16x16x32_bf16 v[2:5], v[154:157], v[186:189], v[2:5]
	v_mfma_f32_16x16x32_bf16 v[54:57], v[150:153], v[166:169], v[54:57]
	v_mfma_f32_16x16x32_bf16 v[50:53], v[158:161], v[166:169], v[50:53]
	v_mfma_f32_16x16x32_bf16 v[38:41], v[150:153], v[174:177], v[38:41]
	v_mfma_f32_16x16x32_bf16 v[34:37], v[158:161], v[174:177], v[34:37]
	v_mfma_f32_16x16x32_bf16 v[22:25], v[150:153], v[182:185], v[22:25]
	v_mfma_f32_16x16x32_bf16 v[18:21], v[158:161], v[182:185], v[18:21]
	v_mfma_f32_16x16x32_bf16 v[6:9], v[150:153], v[190:193], v[6:9]
	v_mfma_f32_16x16x32_bf16 v[2:5], v[158:161], v[190:193], v[2:5]
	s_setprio 0
	s_barrier
	s_mov_b32 m0, s37
	s_nop 0
	global_load_lds_dwordx4 v[220:221], off
	s_mov_b32 m0, s38
	s_nop 0
	global_load_lds_dwordx4 v[222:223], off
	ds_read_b128 v[130:133], v235 offset:32768
	ds_read_b128 v[134:137], v235 offset:33792
	ds_read_b128 v[138:141], v235 offset:34816
	ds_read_b128 v[142:145], v235 offset:35840
	ds_read_b128 v[146:149], v235 offset:49152
	ds_read_b128 v[150:153], v235 offset:50176
	ds_read_b128 v[154:157], v235 offset:51200
	ds_read_b128 v[158:161], v235 offset:52224
	ds_read_b128 v[162:165], v237 offset:32768
	ds_read_b128 v[166:169], v237 offset:33792
	ds_read_b128 v[170:173], v237 offset:34816
	ds_read_b128 v[174:177], v237 offset:35840
	ds_read_b128 v[178:181], v237 offset:36864
	ds_read_b128 v[182:185], v237 offset:37888
	ds_read_b128 v[186:189], v237 offset:38912
	ds_read_b128 v[190:193], v237 offset:39936
	s_add_i32 s62, 0, 0x18000
	s_add_i32 s63, 0, 0x1c000
	s_add_u32 s26, s26, s12
	s_addc_u32 s27, s27, 0
	s_mov_b32 m0, s39
	v_lshl_add_u64 v[224:225], s[26:27], 0, v[204:205]
	global_load_lds_dwordx4 v[224:225], off
	v_lshl_add_u64 v[224:225], s[26:27], 0, v[206:207]
	s_mov_b32 m0, s50
	s_nop 0
	global_load_lds_dwordx4 v[224:225], off
	s_waitcnt vmcnt(8)
	s_waitcnt lgkmcnt(0)
	v_mfma_f32_16x16x32_bf16 v[126:129], v[130:133], v[162:165], v[126:129]
	v_mfma_f32_16x16x32_bf16 v[122:125], v[138:141], v[162:165], v[122:125]
	s_barrier
	s_setprio 1
	v_mfma_f32_16x16x32_bf16 v[110:113], v[130:133], v[170:173], v[110:113]
	v_mfma_f32_16x16x32_bf16 v[106:109], v[138:141], v[170:173], v[106:109]
	v_mfma_f32_16x16x32_bf16 v[94:97], v[130:133], v[178:181], v[94:97]
	v_mfma_f32_16x16x32_bf16 v[90:93], v[138:141], v[178:181], v[90:93]
	v_mfma_f32_16x16x32_bf16 v[78:81], v[130:133], v[186:189], v[78:81]
	v_mfma_f32_16x16x32_bf16 v[74:77], v[138:141], v[186:189], v[74:77]
	v_mfma_f32_16x16x32_bf16 v[126:129], v[134:137], v[166:169], v[126:129]
	v_mfma_f32_16x16x32_bf16 v[122:125], v[142:145], v[166:169], v[122:125]
	v_mfma_f32_16x16x32_bf16 v[110:113], v[134:137], v[174:177], v[110:113]
	v_mfma_f32_16x16x32_bf16 v[106:109], v[142:145], v[174:177], v[106:109]
	v_mfma_f32_16x16x32_bf16 v[94:97], v[134:137], v[182:185], v[94:97]
	v_mfma_f32_16x16x32_bf16 v[90:93], v[142:145], v[182:185], v[90:93]
	v_mfma_f32_16x16x32_bf16 v[78:81], v[134:137], v[190:193], v[78:81]
	v_mfma_f32_16x16x32_bf16 v[74:77], v[142:145], v[190:193], v[74:77]
	v_mfma_f32_16x16x32_bf16 v[118:121], v[146:149], v[162:165], v[118:121]
	v_mfma_f32_16x16x32_bf16 v[114:117], v[154:157], v[162:165], v[114:117]
	v_mfma_f32_16x16x32_bf16 v[102:105], v[146:149], v[170:173], v[102:105]
	v_mfma_f32_16x16x32_bf16 v[98:101], v[154:157], v[170:173], v[98:101]
	v_mfma_f32_16x16x32_bf16 v[86:89], v[146:149], v[178:181], v[86:89]
	v_mfma_f32_16x16x32_bf16 v[82:85], v[154:157], v[178:181], v[82:85]
	v_mfma_f32_16x16x32_bf16 v[70:73], v[146:149], v[186:189], v[70:73]
	v_mfma_f32_16x16x32_bf16 v[66:69], v[154:157], v[186:189], v[66:69]
	v_mfma_f32_16x16x32_bf16 v[118:121], v[150:153], v[166:169], v[118:121]
	v_mfma_f32_16x16x32_bf16 v[114:117], v[158:161], v[166:169], v[114:117]
	v_mfma_f32_16x16x32_bf16 v[102:105], v[150:153], v[174:177], v[102:105]
	v_mfma_f32_16x16x32_bf16 v[98:101], v[158:161], v[174:177], v[98:101]
	v_mfma_f32_16x16x32_bf16 v[86:89], v[150:153], v[182:185], v[86:89]
	v_mfma_f32_16x16x32_bf16 v[82:85], v[158:161], v[182:185], v[82:85]
	v_mfma_f32_16x16x32_bf16 v[70:73], v[150:153], v[190:193], v[70:73]
	v_mfma_f32_16x16x32_bf16 v[66:69], v[158:161], v[190:193], v[66:69]
	s_setprio 0
	s_barrier
	ds_read_b128 v[162:165], v237 offset:49152
	ds_read_b128 v[166:169], v237 offset:50176
	ds_read_b128 v[170:173], v237 offset:51200
	ds_read_b128 v[174:177], v237 offset:52224
	ds_read_b128 v[178:181], v237 offset:53248
	ds_read_b128 v[182:185], v237 offset:54272
	ds_read_b128 v[186:189], v237 offset:55296
	ds_read_b128 v[190:193], v237 offset:56320
	s_add_i32 s26, s62, s36
	v_lshl_add_u64 v[198:199], v[198:199], 0, s[94:95]
	s_mov_b32 m0, s26
	s_nop 0
	global_load_lds_dwordx4 v[198:199], off
	v_lshl_add_u64 v[198:199], v[214:215], 0, s[94:95]
	s_add_i32 m0, s26, 0x2000
	s_add_i32 s26, s63, s36
	global_load_lds_dwordx4 v[198:199], off
	v_lshl_add_u64 v[198:199], v[216:217], 0, s[94:95]
	s_mov_b32 m0, s26
	s_nop 0
	global_load_lds_dwordx4 v[198:199], off
	v_lshl_add_u64 v[198:199], v[218:219], 0, s[94:95]
	s_add_i32 m0, s26, 0x2000
	s_nop 0
	global_load_lds_dwordx4 v[198:199], off
	s_waitcnt vmcnt(6)
	s_waitcnt lgkmcnt(0)
	v_mfma_f32_16x16x32_bf16 v[62:65], v[130:133], v[162:165], v[62:65]
	v_mfma_f32_16x16x32_bf16 v[58:61], v[138:141], v[162:165], v[58:61]
	s_barrier
	s_setprio 1
	v_mfma_f32_16x16x32_bf16 v[46:49], v[130:133], v[170:173], v[46:49]
	v_mfma_f32_16x16x32_bf16 v[42:45], v[138:141], v[170:173], v[42:45]
	v_mfma_f32_16x16x32_bf16 v[30:33], v[130:133], v[178:181], v[30:33]
	v_mfma_f32_16x16x32_bf16 v[26:29], v[138:141], v[178:181], v[26:29]
	v_mfma_f32_16x16x32_bf16 v[14:17], v[130:133], v[186:189], v[14:17]
	v_mfma_f32_16x16x32_bf16 v[10:13], v[138:141], v[186:189], v[10:13]
	v_mfma_f32_16x16x32_bf16 v[62:65], v[134:137], v[166:169], v[62:65]
	v_mfma_f32_16x16x32_bf16 v[58:61], v[142:145], v[166:169], v[58:61]
	v_mfma_f32_16x16x32_bf16 v[46:49], v[134:137], v[174:177], v[46:49]
	v_mfma_f32_16x16x32_bf16 v[42:45], v[142:145], v[174:177], v[42:45]
	v_mfma_f32_16x16x32_bf16 v[30:33], v[134:137], v[182:185], v[30:33]
	v_mfma_f32_16x16x32_bf16 v[26:29], v[142:145], v[182:185], v[26:29]
	s_add_u32 s20, s20, 0x100
	v_mfma_f32_16x16x32_bf16 v[14:17], v[134:137], v[190:193], v[14:17]
	v_mfma_f32_16x16x32_bf16 v[10:13], v[142:145], v[190:193], v[10:13]
	s_addc_u32 s21, s21, 0
	v_mfma_f32_16x16x32_bf16 v[54:57], v[146:149], v[162:165], v[54:57]
	v_mfma_f32_16x16x32_bf16 v[50:53], v[154:157], v[162:165], v[50:53]
	s_add_u32 s23, s23, 0x100
	v_mfma_f32_16x16x32_bf16 v[38:41], v[146:149], v[170:173], v[38:41]
	v_mfma_f32_16x16x32_bf16 v[34:37], v[154:157], v[170:173], v[34:37]
	s_addc_u32 s28, s28, 0
	v_mfma_f32_16x16x32_bf16 v[22:25], v[146:149], v[178:181], v[22:25]
	v_mfma_f32_16x16x32_bf16 v[18:21], v[154:157], v[178:181], v[18:21]
	s_cmp_ge_i32 s29, s25
	v_mfma_f32_16x16x32_bf16 v[6:9], v[146:149], v[186:189], v[6:9]
	v_mfma_f32_16x16x32_bf16 v[2:5], v[154:157], v[186:189], v[2:5]
	s_mov_b32 s26, s29
	v_mfma_f32_16x16x32_bf16 v[54:57], v[150:153], v[166:169], v[54:57]
	v_mfma_f32_16x16x32_bf16 v[50:53], v[158:161], v[166:169], v[50:53]
	v_mfma_f32_16x16x32_bf16 v[38:41], v[150:153], v[174:177], v[38:41]
	v_mfma_f32_16x16x32_bf16 v[34:37], v[158:161], v[174:177], v[34:37]
	v_mfma_f32_16x16x32_bf16 v[22:25], v[150:153], v[182:185], v[22:25]
	v_mfma_f32_16x16x32_bf16 v[18:21], v[158:161], v[182:185], v[18:21]
	v_mfma_f32_16x16x32_bf16 v[6:9], v[150:153], v[190:193], v[6:9]
	v_mfma_f32_16x16x32_bf16 v[2:5], v[158:161], v[190:193], v[2:5]
	s_setprio 0
	s_barrier
	s_cbranch_scc0 .LBB0_875
	v_readlane_b32 s64, v254, 51
	v_readlane_b32 s65, v254, 52
	s_branch .LBB0_878

.LBB0_961:
	v_readlane_b32 s52, v253, 12
	s_mul_i32 s9, s24, 0x2c0000
	v_readlane_b32 s62, v253, 22
	s_mul_hi_u32 s5, s24, 0x2c0000
	s_mov_b32 s26, s24
	v_readlane_b32 s63, v253, 23
	s_add_u32 s24, s62, s9
	v_readlane_b32 s55, v253, 15
	s_addc_u32 s25, s63, s5
	s_mul_i32 s11, s26, 0x58000
	v_readlane_b32 s13, v254, 26
	v_readlane_b32 s56, v253, 16
	s_mul_hi_u32 s10, s26, 0x58000
	s_add_u32 s55, s13, s11
	v_readlane_b32 s11, v254, 27
	v_readlane_b32 s57, v253, 17
	s_addc_u32 s56, s11, s10
	v_readlane_b32 s10, v254, 28
	v_readlane_b32 s58, v253, 18
	s_add_u32 s57, s10, s9
	v_readlane_b32 s9, v254, 29
	v_readlane_b32 s59, v253, 19
	v_readlane_b32 s60, v253, 20
	s_addc_u32 s58, s9, s5
	s_lshl_b32 s4, s4, 12
	s_add_i32 m0, s49, 0x18000
	v_lshl_add_u64 v[10:11], v[10:11], 0, s[94:95]
	s_lshl_b32 s3, s3, 13
	s_and_b32 s9, s4, 0x3000
	s_waitcnt vmcnt(2)
	s_barrier
	global_load_lds_dwordx4 v[10:11], off
	v_lshl_add_u64 v[8:9], v[8:9], 0, s[94:95]
	s_add_i32 m0, s49, 0x1a000
	s_add_i32 s59, s49, 0x8000
	s_add_i32 s60, s49, 0xa000
	global_load_lds_dwordx4 v[8:9], off
	v_lshl_add_u64 v[4:5], v[4:5], 0, s[94:95]
	s_mov_b32 m0, s59
	s_add_u32 s4, s6, 0x80080
	global_load_lds_dwordx4 v[4:5], off
	v_lshl_add_u64 v[4:5], v[6:7], 0, s[94:95]
	s_mov_b32 m0, s60
	s_addc_u32 s5, s7, 0
	global_load_lds_dwordx4 v[4:5], off
	s_add_i32 m0, s49, 0x1c000
	v_lshl_add_u64 v[4:5], s[4:5], 0, v[140:141]
	global_load_lds_dwordx4 v[4:5], off
	v_lshl_add_u64 v[4:5], s[4:5], 0, v[144:145]
	s_add_i32 m0, s49, 0x1e000
	v_and_b32_e32 v6, 15, v12
	global_load_lds_dwordx4 v[4:5], off
	v_lshlrev_b32_e32 v9, 2, v12
	v_and_b32_e32 v7, 48, v12
	v_lshlrev_b32_e32 v6, 6, v6
	v_and_b32_e32 v9, 32, v9
	v_or_b32_e32 v8, v6, v7
	v_bitop3_b32 v6, v6, v9, v7 bitop3:0x36
	v_or_b32_e32 v246, s9, v6
	v_add_u32_e32 v246, 0x10000, v246
	v_and_b32_e32 v6, 1, v13
	v_bitop3_b32 v7, v8, s3, v9 bitop3:0xde
	v_lshlrev_b32_e32 v6, 6, v6
	v_lshlrev_b32_e32 v8, 1, v14
	v_add3_u32 v194, v15, v6, v8
	v_and_b32_e32 v6, 1, v16
	v_readlane_b32 s64, v253, 24
	v_readlane_b32 s65, v253, 25
	s_waitcnt vmcnt(6)
	s_cmpk_lt_u32 s2, 0x100
	s_mov_b64 s[2:3], 0x4080
	v_lshlrev_b32_e32 v6, 6, v6
	v_lshlrev_b32_e32 v8, 1, v17
	v_lshl_add_u64 v[146:147], v[194:195], 0, s[2:3]
	v_add3_u32 v194, v18, v6, v8
	v_readlane_b32 s64, v254, 51
	v_mov_b32_e32 v3, v2
	v_mov_b32_e32 v4, v2
	v_mov_b32_e32 v5, v2
	s_cselect_b64 s[26:27], -1, 0
	v_lshl_add_u64 v[148:149], v[194:195], 0, s[2:3]
	s_mov_b32 s9, 0
	v_add_u32_e32 v247, 0, v7
	v_readlane_b32 s65, v254, 52
	v_readlane_b32 s63, v254, 55
	s_mov_b32 s52, 0x803f
	v_readlane_b32 s53, v253, 13
	v_readlane_b32 s54, v253, 14
	v_readlane_b32 s61, v253, 21
	v_readlane_b32 s66, v253, 26
	v_readlane_b32 s67, v253, 27
	s_barrier
	s_branch .LBB0_964

.LBB0_973:
	s_add_u32 vcc_lo, s0, 0xffffc000
	s_addc_u32 vcc_hi, s1, -1
	v_lshl_add_u64 v[198:199], vcc, 0, v[146:147]
	s_mov_b32 m0, s59
	s_nop 0
	global_load_lds_dwordx4 v[198:199], off
	v_lshl_add_u64 v[198:199], vcc, 0, v[148:149]
	s_mov_b32 m0, s60
	s_nop 0
	global_load_lds_dwordx4 v[198:199], off
	ds_read_b128 v[130:133], v246
	ds_read_b128 v[134:137], v246 offset:1024
	ds_read_b128 v[150:153], v246 offset:2048
	ds_read_b128 v[154:157], v246 offset:3072
	ds_read_b128 v[158:161], v246 offset:16384
	ds_read_b128 v[162:165], v246 offset:17408
	ds_read_b128 v[166:169], v246 offset:18432
	ds_read_b128 v[170:173], v246 offset:19456
	ds_read_b128 v[174:177], v247
	ds_read_b128 v[178:181], v247 offset:1024
	ds_read_b128 v[182:185], v247 offset:2048
	ds_read_b128 v[186:189], v247 offset:3072
	ds_read_b128 v[190:193], v247 offset:4096
	ds_read_b128 v[204:207], v247 offset:5120
	ds_read_b128 v[208:211], v247 offset:6144
	ds_read_b128 v[212:215], v247 offset:7168
	s_add_u32 s4, s0, 0x100
	s_addc_u32 s5, s1, 0
	s_add_i32 s40, 0, 0x10000
	s_cmp_eq_u32 s39, 28
	s_cselect_b32 s11, s35, s5
	s_cselect_b32 s10, s34, s4
	s_cselect_b32 s7, s13, s38
	s_cselect_b32 s6, s29, s33
	s_add_i32 s41, 0, 0x14000
	v_lshl_add_u64 v[198:199], s[0:1], 0, v[146:147]
	s_add_i32 m0, s49, 0xc000
	s_nop 0
	global_load_lds_dwordx4 v[198:199], off
	v_lshl_add_u64 v[198:199], s[0:1], 0, v[148:149]
	s_add_i32 m0, s49, 0xe000
	s_nop 0
	global_load_lds_dwordx4 v[198:199], off
	s_waitcnt vmcnt(8)
	s_waitcnt lgkmcnt(0)
	v_mfma_f32_16x16x32_bf16 v[126:129], v[130:133], v[174:177], v[126:129]
	v_mfma_f32_16x16x32_bf16 v[62:65], v[150:153], v[174:177], v[62:65]
	s_barrier
	s_setprio 1
	v_mfma_f32_16x16x32_bf16 v[122:125], v[130:133], v[182:185], v[122:125]
	v_mfma_f32_16x16x32_bf16 v[58:61], v[150:153], v[182:185], v[58:61]
	v_mfma_f32_16x16x32_bf16 v[114:117], v[130:133], v[190:193], v[114:117]
	v_mfma_f32_16x16x32_bf16 v[50:53], v[150:153], v[190:193], v[50:53]
	v_mfma_f32_16x16x32_bf16 v[106:109], v[130:133], v[208:211], v[106:109]
	v_mfma_f32_16x16x32_bf16 v[42:45], v[150:153], v[208:211], v[42:45]
	v_mfma_f32_16x16x32_bf16 v[126:129], v[134:137], v[178:181], v[126:129]
	v_mfma_f32_16x16x32_bf16 v[62:65], v[154:157], v[178:181], v[62:65]
	v_mfma_f32_16x16x32_bf16 v[122:125], v[134:137], v[186:189], v[122:125]
	v_mfma_f32_16x16x32_bf16 v[58:61], v[154:157], v[186:189], v[58:61]
	v_mfma_f32_16x16x32_bf16 v[114:117], v[134:137], v[204:207], v[114:117]
	v_mfma_f32_16x16x32_bf16 v[50:53], v[154:157], v[204:207], v[50:53]
	v_mfma_f32_16x16x32_bf16 v[106:109], v[134:137], v[212:215], v[106:109]
	v_mfma_f32_16x16x32_bf16 v[42:45], v[154:157], v[212:215], v[42:45]
	v_mfma_f32_16x16x32_bf16 v[118:121], v[158:161], v[174:177], v[118:121]
	v_mfma_f32_16x16x32_bf16 v[54:57], v[166:169], v[174:177], v[54:57]
	v_mfma_f32_16x16x32_bf16 v[110:113], v[158:161], v[182:185], v[110:113]
	v_mfma_f32_16x16x32_bf16 v[46:49], v[166:169], v[182:185], v[46:49]
	v_mfma_f32_16x16x32_bf16 v[102:105], v[158:161], v[190:193], v[102:105]
	v_mfma_f32_16x16x32_bf16 v[38:41], v[166:169], v[190:193], v[38:41]
	v_mfma_f32_16x16x32_bf16 v[98:101], v[158:161], v[208:211], v[98:101]
	v_mfma_f32_16x16x32_bf16 v[34:37], v[166:169], v[208:211], v[34:37]
	v_mfma_f32_16x16x32_bf16 v[118:121], v[162:165], v[178:181], v[118:121]
	v_mfma_f32_16x16x32_bf16 v[54:57], v[170:173], v[178:181], v[54:57]
	v_mfma_f32_16x16x32_bf16 v[110:113], v[162:165], v[186:189], v[110:113]
	v_mfma_f32_16x16x32_bf16 v[46:49], v[170:173], v[186:189], v[46:49]
	v_mfma_f32_16x16x32_bf16 v[102:105], v[162:165], v[204:207], v[102:105]
	v_mfma_f32_16x16x32_bf16 v[38:41], v[170:173], v[204:207], v[38:41]
	v_mfma_f32_16x16x32_bf16 v[98:101], v[162:165], v[212:215], v[98:101]
	v_mfma_f32_16x16x32_bf16 v[34:37], v[170:173], v[212:215], v[34:37]
	s_setprio 0
	s_barrier
	ds_read_b128 v[174:177], v247 offset:16384
	ds_read_b128 v[178:181], v247 offset:17408
	ds_read_b128 v[182:185], v247 offset:18432
	ds_read_b128 v[186:189], v247 offset:19456
	ds_read_b128 v[190:193], v247 offset:20480
	ds_read_b128 v[204:207], v247 offset:21504
	ds_read_b128 v[208:211], v247 offset:22528
	ds_read_b128 v[212:215], v247 offset:23552
	s_add_i32 s0, s40, s48
	v_lshl_add_u64 v[198:199], s[6:7], 0, v[140:141]
	s_mov_b32 m0, s0
	s_nop 0
	global_load_lds_dwordx4 v[198:199], off
	s_add_i32 m0, s0, 0x2000
	s_add_u32 s0, s6, 0x80000
	v_lshl_add_u64 v[200:201], s[6:7], 0, v[144:145]
	s_addc_u32 s1, s7, 0
	s_add_i32 s40, s41, s48
	global_load_lds_dwordx4 v[200:201], off
	v_lshl_add_u64 v[216:217], s[0:1], 0, v[140:141]
	s_mov_b32 m0, s40
	v_lshl_add_u64 v[218:219], s[10:11], 0, v[142:143]
	global_load_lds_dwordx4 v[216:217], off
	v_lshl_add_u64 v[216:217], s[0:1], 0, v[144:145]
	s_add_i32 m0, s40, 0x2000
	s_nop 0
	global_load_lds_dwordx4 v[216:217], off
	v_lshl_add_u64 v[216:217], s[10:11], 0, v[138:139]
	s_waitcnt vmcnt(6)
	s_waitcnt lgkmcnt(0)
	v_mfma_f32_16x16x32_bf16 v[94:97], v[130:133], v[174:177], v[94:97]
	v_mfma_f32_16x16x32_bf16 v[30:33], v[150:153], v[174:177], v[30:33]
	s_barrier
	s_setprio 1
	v_mfma_f32_16x16x32_bf16 v[90:93], v[130:133], v[182:185], v[90:93]
	v_mfma_f32_16x16x32_bf16 v[26:29], v[150:153], v[182:185], v[26:29]
	v_mfma_f32_16x16x32_bf16 v[82:85], v[130:133], v[190:193], v[82:85]
	v_mfma_f32_16x16x32_bf16 v[18:21], v[150:153], v[190:193], v[18:21]
	v_mfma_f32_16x16x32_bf16 v[74:77], v[130:133], v[208:211], v[74:77]
	v_mfma_f32_16x16x32_bf16 v[10:13], v[150:153], v[208:211], v[10:13]
	v_mfma_f32_16x16x32_bf16 v[94:97], v[134:137], v[178:181], v[94:97]
	v_mfma_f32_16x16x32_bf16 v[30:33], v[154:157], v[178:181], v[30:33]
	v_mfma_f32_16x16x32_bf16 v[90:93], v[134:137], v[186:189], v[90:93]
	v_mfma_f32_16x16x32_bf16 v[26:29], v[154:157], v[186:189], v[26:29]
	v_mfma_f32_16x16x32_bf16 v[82:85], v[134:137], v[204:207], v[82:85]
	v_mfma_f32_16x16x32_bf16 v[18:21], v[154:157], v[204:207], v[18:21]
	v_mfma_f32_16x16x32_bf16 v[74:77], v[134:137], v[212:215], v[74:77]
	v_mfma_f32_16x16x32_bf16 v[10:13], v[154:157], v[212:215], v[10:13]
	v_mfma_f32_16x16x32_bf16 v[86:89], v[158:161], v[174:177], v[86:89]
	v_mfma_f32_16x16x32_bf16 v[22:25], v[166:169], v[174:177], v[22:25]
	v_mfma_f32_16x16x32_bf16 v[78:81], v[158:161], v[182:185], v[78:81]
	v_mfma_f32_16x16x32_bf16 v[14:17], v[166:169], v[182:185], v[14:17]
	v_mfma_f32_16x16x32_bf16 v[70:73], v[158:161], v[190:193], v[70:73]
	v_mfma_f32_16x16x32_bf16 v[6:9], v[166:169], v[190:193], v[6:9]
	v_mfma_f32_16x16x32_bf16 v[66:69], v[158:161], v[208:211], v[66:69]
	v_mfma_f32_16x16x32_bf16 v[2:5], v[166:169], v[208:211], v[2:5]
	v_mfma_f32_16x16x32_bf16 v[86:89], v[162:165], v[178:181], v[86:89]
	v_mfma_f32_16x16x32_bf16 v[22:25], v[170:173], v[178:181], v[22:25]
	v_mfma_f32_16x16x32_bf16 v[78:81], v[162:165], v[186:189], v[78:81]
	v_mfma_f32_16x16x32_bf16 v[14:17], v[170:173], v[186:189], v[14:17]
	v_mfma_f32_16x16x32_bf16 v[70:73], v[162:165], v[204:207], v[70:73]
	v_mfma_f32_16x16x32_bf16 v[6:9], v[170:173], v[204:207], v[6:9]
	v_mfma_f32_16x16x32_bf16 v[66:69], v[162:165], v[212:215], v[66:69]
	v_mfma_f32_16x16x32_bf16 v[2:5], v[170:173], v[212:215], v[2:5]
	s_setprio 0
	s_barrier
	s_mov_b32 m0, s49
	s_nop 0
	global_load_lds_dwordx4 v[216:217], off
	s_mov_b32 m0, s70
	s_nop 0
	global_load_lds_dwordx4 v[218:219], off
	ds_read_b128 v[130:133], v246 offset:32768
	ds_read_b128 v[134:137], v246 offset:33792
	ds_read_b128 v[150:153], v246 offset:34816
	ds_read_b128 v[154:157], v246 offset:35840
	ds_read_b128 v[158:161], v246 offset:49152
	ds_read_b128 v[162:165], v246 offset:50176
	ds_read_b128 v[166:169], v246 offset:51200
	ds_read_b128 v[170:173], v246 offset:52224
	ds_read_b128 v[174:177], v247 offset:32768
	ds_read_b128 v[178:181], v247 offset:33792
	ds_read_b128 v[182:185], v247 offset:34816
	ds_read_b128 v[186:189], v247 offset:35840
	ds_read_b128 v[190:193], v247 offset:36864
	ds_read_b128 v[204:207], v247 offset:37888
	ds_read_b128 v[208:211], v247 offset:38912
	ds_read_b128 v[212:215], v247 offset:39936
	s_add_i32 s40, 0, 0x18000
	s_add_i32 s41, 0, 0x1c000
	s_add_u32 s0, s10, 0x4000
	s_addc_u32 s1, s11, 0
	s_mov_b32 m0, s71
	v_lshl_add_u64 v[220:221], s[0:1], 0, v[138:139]
	global_load_lds_dwordx4 v[220:221], off
	v_lshl_add_u64 v[220:221], s[0:1], 0, v[142:143]
	s_mov_b32 m0, s73
	s_nop 0
	global_load_lds_dwordx4 v[220:221], off
	s_waitcnt vmcnt(8)
	s_waitcnt lgkmcnt(0)
	v_mfma_f32_16x16x32_bf16 v[126:129], v[130:133], v[174:177], v[126:129]
	v_mfma_f32_16x16x32_bf16 v[62:65], v[150:153], v[174:177], v[62:65]
	s_barrier
	s_setprio 1
	v_mfma_f32_16x16x32_bf16 v[122:125], v[130:133], v[182:185], v[122:125]
	v_mfma_f32_16x16x32_bf16 v[58:61], v[150:153], v[182:185], v[58:61]
	v_mfma_f32_16x16x32_bf16 v[114:117], v[130:133], v[190:193], v[114:117]
	v_mfma_f32_16x16x32_bf16 v[50:53], v[150:153], v[190:193], v[50:53]
	v_mfma_f32_16x16x32_bf16 v[106:109], v[130:133], v[208:211], v[106:109]
	v_mfma_f32_16x16x32_bf16 v[42:45], v[150:153], v[208:211], v[42:45]
	v_mfma_f32_16x16x32_bf16 v[126:129], v[134:137], v[178:181], v[126:129]
	v_mfma_f32_16x16x32_bf16 v[62:65], v[154:157], v[178:181], v[62:65]
	v_mfma_f32_16x16x32_bf16 v[122:125], v[134:137], v[186:189], v[122:125]
	v_mfma_f32_16x16x32_bf16 v[58:61], v[154:157], v[186:189], v[58:61]
	v_mfma_f32_16x16x32_bf16 v[114:117], v[134:137], v[204:207], v[114:117]
	v_mfma_f32_16x16x32_bf16 v[50:53], v[154:157], v[204:207], v[50:53]
	v_mfma_f32_16x16x32_bf16 v[106:109], v[134:137], v[212:215], v[106:109]
	v_mfma_f32_16x16x32_bf16 v[42:45], v[154:157], v[212:215], v[42:45]
	v_mfma_f32_16x16x32_bf16 v[118:121], v[158:161], v[174:177], v[118:121]
	v_mfma_f32_16x16x32_bf16 v[54:57], v[166:169], v[174:177], v[54:57]
	v_mfma_f32_16x16x32_bf16 v[110:113], v[158:161], v[182:185], v[110:113]
	v_mfma_f32_16x16x32_bf16 v[46:49], v[166:169], v[182:185], v[46:49]
	v_mfma_f32_16x16x32_bf16 v[102:105], v[158:161], v[190:193], v[102:105]
	v_mfma_f32_16x16x32_bf16 v[38:41], v[166:169], v[190:193], v[38:41]
	v_mfma_f32_16x16x32_bf16 v[98:101], v[158:161], v[208:211], v[98:101]
	v_mfma_f32_16x16x32_bf16 v[34:37], v[166:169], v[208:211], v[34:37]
	v_mfma_f32_16x16x32_bf16 v[118:121], v[162:165], v[178:181], v[118:121]
	v_mfma_f32_16x16x32_bf16 v[54:57], v[170:173], v[178:181], v[54:57]
	v_mfma_f32_16x16x32_bf16 v[110:113], v[162:165], v[186:189], v[110:113]
	v_mfma_f32_16x16x32_bf16 v[46:49], v[170:173], v[186:189], v[46:49]
	v_mfma_f32_16x16x32_bf16 v[102:105], v[162:165], v[204:207], v[102:105]
	v_mfma_f32_16x16x32_bf16 v[38:41], v[170:173], v[204:207], v[38:41]
	v_mfma_f32_16x16x32_bf16 v[98:101], v[162:165], v[212:215], v[98:101]
	v_mfma_f32_16x16x32_bf16 v[34:37], v[170:173], v[212:215], v[34:37]
	s_setprio 0
	s_barrier
	ds_read_b128 v[174:177], v247 offset:49152
	ds_read_b128 v[178:181], v247 offset:50176
	ds_read_b128 v[182:185], v247 offset:51200
	ds_read_b128 v[186:189], v247 offset:52224
	ds_read_b128 v[190:193], v247 offset:53248
	ds_read_b128 v[204:207], v247 offset:54272
	ds_read_b128 v[208:211], v247 offset:55296
	ds_read_b128 v[212:215], v247 offset:56320
	s_add_i32 s0, s40, s48
	v_lshl_add_u64 v[198:199], v[198:199], 0, s[94:95]
	s_mov_b32 m0, s0
	s_nop 0
	global_load_lds_dwordx4 v[198:199], off
	s_add_i32 m0, s0, 0x2000
	s_add_u32 s0, s6, 0x80080
	v_lshl_add_u64 v[198:199], v[200:201], 0, s[94:95]
	s_addc_u32 s1, s7, 0
	s_add_i32 s6, s41, s48
	global_load_lds_dwordx4 v[198:199], off
	v_lshl_add_u64 v[198:199], s[0:1], 0, v[140:141]
	s_mov_b32 m0, s6
	s_nop 0
	global_load_lds_dwordx4 v[198:199], off
	v_lshl_add_u64 v[198:199], s[0:1], 0, v[144:145]
	s_add_i32 m0, s6, 0x2000
	s_nop 0
	global_load_lds_dwordx4 v[198:199], off
	s_waitcnt vmcnt(6)
	s_waitcnt lgkmcnt(0)
	v_mfma_f32_16x16x32_bf16 v[94:97], v[130:133], v[174:177], v[94:97]
	v_mfma_f32_16x16x32_bf16 v[30:33], v[150:153], v[174:177], v[30:33]
	s_barrier
	s_setprio 1
	v_mfma_f32_16x16x32_bf16 v[90:93], v[130:133], v[182:185], v[90:93]
	v_mfma_f32_16x16x32_bf16 v[26:29], v[150:153], v[182:185], v[26:29]
	v_mfma_f32_16x16x32_bf16 v[82:85], v[130:133], v[190:193], v[82:85]
	v_mfma_f32_16x16x32_bf16 v[18:21], v[150:153], v[190:193], v[18:21]
	v_mfma_f32_16x16x32_bf16 v[74:77], v[130:133], v[208:211], v[74:77]
	v_mfma_f32_16x16x32_bf16 v[10:13], v[150:153], v[208:211], v[10:13]
	v_mfma_f32_16x16x32_bf16 v[94:97], v[134:137], v[178:181], v[94:97]
	v_mfma_f32_16x16x32_bf16 v[30:33], v[154:157], v[178:181], v[30:33]
	v_mfma_f32_16x16x32_bf16 v[90:93], v[134:137], v[186:189], v[90:93]
	v_mfma_f32_16x16x32_bf16 v[26:29], v[154:157], v[186:189], v[26:29]
	v_mfma_f32_16x16x32_bf16 v[82:85], v[134:137], v[204:207], v[82:85]
	v_mfma_f32_16x16x32_bf16 v[18:21], v[154:157], v[204:207], v[18:21]
	s_add_i32 s39, s39, 2
	v_mfma_f32_16x16x32_bf16 v[74:77], v[134:137], v[212:215], v[74:77]
	v_mfma_f32_16x16x32_bf16 v[10:13], v[154:157], v[212:215], v[10:13]
	s_add_u32 s33, s33, 0x100
	v_mfma_f32_16x16x32_bf16 v[86:89], v[158:161], v[174:177], v[86:89]
	v_mfma_f32_16x16x32_bf16 v[22:25], v[166:169], v[174:177], v[22:25]
	s_addc_u32 s38, s38, 0
	v_mfma_f32_16x16x32_bf16 v[78:81], v[158:161], v[182:185], v[78:81]
	v_mfma_f32_16x16x32_bf16 v[14:17], v[166:169], v[182:185], v[14:17]
	s_cmp_gt_u32 s39, 29
	v_mfma_f32_16x16x32_bf16 v[70:73], v[158:161], v[190:193], v[70:73]
	v_mfma_f32_16x16x32_bf16 v[6:9], v[166:169], v[190:193], v[6:9]
	s_mov_b64 s[0:1], s[4:5]
	v_mfma_f32_16x16x32_bf16 v[66:69], v[158:161], v[208:211], v[66:69]
	v_mfma_f32_16x16x32_bf16 v[2:5], v[166:169], v[208:211], v[2:5]
	v_mfma_f32_16x16x32_bf16 v[86:89], v[162:165], v[178:181], v[86:89]
	v_mfma_f32_16x16x32_bf16 v[22:25], v[170:173], v[178:181], v[22:25]
	v_mfma_f32_16x16x32_bf16 v[78:81], v[162:165], v[186:189], v[78:81]
	v_mfma_f32_16x16x32_bf16 v[14:17], v[170:173], v[186:189], v[14:17]
	v_mfma_f32_16x16x32_bf16 v[70:73], v[162:165], v[204:207], v[70:73]
	v_mfma_f32_16x16x32_bf16 v[6:9], v[170:173], v[204:207], v[6:9]
	v_mfma_f32_16x16x32_bf16 v[66:69], v[162:165], v[212:215], v[66:69]
	v_mfma_f32_16x16x32_bf16 v[2:5], v[170:173], v[212:215], v[2:5]
	s_setprio 0
	s_barrier
	s_cbranch_scc0 .LBB0_973
	s_and_b64 vcc, exec, s[26:27]
	s_cbranch_vccz .LBB0_976
	s_barrier

.LBB0_1431:
	s_lshl_b32 s2, s2, 5
	s_and_b32 s5, s2, 0x60
	s_add_i32 m0, s28, 0x18000
	v_lshl_add_u64 v[10:11], v[10:11], 0, s[94:95]
	s_lshl_b32 s4, s1, 13
	s_lshl_b32 s9, s5, 7
	s_waitcnt vmcnt(2)
	s_barrier
	global_load_lds_dwordx4 v[10:11], off
	v_lshl_add_u64 v[8:9], v[8:9], 0, s[94:95]
	s_add_i32 m0, s28, 0x1a000
	s_add_i32 s38, s28, 0x8000
	s_add_i32 s40, s28, 0xa000
	global_load_lds_dwordx4 v[8:9], off
	v_lshl_add_u64 v[4:5], v[4:5], 0, s[94:95]
	s_mov_b32 m0, s38
	s_add_u32 s2, s20, 0x160080
	global_load_lds_dwordx4 v[4:5], off
	v_lshl_add_u64 v[4:5], v[6:7], 0, s[94:95]
	s_mov_b32 m0, s40
	s_addc_u32 s3, s21, 0
	global_load_lds_dwordx4 v[4:5], off
	s_add_i32 m0, s28, 0x1c000
	v_lshl_add_u64 v[4:5], s[2:3], 0, v[194:195]
	global_load_lds_dwordx4 v[4:5], off
	v_lshl_add_u64 v[4:5], s[2:3], 0, v[204:205]
	s_add_i32 m0, s28, 0x1e000
	v_bfe_u32 v6, v14, 4, 2
	global_load_lds_dwordx4 v[4:5], off
	v_and_b32_e32 v7, 15, v14
	v_lshlrev_b32_e32 v8, 4, v6
	v_lshl_or_b32 v197, s1, 6, v7
	v_lshl_or_b32 v7, v7, 6, v8
	v_lshlrev_b32_e32 v8, 2, v14
	v_and_b32_e32 v8, 32, v8
	v_lshl_or_b32 v199, v6, 3, s5
	s_movk_i32 s5, 0x1600
	v_bitop3_b32 v9, v7, s4, v8 bitop3:0xde
	v_bitop3_b32 v198, v7, s9, v8 bitop3:0xde
	v_add_u32_e32 v198, 0x10000, v198
	v_cmp_eq_u32_e64 s[2:3], 0, v6
	v_lshrrev_b32_e32 v7, 1, v18
	v_mul_lo_u32 v6, v17, s5
	s_mov_b32 s4, 0x16000
	s_cmpk_lt_u32 s0, 0x100
	v_mad_u64_u32 v[6:7], s[0:1], v7, s4, v[6:7]
	v_or_b32_e32 v6, v6, v19
	v_add_lshl_u32 v6, v6, v20, 1
	v_mov_b32_e32 v7, v195
	s_mov_b64 s[16:17], 0x160080
	v_lshl_add_u64 v[210:211], v[6:7], 0, s[16:17]
	v_lshrrev_b32_e32 v7, 1, v12
	v_mul_lo_u32 v6, v13, s5
	v_mad_u64_u32 v[6:7], s[0:1], v7, s4, v[6:7]
	s_waitcnt vmcnt(6)
	v_or_b32_e32 v6, v6, v15
	v_add_lshl_u32 v6, v6, v16, 1
	v_mov_b32_e32 v7, v195
	v_mov_b32_e32 v3, v2
	v_mov_b32_e32 v4, v2
	v_mov_b32_e32 v5, v2
	s_cselect_b64 s[14:15], -1, 0
	s_mov_b32 s41, 0
	s_mov_b32 s9, s85
	v_lshl_add_u64 v[212:213], v[6:7], 0, s[16:17]
	v_add_u32_e32 v234, 0, v9
	s_barrier
	s_branch .LBB0_1434

.LBB0_1441:
	s_add_u32 vcc_lo, s18, 0xffea0000
	s_addc_u32 vcc_hi, s19, -1
	v_lshl_add_u64 v[200:201], vcc, 0, v[210:211]
	s_mov_b32 m0, s38
	s_nop 0
	global_load_lds_dwordx4 v[200:201], off
	v_lshl_add_u64 v[200:201], vcc, 0, v[212:213]
	s_mov_b32 m0, s40
	s_nop 0
	global_load_lds_dwordx4 v[200:201], off
	ds_read_b128 v[66:69], v198
	ds_read_b128 v[78:81], v198 offset:1024
	ds_read_b128 v[86:89], v198 offset:2048
	ds_read_b128 v[98:101], v198 offset:3072
	ds_read_b128 v[106:109], v198 offset:16384
	ds_read_b128 v[118:121], v198 offset:17408
	ds_read_b128 v[130:133], v198 offset:18432
	ds_read_b128 v[142:145], v198 offset:19456
	ds_read_b128 v[150:153], v234
	ds_read_b128 v[154:157], v234 offset:1024
	ds_read_b128 v[158:161], v234 offset:2048
	ds_read_b128 v[162:165], v234 offset:3072
	ds_read_b128 v[170:173], v234 offset:4096
	ds_read_b128 v[174:177], v234 offset:5120
	ds_read_b128 v[178:181], v234 offset:6144
	ds_read_b128 v[190:193], v234 offset:7168
	s_add_u32 s20, s18, 0x100
	s_addc_u32 s21, s19, 0
	s_add_i32 s49, 0, 0x10000
	s_cmpk_eq_i32 s48, 0x54
	s_cselect_b32 s25, s1, s21
	s_cselect_b32 s24, s0, s20
	s_cselect_b32 s23, s17, s47
	s_cselect_b32 s22, s16, s46
	s_add_i32 s50, 0, 0x14000
	v_lshl_add_u64 v[200:201], s[18:19], 0, v[210:211]
	s_add_i32 m0, s28, 0xc000
	s_nop 0
	global_load_lds_dwordx4 v[200:201], off
	v_lshl_add_u64 v[200:201], s[18:19], 0, v[212:213]
	s_add_i32 m0, s28, 0xe000
	s_nop 0
	global_load_lds_dwordx4 v[200:201], off
	s_waitcnt vmcnt(8)
	s_waitcnt lgkmcnt(0)
	v_mfma_f32_16x16x32_bf16 v[186:189], v[66:69], v[150:153], v[186:189]
	v_mfma_f32_16x16x32_bf16 v[182:185], v[86:89], v[150:153], v[182:185]
	s_barrier
	s_setprio 1
	v_mfma_f32_16x16x32_bf16 v[138:141], v[66:69], v[158:161], v[138:141]
	v_mfma_f32_16x16x32_bf16 v[134:137], v[86:89], v[158:161], v[134:137]
	v_mfma_f32_16x16x32_bf16 v[114:117], v[66:69], v[170:173], v[114:117]
	v_mfma_f32_16x16x32_bf16 v[110:113], v[86:89], v[170:173], v[110:113]
	v_mfma_f32_16x16x32_bf16 v[90:93], v[66:69], v[178:181], v[90:93]
	v_mfma_f32_16x16x32_bf16 v[82:85], v[86:89], v[178:181], v[82:85]
	v_mfma_f32_16x16x32_bf16 v[186:189], v[78:81], v[154:157], v[186:189]
	v_mfma_f32_16x16x32_bf16 v[182:185], v[98:101], v[154:157], v[182:185]
	v_mfma_f32_16x16x32_bf16 v[138:141], v[78:81], v[162:165], v[138:141]
	v_mfma_f32_16x16x32_bf16 v[134:137], v[98:101], v[162:165], v[134:137]
	v_mfma_f32_16x16x32_bf16 v[114:117], v[78:81], v[174:177], v[114:117]
	v_mfma_f32_16x16x32_bf16 v[110:113], v[98:101], v[174:177], v[110:113]
	v_mfma_f32_16x16x32_bf16 v[90:93], v[78:81], v[190:193], v[90:93]
	v_mfma_f32_16x16x32_bf16 v[82:85], v[98:101], v[190:193], v[82:85]
	v_mfma_f32_16x16x32_bf16 v[166:169], v[106:109], v[150:153], v[166:169]
	v_mfma_f32_16x16x32_bf16 v[146:149], v[130:133], v[150:153], v[146:149]
	v_mfma_f32_16x16x32_bf16 v[126:129], v[106:109], v[158:161], v[126:129]
	v_mfma_f32_16x16x32_bf16 v[122:125], v[130:133], v[158:161], v[122:125]
	v_mfma_f32_16x16x32_bf16 v[102:105], v[106:109], v[170:173], v[102:105]
	v_mfma_f32_16x16x32_bf16 v[94:97], v[130:133], v[170:173], v[94:97]
	v_mfma_f32_16x16x32_bf16 v[74:77], v[106:109], v[178:181], v[74:77]
	v_mfma_f32_16x16x32_bf16 v[70:73], v[130:133], v[178:181], v[70:73]
	v_mfma_f32_16x16x32_bf16 v[166:169], v[118:121], v[154:157], v[166:169]
	v_mfma_f32_16x16x32_bf16 v[146:149], v[142:145], v[154:157], v[146:149]
	v_mfma_f32_16x16x32_bf16 v[126:129], v[118:121], v[162:165], v[126:129]
	v_mfma_f32_16x16x32_bf16 v[122:125], v[142:145], v[162:165], v[122:125]
	v_mfma_f32_16x16x32_bf16 v[102:105], v[118:121], v[174:177], v[102:105]
	v_mfma_f32_16x16x32_bf16 v[94:97], v[142:145], v[174:177], v[94:97]
	v_mfma_f32_16x16x32_bf16 v[74:77], v[118:121], v[190:193], v[74:77]
	v_mfma_f32_16x16x32_bf16 v[70:73], v[142:145], v[190:193], v[70:73]
	s_setprio 0
	s_barrier
	ds_read_b128 v[150:153], v234 offset:16384
	ds_read_b128 v[154:157], v234 offset:17408
	ds_read_b128 v[158:161], v234 offset:18432
	ds_read_b128 v[162:165], v234 offset:19456
	ds_read_b128 v[170:173], v234 offset:20480
	ds_read_b128 v[174:177], v234 offset:21504
	ds_read_b128 v[178:181], v234 offset:22528
	ds_read_b128 v[190:193], v234 offset:23552
	s_add_i32 s18, s49, s26
	v_lshl_add_u64 v[200:201], s[22:23], 0, v[194:195]
	s_mov_b32 m0, s18
	s_nop 0
	global_load_lds_dwordx4 v[200:201], off
	s_add_i32 m0, s18, 0x2000
	s_add_u32 s18, s22, 0x160000
	v_lshl_add_u64 v[214:215], s[22:23], 0, v[204:205]
	s_addc_u32 s19, s23, 0
	s_add_i32 s49, s50, s26
	global_load_lds_dwordx4 v[214:215], off
	v_lshl_add_u64 v[216:217], s[18:19], 0, v[194:195]
	s_mov_b32 m0, s49
	v_lshl_add_u64 v[218:219], s[24:25], 0, v[206:207]
	global_load_lds_dwordx4 v[216:217], off
	v_lshl_add_u64 v[216:217], s[18:19], 0, v[204:205]
	s_add_i32 m0, s49, 0x2000
	s_nop 0
	global_load_lds_dwordx4 v[216:217], off
	v_lshl_add_u64 v[216:217], s[24:25], 0, v[208:209]
	s_waitcnt vmcnt(6)
	s_waitcnt lgkmcnt(0)
	v_mfma_f32_16x16x32_bf16 v[62:65], v[66:69], v[150:153], v[62:65]
	v_mfma_f32_16x16x32_bf16 v[58:61], v[86:89], v[150:153], v[58:61]
	s_barrier
	s_setprio 1
	v_mfma_f32_16x16x32_bf16 v[46:49], v[66:69], v[158:161], v[46:49]
	v_mfma_f32_16x16x32_bf16 v[42:45], v[86:89], v[158:161], v[42:45]
	v_mfma_f32_16x16x32_bf16 v[30:33], v[66:69], v[170:173], v[30:33]
	v_mfma_f32_16x16x32_bf16 v[26:29], v[86:89], v[170:173], v[26:29]
	v_mfma_f32_16x16x32_bf16 v[14:17], v[66:69], v[178:181], v[14:17]
	v_mfma_f32_16x16x32_bf16 v[10:13], v[86:89], v[178:181], v[10:13]
	v_mfma_f32_16x16x32_bf16 v[62:65], v[78:81], v[154:157], v[62:65]
	v_mfma_f32_16x16x32_bf16 v[58:61], v[98:101], v[154:157], v[58:61]
	v_mfma_f32_16x16x32_bf16 v[46:49], v[78:81], v[162:165], v[46:49]
	v_mfma_f32_16x16x32_bf16 v[42:45], v[98:101], v[162:165], v[42:45]
	v_mfma_f32_16x16x32_bf16 v[30:33], v[78:81], v[174:177], v[30:33]
	v_mfma_f32_16x16x32_bf16 v[26:29], v[98:101], v[174:177], v[26:29]
	v_mfma_f32_16x16x32_bf16 v[14:17], v[78:81], v[190:193], v[14:17]
	v_mfma_f32_16x16x32_bf16 v[10:13], v[98:101], v[190:193], v[10:13]
	v_mfma_f32_16x16x32_bf16 v[54:57], v[106:109], v[150:153], v[54:57]
	v_mfma_f32_16x16x32_bf16 v[50:53], v[130:133], v[150:153], v[50:53]
	v_mfma_f32_16x16x32_bf16 v[38:41], v[106:109], v[158:161], v[38:41]
	v_mfma_f32_16x16x32_bf16 v[34:37], v[130:133], v[158:161], v[34:37]
	v_mfma_f32_16x16x32_bf16 v[22:25], v[106:109], v[170:173], v[22:25]
	v_mfma_f32_16x16x32_bf16 v[18:21], v[130:133], v[170:173], v[18:21]
	v_mfma_f32_16x16x32_bf16 v[6:9], v[106:109], v[178:181], v[6:9]
	v_mfma_f32_16x16x32_bf16 v[2:5], v[130:133], v[178:181], v[2:5]
	v_mfma_f32_16x16x32_bf16 v[54:57], v[118:121], v[154:157], v[54:57]
	v_mfma_f32_16x16x32_bf16 v[50:53], v[142:145], v[154:157], v[50:53]
	v_mfma_f32_16x16x32_bf16 v[38:41], v[118:121], v[162:165], v[38:41]
	v_mfma_f32_16x16x32_bf16 v[34:37], v[142:145], v[162:165], v[34:37]
	v_mfma_f32_16x16x32_bf16 v[22:25], v[118:121], v[174:177], v[22:25]
	v_mfma_f32_16x16x32_bf16 v[18:21], v[142:145], v[174:177], v[18:21]
	v_mfma_f32_16x16x32_bf16 v[6:9], v[118:121], v[190:193], v[6:9]
	v_mfma_f32_16x16x32_bf16 v[2:5], v[142:145], v[190:193], v[2:5]
	s_setprio 0
	s_barrier
	s_mov_b32 m0, s28
	s_nop 0
	global_load_lds_dwordx4 v[216:217], off
	s_mov_b32 m0, s29
	s_nop 0
	global_load_lds_dwordx4 v[218:219], off
	ds_read_b128 v[66:69], v198 offset:32768
	ds_read_b128 v[78:81], v198 offset:33792
	ds_read_b128 v[86:89], v198 offset:34816
	ds_read_b128 v[98:101], v198 offset:35840
	ds_read_b128 v[106:109], v198 offset:49152
	ds_read_b128 v[118:121], v198 offset:50176
	ds_read_b128 v[130:133], v198 offset:51200
	ds_read_b128 v[142:145], v198 offset:52224
	ds_read_b128 v[150:153], v234 offset:32768
	ds_read_b128 v[154:157], v234 offset:33792
	ds_read_b128 v[158:161], v234 offset:34816
	ds_read_b128 v[162:165], v234 offset:35840
	ds_read_b128 v[170:173], v234 offset:36864
	ds_read_b128 v[174:177], v234 offset:37888
	ds_read_b128 v[178:181], v234 offset:38912
	ds_read_b128 v[190:193], v234 offset:39936
	s_add_i32 s49, 0, 0x18000
	s_add_i32 s50, 0, 0x1c000
	s_add_u32 s18, s24, 0x160000
	s_addc_u32 s19, s25, 0
	s_mov_b32 m0, s33
	v_lshl_add_u64 v[220:221], s[18:19], 0, v[208:209]
	global_load_lds_dwordx4 v[220:221], off
	v_lshl_add_u64 v[220:221], s[18:19], 0, v[206:207]
	s_mov_b32 m0, s37
	s_nop 0
	global_load_lds_dwordx4 v[220:221], off
	s_waitcnt vmcnt(8)
	s_waitcnt lgkmcnt(0)
	v_mfma_f32_16x16x32_bf16 v[186:189], v[66:69], v[150:153], v[186:189]
	v_mfma_f32_16x16x32_bf16 v[182:185], v[86:89], v[150:153], v[182:185]
	s_barrier
	s_setprio 1
	v_mfma_f32_16x16x32_bf16 v[138:141], v[66:69], v[158:161], v[138:141]
	v_mfma_f32_16x16x32_bf16 v[134:137], v[86:89], v[158:161], v[134:137]
	v_mfma_f32_16x16x32_bf16 v[114:117], v[66:69], v[170:173], v[114:117]
	v_mfma_f32_16x16x32_bf16 v[110:113], v[86:89], v[170:173], v[110:113]
	v_mfma_f32_16x16x32_bf16 v[90:93], v[66:69], v[178:181], v[90:93]
	v_mfma_f32_16x16x32_bf16 v[82:85], v[86:89], v[178:181], v[82:85]
	v_mfma_f32_16x16x32_bf16 v[186:189], v[78:81], v[154:157], v[186:189]
	v_mfma_f32_16x16x32_bf16 v[182:185], v[98:101], v[154:157], v[182:185]
	v_mfma_f32_16x16x32_bf16 v[138:141], v[78:81], v[162:165], v[138:141]
	v_mfma_f32_16x16x32_bf16 v[134:137], v[98:101], v[162:165], v[134:137]
	v_mfma_f32_16x16x32_bf16 v[114:117], v[78:81], v[174:177], v[114:117]
	v_mfma_f32_16x16x32_bf16 v[110:113], v[98:101], v[174:177], v[110:113]
	v_mfma_f32_16x16x32_bf16 v[90:93], v[78:81], v[190:193], v[90:93]
	v_mfma_f32_16x16x32_bf16 v[82:85], v[98:101], v[190:193], v[82:85]
	v_mfma_f32_16x16x32_bf16 v[166:169], v[106:109], v[150:153], v[166:169]
	v_mfma_f32_16x16x32_bf16 v[146:149], v[130:133], v[150:153], v[146:149]
	v_mfma_f32_16x16x32_bf16 v[126:129], v[106:109], v[158:161], v[126:129]
	v_mfma_f32_16x16x32_bf16 v[122:125], v[130:133], v[158:161], v[122:125]
	v_mfma_f32_16x16x32_bf16 v[102:105], v[106:109], v[170:173], v[102:105]
	v_mfma_f32_16x16x32_bf16 v[94:97], v[130:133], v[170:173], v[94:97]
	v_mfma_f32_16x16x32_bf16 v[74:77], v[106:109], v[178:181], v[74:77]
	v_mfma_f32_16x16x32_bf16 v[70:73], v[130:133], v[178:181], v[70:73]
	v_mfma_f32_16x16x32_bf16 v[166:169], v[118:121], v[154:157], v[166:169]
	v_mfma_f32_16x16x32_bf16 v[146:149], v[142:145], v[154:157], v[146:149]
	v_mfma_f32_16x16x32_bf16 v[126:129], v[118:121], v[162:165], v[126:129]
	v_mfma_f32_16x16x32_bf16 v[122:125], v[142:145], v[162:165], v[122:125]
	v_mfma_f32_16x16x32_bf16 v[102:105], v[118:121], v[174:177], v[102:105]
	v_mfma_f32_16x16x32_bf16 v[94:97], v[142:145], v[174:177], v[94:97]
	v_mfma_f32_16x16x32_bf16 v[74:77], v[118:121], v[190:193], v[74:77]
	v_mfma_f32_16x16x32_bf16 v[70:73], v[142:145], v[190:193], v[70:73]
	s_setprio 0
	s_barrier
	ds_read_b128 v[150:153], v234 offset:49152
	ds_read_b128 v[154:157], v234 offset:50176
	ds_read_b128 v[158:161], v234 offset:51200
	ds_read_b128 v[162:165], v234 offset:52224
	ds_read_b128 v[170:173], v234 offset:53248
	ds_read_b128 v[174:177], v234 offset:54272
	ds_read_b128 v[178:181], v234 offset:55296
	ds_read_b128 v[190:193], v234 offset:56320
	s_add_i32 s18, s49, s26
	v_lshl_add_u64 v[200:201], v[200:201], 0, s[94:95]
	s_mov_b32 m0, s18
	s_nop 0
	global_load_lds_dwordx4 v[200:201], off
	s_add_i32 m0, s18, 0x2000
	s_add_u32 s18, s22, 0x160080
	v_lshl_add_u64 v[200:201], v[214:215], 0, s[94:95]
	s_addc_u32 s19, s23, 0
	s_add_i32 s22, s50, s26
	global_load_lds_dwordx4 v[200:201], off
	v_lshl_add_u64 v[200:201], s[18:19], 0, v[194:195]
	s_mov_b32 m0, s22
	s_nop 0
	global_load_lds_dwordx4 v[200:201], off
	v_lshl_add_u64 v[200:201], s[18:19], 0, v[204:205]
	s_add_i32 m0, s22, 0x2000
	s_nop 0
	global_load_lds_dwordx4 v[200:201], off
	s_waitcnt vmcnt(6)
	s_waitcnt lgkmcnt(0)
	v_mfma_f32_16x16x32_bf16 v[62:65], v[66:69], v[150:153], v[62:65]
	v_mfma_f32_16x16x32_bf16 v[58:61], v[86:89], v[150:153], v[58:61]
	s_barrier
	s_setprio 1
	v_mfma_f32_16x16x32_bf16 v[46:49], v[66:69], v[158:161], v[46:49]
	v_mfma_f32_16x16x32_bf16 v[42:45], v[86:89], v[158:161], v[42:45]
	v_mfma_f32_16x16x32_bf16 v[30:33], v[66:69], v[170:173], v[30:33]
	v_mfma_f32_16x16x32_bf16 v[26:29], v[86:89], v[170:173], v[26:29]
	v_mfma_f32_16x16x32_bf16 v[14:17], v[66:69], v[178:181], v[14:17]
	v_mfma_f32_16x16x32_bf16 v[10:13], v[86:89], v[178:181], v[10:13]
	v_mfma_f32_16x16x32_bf16 v[62:65], v[78:81], v[154:157], v[62:65]
	v_mfma_f32_16x16x32_bf16 v[58:61], v[98:101], v[154:157], v[58:61]
	v_mfma_f32_16x16x32_bf16 v[46:49], v[78:81], v[162:165], v[46:49]
	v_mfma_f32_16x16x32_bf16 v[42:45], v[98:101], v[162:165], v[42:45]
	v_mfma_f32_16x16x32_bf16 v[30:33], v[78:81], v[174:177], v[30:33]
	v_mfma_f32_16x16x32_bf16 v[26:29], v[98:101], v[174:177], v[26:29]
	s_add_i32 s48, s48, 2
	v_mfma_f32_16x16x32_bf16 v[14:17], v[78:81], v[190:193], v[14:17]
	v_mfma_f32_16x16x32_bf16 v[10:13], v[98:101], v[190:193], v[10:13]
	s_add_u32 s46, s46, 0x100
	v_mfma_f32_16x16x32_bf16 v[54:57], v[106:109], v[150:153], v[54:57]
	v_mfma_f32_16x16x32_bf16 v[50:53], v[130:133], v[150:153], v[50:53]
	s_addc_u32 s47, s47, 0
	v_mfma_f32_16x16x32_bf16 v[38:41], v[106:109], v[158:161], v[38:41]
	v_mfma_f32_16x16x32_bf16 v[34:37], v[130:133], v[158:161], v[34:37]
	s_cmpk_gt_u32 s48, 0x55
	v_mfma_f32_16x16x32_bf16 v[22:25], v[106:109], v[170:173], v[22:25]
	v_mfma_f32_16x16x32_bf16 v[18:21], v[130:133], v[170:173], v[18:21]
	s_mov_b64 s[18:19], s[20:21]
	v_mfma_f32_16x16x32_bf16 v[6:9], v[106:109], v[178:181], v[6:9]
	v_mfma_f32_16x16x32_bf16 v[2:5], v[130:133], v[178:181], v[2:5]
	v_mfma_f32_16x16x32_bf16 v[54:57], v[118:121], v[154:157], v[54:57]
	v_mfma_f32_16x16x32_bf16 v[50:53], v[142:145], v[154:157], v[50:53]
	v_mfma_f32_16x16x32_bf16 v[38:41], v[118:121], v[162:165], v[38:41]
	v_mfma_f32_16x16x32_bf16 v[34:37], v[142:145], v[162:165], v[34:37]
	v_mfma_f32_16x16x32_bf16 v[22:25], v[118:121], v[174:177], v[22:25]
	v_mfma_f32_16x16x32_bf16 v[18:21], v[142:145], v[174:177], v[18:21]
	v_mfma_f32_16x16x32_bf16 v[6:9], v[118:121], v[190:193], v[6:9]
	v_mfma_f32_16x16x32_bf16 v[2:5], v[142:145], v[190:193], v[2:5]
	s_setprio 0
	s_barrier
	s_cbranch_scc0 .LBB0_1441
	s_and_b64 vcc, exec, s[14:15]
	s_cbranch_vccz .LBB0_1444
	s_barrier

.LBB0_1500:
	s_lshl_b32 s3, s3, 5
	s_and_b32 s7, s3, 0x60
	s_add_i32 m0, s40, 0x18000
	v_lshl_add_u64 v[10:11], v[10:11], 0, s[94:95]
	s_lshl_b32 s6, s2, 13
	s_lshl_b32 s3, s7, 7
	s_waitcnt vmcnt(2)
	s_barrier
	global_load_lds_dwordx4 v[10:11], off
	v_lshl_add_u64 v[8:9], v[8:9], 0, s[94:95]
	s_add_i32 m0, s40, 0x1a000
	s_add_i32 s44, s40, 0x8000
	s_add_i32 s45, s40, 0xa000
	global_load_lds_dwordx4 v[8:9], off
	v_lshl_add_u64 v[4:5], v[4:5], 0, s[94:95]
	s_mov_b32 m0, s44
	s_add_u32 s4, s24, 0x160080
	global_load_lds_dwordx4 v[4:5], off
	v_lshl_add_u64 v[4:5], v[6:7], 0, s[94:95]
	s_mov_b32 m0, s45
	s_addc_u32 s5, s25, 0
	global_load_lds_dwordx4 v[4:5], off
	s_add_i32 m0, s40, 0x1c000
	v_lshl_add_u64 v[4:5], s[4:5], 0, v[194:195]
	global_load_lds_dwordx4 v[4:5], off
	v_lshl_add_u64 v[4:5], s[4:5], 0, v[208:209]
	s_add_i32 m0, s40, 0x1e000
	v_bfe_u32 v7, v12, 4, 2
	global_load_lds_dwordx4 v[4:5], off
	v_and_b32_e32 v6, 15, v12
	v_lshlrev_b32_e32 v8, 4, v7
	v_lshl_or_b32 v234, s2, 6, v6
	v_lshl_or_b32 v6, v6, 6, v8
	v_lshlrev_b32_e32 v8, 2, v12
	v_and_b32_e32 v8, 32, v8
	v_lshl_or_b32 v236, v7, 3, s7
	s_movk_i32 s7, 0x1600
	v_bitop3_b32 v9, v6, s6, v8 bitop3:0xde
	v_bitop3_b32 v235, v6, s3, v8 bitop3:0xde
	v_add_u32_e32 v235, 0x10000, v235
	v_cmp_eq_u32_e64 s[2:3], 0, v7
	v_lshrrev_b32_e32 v7, 1, v13
	v_mul_lo_u32 v6, v15, s7
	s_mov_b32 s6, 0x16000
	v_mad_u64_u32 v[6:7], s[4:5], v7, s6, v[6:7]
	v_or_b32_e32 v6, v6, v14
	v_add_lshl_u32 v6, v6, v16, 1
	v_mov_b32_e32 v7, v195
	s_mov_b64 s[14:15], 0x160080
	v_lshl_add_u64 v[210:211], v[6:7], 0, s[14:15]
	v_lshrrev_b32_e32 v7, 1, v17
	v_mul_lo_u32 v6, v19, s7
	v_mad_u64_u32 v[6:7], s[4:5], v7, s6, v[6:7]
	s_waitcnt vmcnt(6)
	v_or_b32_e32 v6, v6, v18
	s_cmpk_lt_u32 s12, 0x100
	v_add_lshl_u32 v6, v6, v20, 1
	v_mov_b32_e32 v7, v195
	v_mov_b32_e32 v3, v2
	v_mov_b32_e32 v4, v2
	v_mov_b32_e32 v5, v2
	s_cselect_b64 s[12:13], -1, 0
	s_mov_b32 s46, 0
	v_lshl_add_u64 v[212:213], v[6:7], 0, s[14:15]
	v_add_u32_e32 v237, 0, v9
	s_mov_b32 s51, s21
	s_barrier
	s_branch .LBB0_1503

.LBB0_1511:
	s_add_u32 vcc_lo, s18, 0xffea0000
	s_addc_u32 vcc_hi, s19, -1
	v_lshl_add_u64 v[198:199], vcc, 0, v[210:211]
	s_mov_b32 m0, s44
	s_nop 0
	global_load_lds_dwordx4 v[198:199], off
	v_lshl_add_u64 v[198:199], vcc, 0, v[212:213]
	s_mov_b32 m0, s45
	s_nop 0
	global_load_lds_dwordx4 v[198:199], off
	ds_read_b128 v[130:133], v235
	ds_read_b128 v[134:137], v235 offset:1024
	ds_read_b128 v[138:141], v235 offset:2048
	ds_read_b128 v[142:145], v235 offset:3072
	ds_read_b128 v[146:149], v235 offset:16384
	ds_read_b128 v[150:153], v235 offset:17408
	ds_read_b128 v[154:157], v235 offset:18432
	ds_read_b128 v[158:161], v235 offset:19456
	ds_read_b128 v[162:165], v237
	ds_read_b128 v[166:169], v237 offset:1024
	ds_read_b128 v[170:173], v237 offset:2048
	ds_read_b128 v[174:177], v237 offset:3072
	ds_read_b128 v[178:181], v237 offset:4096
	ds_read_b128 v[182:185], v237 offset:5120
	ds_read_b128 v[186:189], v237 offset:6144
	ds_read_b128 v[190:193], v237 offset:7168
	s_add_i32 s55, s26, 2
	s_add_u32 s24, s18, 0x100
	s_addc_u32 s25, s19, 0
	s_add_i32 s56, 0, 0x10000
	s_cmp_eq_u32 s15, s26
	s_cselect_b32 s29, s7, s25
	s_cselect_b32 s28, s6, s24
	s_cselect_b32 s27, s17, s54
	s_cselect_b32 s26, s16, s23
	s_add_i32 s57, 0, 0x14000
	v_lshl_add_u64 v[198:199], s[18:19], 0, v[210:211]
	s_add_i32 m0, s40, 0xc000
	s_nop 0
	global_load_lds_dwordx4 v[198:199], off
	v_lshl_add_u64 v[198:199], s[18:19], 0, v[212:213]
	s_add_i32 m0, s40, 0xe000
	s_nop 0
	global_load_lds_dwordx4 v[198:199], off
	s_waitcnt vmcnt(8)
	s_waitcnt lgkmcnt(0)
	v_mfma_f32_16x16x32_bf16 v[126:129], v[130:133], v[162:165], v[126:129]
	v_mfma_f32_16x16x32_bf16 v[122:125], v[138:141], v[162:165], v[122:125]
	s_barrier
	s_setprio 1
	v_mfma_f32_16x16x32_bf16 v[110:113], v[130:133], v[170:173], v[110:113]
	v_mfma_f32_16x16x32_bf16 v[106:109], v[138:141], v[170:173], v[106:109]
	v_mfma_f32_16x16x32_bf16 v[94:97], v[130:133], v[178:181], v[94:97]
	v_mfma_f32_16x16x32_bf16 v[90:93], v[138:141], v[178:181], v[90:93]
	v_mfma_f32_16x16x32_bf16 v[78:81], v[130:133], v[186:189], v[78:81]
	v_mfma_f32_16x16x32_bf16 v[74:77], v[138:141], v[186:189], v[74:77]
	v_mfma_f32_16x16x32_bf16 v[126:129], v[134:137], v[166:169], v[126:129]
	v_mfma_f32_16x16x32_bf16 v[122:125], v[142:145], v[166:169], v[122:125]
	v_mfma_f32_16x16x32_bf16 v[110:113], v[134:137], v[174:177], v[110:113]
	v_mfma_f32_16x16x32_bf16 v[106:109], v[142:145], v[174:177], v[106:109]
	v_mfma_f32_16x16x32_bf16 v[94:97], v[134:137], v[182:185], v[94:97]
	v_mfma_f32_16x16x32_bf16 v[90:93], v[142:145], v[182:185], v[90:93]
	v_mfma_f32_16x16x32_bf16 v[78:81], v[134:137], v[190:193], v[78:81]
	v_mfma_f32_16x16x32_bf16 v[74:77], v[142:145], v[190:193], v[74:77]
	v_mfma_f32_16x16x32_bf16 v[118:121], v[146:149], v[162:165], v[118:121]
	v_mfma_f32_16x16x32_bf16 v[114:117], v[154:157], v[162:165], v[114:117]
	v_mfma_f32_16x16x32_bf16 v[102:105], v[146:149], v[170:173], v[102:105]
	v_mfma_f32_16x16x32_bf16 v[98:101], v[154:157], v[170:173], v[98:101]
	v_mfma_f32_16x16x32_bf16 v[86:89], v[146:149], v[178:181], v[86:89]
	v_mfma_f32_16x16x32_bf16 v[82:85], v[154:157], v[178:181], v[82:85]
	v_mfma_f32_16x16x32_bf16 v[70:73], v[146:149], v[186:189], v[70:73]
	v_mfma_f32_16x16x32_bf16 v[66:69], v[154:157], v[186:189], v[66:69]
	v_mfma_f32_16x16x32_bf16 v[118:121], v[150:153], v[166:169], v[118:121]
	v_mfma_f32_16x16x32_bf16 v[114:117], v[158:161], v[166:169], v[114:117]
	v_mfma_f32_16x16x32_bf16 v[102:105], v[150:153], v[174:177], v[102:105]
	v_mfma_f32_16x16x32_bf16 v[98:101], v[158:161], v[174:177], v[98:101]
	v_mfma_f32_16x16x32_bf16 v[86:89], v[150:153], v[182:185], v[86:89]
	v_mfma_f32_16x16x32_bf16 v[82:85], v[158:161], v[182:185], v[82:85]
	v_mfma_f32_16x16x32_bf16 v[70:73], v[150:153], v[190:193], v[70:73]
	v_mfma_f32_16x16x32_bf16 v[66:69], v[158:161], v[190:193], v[66:69]
	s_setprio 0
	s_barrier
	ds_read_b128 v[162:165], v237 offset:16384
	ds_read_b128 v[166:169], v237 offset:17408
	ds_read_b128 v[170:173], v237 offset:18432
	ds_read_b128 v[174:177], v237 offset:19456
	ds_read_b128 v[178:181], v237 offset:20480
	ds_read_b128 v[182:185], v237 offset:21504
	ds_read_b128 v[186:189], v237 offset:22528
	ds_read_b128 v[190:193], v237 offset:23552
	s_add_i32 s18, s56, s39
	v_lshl_add_u64 v[198:199], s[26:27], 0, v[194:195]
	s_mov_b32 m0, s18
	s_nop 0
	global_load_lds_dwordx4 v[198:199], off
	s_add_i32 m0, s18, 0x2000
	s_add_u32 s18, s26, 0x160000
	v_lshl_add_u64 v[200:201], s[26:27], 0, v[208:209]
	s_addc_u32 s19, s27, 0
	s_add_i32 s56, s57, s39
	global_load_lds_dwordx4 v[200:201], off
	v_lshl_add_u64 v[214:215], s[18:19], 0, v[194:195]
	s_mov_b32 m0, s56
	v_lshl_add_u64 v[216:217], s[28:29], 0, v[206:207]
	global_load_lds_dwordx4 v[214:215], off
	v_lshl_add_u64 v[214:215], s[18:19], 0, v[208:209]
	s_add_i32 m0, s56, 0x2000
	s_nop 0
	global_load_lds_dwordx4 v[214:215], off
	v_lshl_add_u64 v[214:215], s[28:29], 0, v[204:205]
	s_waitcnt vmcnt(6)
	s_waitcnt lgkmcnt(0)
	v_mfma_f32_16x16x32_bf16 v[62:65], v[130:133], v[162:165], v[62:65]
	v_mfma_f32_16x16x32_bf16 v[58:61], v[138:141], v[162:165], v[58:61]
	s_barrier
	s_setprio 1
	v_mfma_f32_16x16x32_bf16 v[46:49], v[130:133], v[170:173], v[46:49]
	v_mfma_f32_16x16x32_bf16 v[42:45], v[138:141], v[170:173], v[42:45]
	v_mfma_f32_16x16x32_bf16 v[30:33], v[130:133], v[178:181], v[30:33]
	v_mfma_f32_16x16x32_bf16 v[26:29], v[138:141], v[178:181], v[26:29]
	v_mfma_f32_16x16x32_bf16 v[14:17], v[130:133], v[186:189], v[14:17]
	v_mfma_f32_16x16x32_bf16 v[10:13], v[138:141], v[186:189], v[10:13]
	v_mfma_f32_16x16x32_bf16 v[62:65], v[134:137], v[166:169], v[62:65]
	v_mfma_f32_16x16x32_bf16 v[58:61], v[142:145], v[166:169], v[58:61]
	v_mfma_f32_16x16x32_bf16 v[46:49], v[134:137], v[174:177], v[46:49]
	v_mfma_f32_16x16x32_bf16 v[42:45], v[142:145], v[174:177], v[42:45]
	v_mfma_f32_16x16x32_bf16 v[30:33], v[134:137], v[182:185], v[30:33]
	v_mfma_f32_16x16x32_bf16 v[26:29], v[142:145], v[182:185], v[26:29]
	v_mfma_f32_16x16x32_bf16 v[14:17], v[134:137], v[190:193], v[14:17]
	v_mfma_f32_16x16x32_bf16 v[10:13], v[142:145], v[190:193], v[10:13]
	v_mfma_f32_16x16x32_bf16 v[54:57], v[146:149], v[162:165], v[54:57]
	v_mfma_f32_16x16x32_bf16 v[50:53], v[154:157], v[162:165], v[50:53]
	v_mfma_f32_16x16x32_bf16 v[38:41], v[146:149], v[170:173], v[38:41]
	v_mfma_f32_16x16x32_bf16 v[34:37], v[154:157], v[170:173], v[34:37]
	v_mfma_f32_16x16x32_bf16 v[22:25], v[146:149], v[178:181], v[22:25]
	v_mfma_f32_16x16x32_bf16 v[18:21], v[154:157], v[178:181], v[18:21]
	v_mfma_f32_16x16x32_bf16 v[6:9], v[146:149], v[186:189], v[6:9]
	v_mfma_f32_16x16x32_bf16 v[2:5], v[154:157], v[186:189], v[2:5]
	v_mfma_f32_16x16x32_bf16 v[54:57], v[150:153], v[166:169], v[54:57]
	v_mfma_f32_16x16x32_bf16 v[50:53], v[158:161], v[166:169], v[50:53]
	v_mfma_f32_16x16x32_bf16 v[38:41], v[150:153], v[174:177], v[38:41]
	v_mfma_f32_16x16x32_bf16 v[34:37], v[158:161], v[174:177], v[34:37]
	v_mfma_f32_16x16x32_bf16 v[22:25], v[150:153], v[182:185], v[22:25]
	v_mfma_f32_16x16x32_bf16 v[18:21], v[158:161], v[182:185], v[18:21]
	v_mfma_f32_16x16x32_bf16 v[6:9], v[150:153], v[190:193], v[6:9]
	v_mfma_f32_16x16x32_bf16 v[2:5], v[158:161], v[190:193], v[2:5]
	s_setprio 0
	s_barrier
	s_mov_b32 m0, s40
	s_nop 0
	global_load_lds_dwordx4 v[214:215], off
	s_mov_b32 m0, s41
	s_nop 0
	global_load_lds_dwordx4 v[216:217], off
	ds_read_b128 v[130:133], v235 offset:32768
	ds_read_b128 v[134:137], v235 offset:33792
	ds_read_b128 v[138:141], v235 offset:34816
	ds_read_b128 v[142:145], v235 offset:35840
	ds_read_b128 v[146:149], v235 offset:49152
	ds_read_b128 v[150:153], v235 offset:50176
	ds_read_b128 v[154:157], v235 offset:51200
	ds_read_b128 v[158:161], v235 offset:52224
	ds_read_b128 v[162:165], v237 offset:32768
	ds_read_b128 v[166:169], v237 offset:33792
	ds_read_b128 v[170:173], v237 offset:34816
	ds_read_b128 v[174:177], v237 offset:35840
	ds_read_b128 v[178:181], v237 offset:36864
	ds_read_b128 v[182:185], v237 offset:37888
	ds_read_b128 v[186:189], v237 offset:38912
	ds_read_b128 v[190:193], v237 offset:39936
	s_add_i32 s56, 0, 0x18000
	s_add_i32 s57, 0, 0x1c000
	s_add_u32 s18, s28, 0x160000
	s_addc_u32 s19, s29, 0
	s_mov_b32 m0, s42
	v_lshl_add_u64 v[218:219], s[18:19], 0, v[204:205]
	global_load_lds_dwordx4 v[218:219], off
	v_lshl_add_u64 v[218:219], s[18:19], 0, v[206:207]
	s_mov_b32 m0, s43
	s_nop 0
	global_load_lds_dwordx4 v[218:219], off
	s_waitcnt vmcnt(8)
	s_waitcnt lgkmcnt(0)
	v_mfma_f32_16x16x32_bf16 v[126:129], v[130:133], v[162:165], v[126:129]
	v_mfma_f32_16x16x32_bf16 v[122:125], v[138:141], v[162:165], v[122:125]
	s_barrier
	s_setprio 1
	v_mfma_f32_16x16x32_bf16 v[110:113], v[130:133], v[170:173], v[110:113]
	v_mfma_f32_16x16x32_bf16 v[106:109], v[138:141], v[170:173], v[106:109]
	v_mfma_f32_16x16x32_bf16 v[94:97], v[130:133], v[178:181], v[94:97]
	v_mfma_f32_16x16x32_bf16 v[90:93], v[138:141], v[178:181], v[90:93]
	v_mfma_f32_16x16x32_bf16 v[78:81], v[130:133], v[186:189], v[78:81]
	v_mfma_f32_16x16x32_bf16 v[74:77], v[138:141], v[186:189], v[74:77]
	v_mfma_f32_16x16x32_bf16 v[126:129], v[134:137], v[166:169], v[126:129]
	v_mfma_f32_16x16x32_bf16 v[122:125], v[142:145], v[166:169], v[122:125]
	v_mfma_f32_16x16x32_bf16 v[110:113], v[134:137], v[174:177], v[110:113]
	v_mfma_f32_16x16x32_bf16 v[106:109], v[142:145], v[174:177], v[106:109]
	v_mfma_f32_16x16x32_bf16 v[94:97], v[134:137], v[182:185], v[94:97]
	v_mfma_f32_16x16x32_bf16 v[90:93], v[142:145], v[182:185], v[90:93]
	v_mfma_f32_16x16x32_bf16 v[78:81], v[134:137], v[190:193], v[78:81]
	v_mfma_f32_16x16x32_bf16 v[74:77], v[142:145], v[190:193], v[74:77]
	v_mfma_f32_16x16x32_bf16 v[118:121], v[146:149], v[162:165], v[118:121]
	v_mfma_f32_16x16x32_bf16 v[114:117], v[154:157], v[162:165], v[114:117]
	v_mfma_f32_16x16x32_bf16 v[102:105], v[146:149], v[170:173], v[102:105]
	v_mfma_f32_16x16x32_bf16 v[98:101], v[154:157], v[170:173], v[98:101]
	v_mfma_f32_16x16x32_bf16 v[86:89], v[146:149], v[178:181], v[86:89]
	v_mfma_f32_16x16x32_bf16 v[82:85], v[154:157], v[178:181], v[82:85]
	v_mfma_f32_16x16x32_bf16 v[70:73], v[146:149], v[186:189], v[70:73]
	v_mfma_f32_16x16x32_bf16 v[66:69], v[154:157], v[186:189], v[66:69]
	v_mfma_f32_16x16x32_bf16 v[118:121], v[150:153], v[166:169], v[118:121]
	v_mfma_f32_16x16x32_bf16 v[114:117], v[158:161], v[166:169], v[114:117]
	v_mfma_f32_16x16x32_bf16 v[102:105], v[150:153], v[174:177], v[102:105]
	v_mfma_f32_16x16x32_bf16 v[98:101], v[158:161], v[174:177], v[98:101]
	v_mfma_f32_16x16x32_bf16 v[86:89], v[150:153], v[182:185], v[86:89]
	v_mfma_f32_16x16x32_bf16 v[82:85], v[158:161], v[182:185], v[82:85]
	v_mfma_f32_16x16x32_bf16 v[70:73], v[150:153], v[190:193], v[70:73]
	v_mfma_f32_16x16x32_bf16 v[66:69], v[158:161], v[190:193], v[66:69]
	s_setprio 0
	s_barrier
	ds_read_b128 v[162:165], v237 offset:49152
	ds_read_b128 v[166:169], v237 offset:50176
	ds_read_b128 v[170:173], v237 offset:51200
	ds_read_b128 v[174:177], v237 offset:52224
	ds_read_b128 v[178:181], v237 offset:53248
	ds_read_b128 v[182:185], v237 offset:54272
	ds_read_b128 v[186:189], v237 offset:55296
	ds_read_b128 v[190:193], v237 offset:56320
	s_add_i32 s18, s56, s39
	v_lshl_add_u64 v[198:199], v[198:199], 0, s[94:95]
	s_mov_b32 m0, s18
	s_nop 0
	global_load_lds_dwordx4 v[198:199], off
	s_add_i32 m0, s18, 0x2000
	s_add_u32 s18, s26, 0x160080
	v_lshl_add_u64 v[198:199], v[200:201], 0, s[94:95]
	s_addc_u32 s19, s27, 0
	s_add_i32 s26, s57, s39
	global_load_lds_dwordx4 v[198:199], off
	v_lshl_add_u64 v[198:199], s[18:19], 0, v[194:195]
	s_mov_b32 m0, s26
	s_nop 0
	global_load_lds_dwordx4 v[198:199], off
	v_lshl_add_u64 v[198:199], s[18:19], 0, v[208:209]
	s_add_i32 m0, s26, 0x2000
	s_nop 0
	global_load_lds_dwordx4 v[198:199], off
	s_waitcnt vmcnt(6)
	s_waitcnt lgkmcnt(0)
	v_mfma_f32_16x16x32_bf16 v[62:65], v[130:133], v[162:165], v[62:65]
	v_mfma_f32_16x16x32_bf16 v[58:61], v[138:141], v[162:165], v[58:61]
	s_barrier
	s_setprio 1
	v_mfma_f32_16x16x32_bf16 v[46:49], v[130:133], v[170:173], v[46:49]
	v_mfma_f32_16x16x32_bf16 v[42:45], v[138:141], v[170:173], v[42:45]
	v_mfma_f32_16x16x32_bf16 v[30:33], v[130:133], v[178:181], v[30:33]
	v_mfma_f32_16x16x32_bf16 v[26:29], v[138:141], v[178:181], v[26:29]
	v_mfma_f32_16x16x32_bf16 v[14:17], v[130:133], v[186:189], v[14:17]
	v_mfma_f32_16x16x32_bf16 v[10:13], v[138:141], v[186:189], v[10:13]
	v_mfma_f32_16x16x32_bf16 v[62:65], v[134:137], v[166:169], v[62:65]
	v_mfma_f32_16x16x32_bf16 v[58:61], v[142:145], v[166:169], v[58:61]
	v_mfma_f32_16x16x32_bf16 v[46:49], v[134:137], v[174:177], v[46:49]
	v_mfma_f32_16x16x32_bf16 v[42:45], v[142:145], v[174:177], v[42:45]
	v_mfma_f32_16x16x32_bf16 v[30:33], v[134:137], v[182:185], v[30:33]
	v_mfma_f32_16x16x32_bf16 v[26:29], v[142:145], v[182:185], v[26:29]
	s_add_u32 s23, s23, 0x100
	v_mfma_f32_16x16x32_bf16 v[14:17], v[134:137], v[190:193], v[14:17]
	v_mfma_f32_16x16x32_bf16 v[10:13], v[142:145], v[190:193], v[10:13]
	s_addc_u32 s54, s54, 0
	v_mfma_f32_16x16x32_bf16 v[54:57], v[146:149], v[162:165], v[54:57]
	v_mfma_f32_16x16x32_bf16 v[50:53], v[154:157], v[162:165], v[50:53]
	s_cmp_ge_i32 s55, s21
	v_mfma_f32_16x16x32_bf16 v[38:41], v[146:149], v[170:173], v[38:41]
	v_mfma_f32_16x16x32_bf16 v[34:37], v[154:157], v[170:173], v[34:37]
	s_mov_b64 s[18:19], s[24:25]
	v_mfma_f32_16x16x32_bf16 v[22:25], v[146:149], v[178:181], v[22:25]
	v_mfma_f32_16x16x32_bf16 v[18:21], v[154:157], v[178:181], v[18:21]
	s_mov_b32 s26, s55
	v_mfma_f32_16x16x32_bf16 v[6:9], v[146:149], v[186:189], v[6:9]
	v_mfma_f32_16x16x32_bf16 v[2:5], v[154:157], v[186:189], v[2:5]
	v_mfma_f32_16x16x32_bf16 v[54:57], v[150:153], v[166:169], v[54:57]
	v_mfma_f32_16x16x32_bf16 v[50:53], v[158:161], v[166:169], v[50:53]
	v_mfma_f32_16x16x32_bf16 v[38:41], v[150:153], v[174:177], v[38:41]
	v_mfma_f32_16x16x32_bf16 v[34:37], v[158:161], v[174:177], v[34:37]
	v_mfma_f32_16x16x32_bf16 v[22:25], v[150:153], v[182:185], v[22:25]
	v_mfma_f32_16x16x32_bf16 v[18:21], v[158:161], v[182:185], v[18:21]
	v_mfma_f32_16x16x32_bf16 v[6:9], v[150:153], v[190:193], v[6:9]
	v_mfma_f32_16x16x32_bf16 v[2:5], v[158:161], v[190:193], v[2:5]
	s_setprio 0
	s_barrier
	s_cbranch_scc0 .LBB0_1511
	s_and_b64 vcc, exec, s[12:13]
	s_cbranch_vccz .LBB0_1514
